# DMA GEMM mainloops: DMA issue in the MFMA shadow plus one static s_setprio 1 for the blocks of the second launch half (blockIdx>=256) during the mainloop
# speedup vs baseline: 1.0679x; 1.0175x over previous
.LBB0_463:
	s_ashr_i32 s0, s12, 3
	s_mul_hi_i32 s1, s0, 0x66666667
	s_lshr_b32 s13, s1, 31
	s_ashr_i32 s1, s1, 4
	s_add_i32 s1, s1, s13
	s_mul_i32 s13, s1, 40
	s_sub_i32 s0, s0, s13
	s_and_b32 s22, s0, 7
	s_mul_i32 s1, s1, 5
	s_ashr_i32 s0, s0, 3
	s_lshl_b32 s13, s12, 3
	s_add_i32 s1, s1, s0
	s_and_b32 s13, s13, 56
	s_lshl_b32 s0, s1, 7
	s_or_b32 s13, s22, s13
	s_add_i32 s22, s0, 0x100
	s_cmp_lt_i32 s1, 6
	s_cselect_b32 s0, s0, s22
	s_lshl_b32 s1, s13, 18
	v_readlane_b32 s22, v251, 31
	v_mov_b32_e32 v36, v178
	v_readlane_b32 s23, v251, 32
	s_add_u32 s22, s22, s1
	s_addc_u32 s23, s23, 0
	v_ashrrev_i32_e32 v34, 3, v36
	s_ashr_i32 s1, s0, 31
	v_lshlrev_b32_e32 v0, 3, v36
	v_ashrrev_i32_e32 v35, 31, v34
	s_lshl_b64 s[24:25], s[0:1], 11
	v_and_b32_e32 v37, 56, v0
	v_lshlrev_b64 v[2:3], 11, v[34:35]
	s_add_u32 s24, s92, s24
	v_lshl_add_u64 v[4:5], s[22:23], 0, v[2:3]
	v_lshlrev_b32_e32 v0, 1, v37
	s_addc_u32 s25, s93, s25
	v_lshl_add_u64 v[68:69], v[4:5], 0, v[0:1]
	v_lshl_add_u64 v[2:3], s[24:25], 0, v[2:3]
	v_lshl_add_u64 v[70:71], v[2:3], 0, v[0:1]
	v_and_b32_e32 v0, 7, v36
	v_bfe_u32 v66, v36, 4, 3
	v_xor_b32_e32 v66, v66, v0
	v_sub_u32_e32 v66, v66, v0
	v_lshlrev_b32_e32 v66, 4, v66
	v_ashrrev_i32_e32 v67, 31, v66
	v_lshl_add_u64 v[68:69], v[68:69], 0, v[66:67]
	v_lshl_add_u64 v[70:71], v[70:71], 0, v[66:67]
	v_add_co_u32_e32 v72, vcc, s73, v68
	s_nop 1
	v_addc_co_u32_e32 v73, vcc, 0, v69, vcc
	v_add_co_u32_e32 v74, vcc, s73, v70
	s_nop 1
	v_addc_co_u32_e32 v75, vcc, 0, v71, vcc
	v_add_co_u32_e32 v76, vcc, s52, v68
	s_nop 1
	v_addc_co_u32_e32 v77, vcc, 0, v69, vcc
	v_add_co_u32_e32 v78, vcc, s52, v70
	s_nop 1
	v_addc_co_u32_e32 v79, vcc, 0, v71, vcc
	v_add_co_u32_e32 v80, vcc, s53, v68
	s_nop 1
	v_addc_co_u32_e32 v81, vcc, 0, v69, vcc
	v_add_co_u32_e32 v82, vcc, s53, v70
	s_nop 1
	v_addc_co_u32_e32 v83, vcc, 0, v71, vcc
	v_and_b32_e32 v0, 31, v36
	v_bfe_u32 v66, v36, 5, 1
	v_bfe_u32 v67, v36, 1, 3
	v_xor_b32_e32 v66, v66, v67
	v_lshlrev_b32_e32 v66, 4, v66
	v_lshl_add_u32 v66, v0, 7, v66
	v_bfe_u32 v67, v36, 7, 1
	v_lshl_add_u32 v86, v67, 13, v66
	v_bfe_u32 v67, v36, 6, 1
	v_lshl_add_u32 v90, v67, 13, v66
	v_add_u32_e32 v90, 0x4000, v90
	v_xor_b32_e32 v87, 32, v86
	v_xor_b32_e32 v91, 32, v90
	v_xor_b32_e32 v88, 64, v86
	v_xor_b32_e32 v92, 64, v90
	v_xor_b32_e32 v89, 96, v86
	v_xor_b32_e32 v93, 96, v90
	v_lshrrev_b32_e32 v66, 6, v36
	v_lshlrev_b32_e32 v66, 10, v66
	s_nop 1
	v_readfirstlane_b32 s14, v66
	s_movk_i32 s1, 0x14c0
	s_mov_b32 s27, 0
	s_lshl_b32 s13, s13, 7
	v_readlane_b32 s15, v251, 0
	s_cmpk_lt_u32 s15, 0x100
	s_cbranch_scc1 .Lgp_g0
	s_setprio 1
.Lgp_g0:
	s_add_u32 m0, s14, 0x800
	s_nop 0
	global_load_lds_dwordx4 v[68:69], off
	s_add_u32 m0, s14, 0x1800
	s_nop 0
	global_load_lds_dwordx4 v[72:73], off
	s_add_u32 m0, s14, 0x2800
	s_nop 0
	global_load_lds_dwordx4 v[76:77], off
	s_add_u32 m0, s14, 0x3800
	s_nop 0
	global_load_lds_dwordx4 v[80:81], off
	s_add_u32 m0, s14, 0x4800
	s_nop 0
	global_load_lds_dwordx4 v[70:71], off
	s_add_u32 m0, s14, 0x5800
	s_nop 0
	global_load_lds_dwordx4 v[74:75], off
	s_add_u32 m0, s14, 0x6800
	s_nop 0
	global_load_lds_dwordx4 v[78:79], off
	s_add_u32 m0, s14, 0x7800
	s_nop 0
	global_load_lds_dwordx4 v[82:83], off
	s_add_u32 m0, s14, 0x8780
	s_nop 0
	global_load_lds_dwordx4 v[68:69], off offset:128
	s_add_u32 m0, s14, 0x9780
	s_nop 0
	global_load_lds_dwordx4 v[72:73], off offset:128
	s_add_u32 m0, s14, 0xa780
	s_nop 0
	global_load_lds_dwordx4 v[76:77], off offset:128
	s_add_u32 m0, s14, 0xb780
	s_nop 0
	global_load_lds_dwordx4 v[80:81], off offset:128
	s_add_u32 m0, s14, 0xc780
	s_nop 0
	global_load_lds_dwordx4 v[70:71], off offset:128
	s_add_u32 m0, s14, 0xd780
	s_nop 0
	global_load_lds_dwordx4 v[74:75], off offset:128
	s_add_u32 m0, s14, 0xe780
	s_nop 0
	global_load_lds_dwordx4 v[78:79], off offset:128
	s_add_u32 m0, s14, 0xf780
	s_nop 0
	global_load_lds_dwordx4 v[82:83], off offset:128
	s_waitcnt vmcnt(8)
	s_barrier
	ds_read_b128 v[94:97], v86 offset:2048
	ds_read_b128 v[98:101], v86 offset:6144
	ds_read_b128 v[102:105], v90 offset:2048
	ds_read_b128 v[106:109], v90 offset:6144
	ds_read_b128 v[110:113], v87 offset:2048
	ds_read_b128 v[114:117], v87 offset:6144
	ds_read_b128 v[118:121], v91 offset:2048
	ds_read_b128 v[122:125], v91 offset:6144
	ds_read_b128 v[126:129], v88 offset:2048
	ds_read_b128 v[130:133], v88 offset:6144
	ds_read_b128 v[134:137], v92 offset:2048
	ds_read_b128 v[138:141], v92 offset:6144
	ds_read_b128 v[142:145], v89 offset:2048
	ds_read_b128 v[146:149], v89 offset:6144
	ds_read_b128 v[150:153], v93 offset:2048
	ds_read_b128 v[154:157], v93 offset:6144
	s_waitcnt lgkmcnt(0)
	s_barrier
	s_add_u32 m0, s14, 0x700
	s_nop 0
	global_load_lds_dwordx4 v[68:69], off offset:256
	s_add_u32 m0, s14, 0x1700
	s_nop 0
	global_load_lds_dwordx4 v[72:73], off offset:256
	s_add_u32 m0, s14, 0x2700
	s_nop 0
	global_load_lds_dwordx4 v[76:77], off offset:256
	s_add_u32 m0, s14, 0x3700
	s_nop 0
	global_load_lds_dwordx4 v[80:81], off offset:256
	s_add_u32 m0, s14, 0x4700
	s_nop 0
	global_load_lds_dwordx4 v[70:71], off offset:256
	s_add_u32 m0, s14, 0x5700
	s_nop 0
	global_load_lds_dwordx4 v[74:75], off offset:256
	s_add_u32 m0, s14, 0x6700
	s_nop 0
	global_load_lds_dwordx4 v[78:79], off offset:256
	s_add_u32 m0, s14, 0x7700
	s_nop 0
	global_load_lds_dwordx4 v[82:83], off offset:256
	v_mfma_f32_32x32x16_bf16 v[34:49], v[94:97], v[102:105], 0
	v_mfma_f32_32x32x16_bf16 v[50:65], v[94:97], v[106:109], 0
	v_mfma_f32_32x32x16_bf16 v[2:17], v[98:101], v[102:105], 0
	v_mfma_f32_32x32x16_bf16 v[18:33], v[98:101], v[106:109], 0
	s_waitcnt vmcnt(8)
	s_barrier
	ds_read_b128 v[94:97], v86 offset:34816
	ds_read_b128 v[98:101], v86 offset:38912
	ds_read_b128 v[102:105], v90 offset:34816
	ds_read_b128 v[106:109], v90 offset:38912
	v_mfma_f32_32x32x16_bf16 v[34:49], v[110:113], v[118:121], v[34:49]
	v_mfma_f32_32x32x16_bf16 v[50:65], v[110:113], v[122:125], v[50:65]
	v_mfma_f32_32x32x16_bf16 v[2:17], v[114:117], v[118:121], v[2:17]
	v_mfma_f32_32x32x16_bf16 v[18:33], v[114:117], v[122:125], v[18:33]
	ds_read_b128 v[110:113], v87 offset:34816
	ds_read_b128 v[114:117], v87 offset:38912
	ds_read_b128 v[118:121], v91 offset:34816
	ds_read_b128 v[122:125], v91 offset:38912
	v_mfma_f32_32x32x16_bf16 v[34:49], v[126:129], v[134:137], v[34:49]
	v_mfma_f32_32x32x16_bf16 v[50:65], v[126:129], v[138:141], v[50:65]
	v_mfma_f32_32x32x16_bf16 v[2:17], v[130:133], v[134:137], v[2:17]
	v_mfma_f32_32x32x16_bf16 v[18:33], v[130:133], v[138:141], v[18:33]
	ds_read_b128 v[126:129], v88 offset:34816
	ds_read_b128 v[130:133], v88 offset:38912
	ds_read_b128 v[134:137], v92 offset:34816
	ds_read_b128 v[138:141], v92 offset:38912
	v_mfma_f32_32x32x16_bf16 v[34:49], v[142:145], v[150:153], v[34:49]
	v_mfma_f32_32x32x16_bf16 v[50:65], v[142:145], v[154:157], v[50:65]
	v_mfma_f32_32x32x16_bf16 v[2:17], v[146:149], v[150:153], v[2:17]
	v_mfma_f32_32x32x16_bf16 v[18:33], v[146:149], v[154:157], v[18:33]
	ds_read_b128 v[142:145], v89 offset:34816
	ds_read_b128 v[146:149], v89 offset:38912
	ds_read_b128 v[150:153], v93 offset:34816
	ds_read_b128 v[154:157], v93 offset:38912
	s_waitcnt lgkmcnt(0)
	s_barrier
	v_mfma_f32_32x32x16_bf16 v[34:49], v[94:97], v[102:105], v[34:49]
	s_add_u32 m0, s14, 0x8680
	s_nop 0
	global_load_lds_dwordx4 v[68:69], off offset:384
	s_add_u32 m0, s14, 0x9680
	s_nop 0
	global_load_lds_dwordx4 v[72:73], off offset:384
	v_mfma_f32_32x32x16_bf16 v[50:65], v[94:97], v[106:109], v[50:65]
	s_add_u32 m0, s14, 0xa680
	s_nop 0
	global_load_lds_dwordx4 v[76:77], off offset:384
	s_add_u32 m0, s14, 0xb680
	s_nop 0
	global_load_lds_dwordx4 v[80:81], off offset:384
	v_mfma_f32_32x32x16_bf16 v[2:17], v[98:101], v[102:105], v[2:17]
	s_add_u32 m0, s14, 0xc680
	s_nop 0
	global_load_lds_dwordx4 v[70:71], off offset:384
	s_add_u32 m0, s14, 0xd680
	s_nop 0
	global_load_lds_dwordx4 v[74:75], off offset:384
	v_mfma_f32_32x32x16_bf16 v[18:33], v[98:101], v[106:109], v[18:33]
	s_add_u32 m0, s14, 0xe680
	s_nop 0
	global_load_lds_dwordx4 v[78:79], off offset:384
	s_add_u32 m0, s14, 0xf680
	s_nop 0
	global_load_lds_dwordx4 v[82:83], off offset:384
	s_waitcnt vmcnt(8)
	s_barrier
	ds_read_b128 v[94:97], v86 offset:2048
	ds_read_b128 v[98:101], v86 offset:6144
	ds_read_b128 v[102:105], v90 offset:2048
	ds_read_b128 v[106:109], v90 offset:6144
	v_mfma_f32_32x32x16_bf16 v[34:49], v[110:113], v[118:121], v[34:49]
	v_mfma_f32_32x32x16_bf16 v[50:65], v[110:113], v[122:125], v[50:65]
	v_mfma_f32_32x32x16_bf16 v[2:17], v[114:117], v[118:121], v[2:17]
	v_mfma_f32_32x32x16_bf16 v[18:33], v[114:117], v[122:125], v[18:33]
	ds_read_b128 v[110:113], v87 offset:2048
	ds_read_b128 v[114:117], v87 offset:6144
	ds_read_b128 v[118:121], v91 offset:2048
	ds_read_b128 v[122:125], v91 offset:6144
	v_mfma_f32_32x32x16_bf16 v[34:49], v[126:129], v[134:137], v[34:49]
	v_mfma_f32_32x32x16_bf16 v[50:65], v[126:129], v[138:141], v[50:65]
	v_mfma_f32_32x32x16_bf16 v[2:17], v[130:133], v[134:137], v[2:17]
	v_mfma_f32_32x32x16_bf16 v[18:33], v[130:133], v[138:141], v[18:33]
	ds_read_b128 v[126:129], v88 offset:2048
	ds_read_b128 v[130:133], v88 offset:6144
	ds_read_b128 v[134:137], v92 offset:2048
	ds_read_b128 v[138:141], v92 offset:6144
	v_mfma_f32_32x32x16_bf16 v[34:49], v[142:145], v[150:153], v[34:49]
	v_mfma_f32_32x32x16_bf16 v[50:65], v[142:145], v[154:157], v[50:65]
	v_mfma_f32_32x32x16_bf16 v[2:17], v[146:149], v[150:153], v[2:17]
	v_mfma_f32_32x32x16_bf16 v[18:33], v[146:149], v[154:157], v[18:33]
	ds_read_b128 v[142:145], v89 offset:2048
	ds_read_b128 v[146:149], v89 offset:6144
	ds_read_b128 v[150:153], v93 offset:2048
	ds_read_b128 v[154:157], v93 offset:6144
	s_waitcnt lgkmcnt(0)
	s_barrier
	v_mfma_f32_32x32x16_bf16 v[34:49], v[94:97], v[102:105], v[34:49]
	s_add_u32 m0, s14, 0x600
	s_nop 0
	global_load_lds_dwordx4 v[68:69], off offset:512
	s_add_u32 m0, s14, 0x1600
	s_nop 0
	global_load_lds_dwordx4 v[72:73], off offset:512
	v_mfma_f32_32x32x16_bf16 v[50:65], v[94:97], v[106:109], v[50:65]
	s_add_u32 m0, s14, 0x2600
	s_nop 0
	global_load_lds_dwordx4 v[76:77], off offset:512
	s_add_u32 m0, s14, 0x3600
	s_nop 0
	global_load_lds_dwordx4 v[80:81], off offset:512
	v_mfma_f32_32x32x16_bf16 v[2:17], v[98:101], v[102:105], v[2:17]
	s_add_u32 m0, s14, 0x4600
	s_nop 0
	global_load_lds_dwordx4 v[70:71], off offset:512
	s_add_u32 m0, s14, 0x5600
	s_nop 0
	global_load_lds_dwordx4 v[74:75], off offset:512
	v_mfma_f32_32x32x16_bf16 v[18:33], v[98:101], v[106:109], v[18:33]
	s_add_u32 m0, s14, 0x6600
	s_nop 0
	global_load_lds_dwordx4 v[78:79], off offset:512
	s_add_u32 m0, s14, 0x7600
	s_nop 0
	global_load_lds_dwordx4 v[82:83], off offset:512
	s_waitcnt vmcnt(8)
	s_barrier
	ds_read_b128 v[94:97], v86 offset:34816
	ds_read_b128 v[98:101], v86 offset:38912
	ds_read_b128 v[102:105], v90 offset:34816
	ds_read_b128 v[106:109], v90 offset:38912
	v_mfma_f32_32x32x16_bf16 v[34:49], v[110:113], v[118:121], v[34:49]
	v_mfma_f32_32x32x16_bf16 v[50:65], v[110:113], v[122:125], v[50:65]
	v_mfma_f32_32x32x16_bf16 v[2:17], v[114:117], v[118:121], v[2:17]
	v_mfma_f32_32x32x16_bf16 v[18:33], v[114:117], v[122:125], v[18:33]
	ds_read_b128 v[110:113], v87 offset:34816
	ds_read_b128 v[114:117], v87 offset:38912
	ds_read_b128 v[118:121], v91 offset:34816
	ds_read_b128 v[122:125], v91 offset:38912
	v_mfma_f32_32x32x16_bf16 v[34:49], v[126:129], v[134:137], v[34:49]
	v_mfma_f32_32x32x16_bf16 v[50:65], v[126:129], v[138:141], v[50:65]
	v_mfma_f32_32x32x16_bf16 v[2:17], v[130:133], v[134:137], v[2:17]
	v_mfma_f32_32x32x16_bf16 v[18:33], v[130:133], v[138:141], v[18:33]
	ds_read_b128 v[126:129], v88 offset:34816
	ds_read_b128 v[130:133], v88 offset:38912
	ds_read_b128 v[134:137], v92 offset:34816
	ds_read_b128 v[138:141], v92 offset:38912
	v_mfma_f32_32x32x16_bf16 v[34:49], v[142:145], v[150:153], v[34:49]
	v_mfma_f32_32x32x16_bf16 v[50:65], v[142:145], v[154:157], v[50:65]
	v_mfma_f32_32x32x16_bf16 v[2:17], v[146:149], v[150:153], v[2:17]
	v_mfma_f32_32x32x16_bf16 v[18:33], v[146:149], v[154:157], v[18:33]
	ds_read_b128 v[142:145], v89 offset:34816
	ds_read_b128 v[146:149], v89 offset:38912
	ds_read_b128 v[150:153], v93 offset:34816
	ds_read_b128 v[154:157], v93 offset:38912
	s_waitcnt lgkmcnt(0)
	s_barrier
	v_mfma_f32_32x32x16_bf16 v[34:49], v[94:97], v[102:105], v[34:49]
	s_add_u32 m0, s14, 0x8580
	s_nop 0
	global_load_lds_dwordx4 v[68:69], off offset:640
	s_add_u32 m0, s14, 0x9580
	s_nop 0
	global_load_lds_dwordx4 v[72:73], off offset:640
	v_mfma_f32_32x32x16_bf16 v[50:65], v[94:97], v[106:109], v[50:65]
	s_add_u32 m0, s14, 0xa580
	s_nop 0
	global_load_lds_dwordx4 v[76:77], off offset:640
	s_add_u32 m0, s14, 0xb580
	s_nop 0
	global_load_lds_dwordx4 v[80:81], off offset:640
	v_mfma_f32_32x32x16_bf16 v[2:17], v[98:101], v[102:105], v[2:17]
	s_add_u32 m0, s14, 0xc580
	s_nop 0
	global_load_lds_dwordx4 v[70:71], off offset:640
	s_add_u32 m0, s14, 0xd580
	s_nop 0
	global_load_lds_dwordx4 v[74:75], off offset:640
	v_mfma_f32_32x32x16_bf16 v[18:33], v[98:101], v[106:109], v[18:33]
	s_add_u32 m0, s14, 0xe580
	s_nop 0
	global_load_lds_dwordx4 v[78:79], off offset:640
	s_add_u32 m0, s14, 0xf580
	s_nop 0
	global_load_lds_dwordx4 v[82:83], off offset:640
	s_waitcnt vmcnt(8)
	s_barrier
	ds_read_b128 v[94:97], v86 offset:2048
	ds_read_b128 v[98:101], v86 offset:6144
	ds_read_b128 v[102:105], v90 offset:2048
	ds_read_b128 v[106:109], v90 offset:6144
	v_mfma_f32_32x32x16_bf16 v[34:49], v[110:113], v[118:121], v[34:49]
	v_mfma_f32_32x32x16_bf16 v[50:65], v[110:113], v[122:125], v[50:65]
	v_mfma_f32_32x32x16_bf16 v[2:17], v[114:117], v[118:121], v[2:17]
	v_mfma_f32_32x32x16_bf16 v[18:33], v[114:117], v[122:125], v[18:33]
	ds_read_b128 v[110:113], v87 offset:2048
	ds_read_b128 v[114:117], v87 offset:6144
	ds_read_b128 v[118:121], v91 offset:2048
	ds_read_b128 v[122:125], v91 offset:6144
	v_mfma_f32_32x32x16_bf16 v[34:49], v[126:129], v[134:137], v[34:49]
	v_mfma_f32_32x32x16_bf16 v[50:65], v[126:129], v[138:141], v[50:65]
	v_mfma_f32_32x32x16_bf16 v[2:17], v[130:133], v[134:137], v[2:17]
	v_mfma_f32_32x32x16_bf16 v[18:33], v[130:133], v[138:141], v[18:33]
	ds_read_b128 v[126:129], v88 offset:2048
	ds_read_b128 v[130:133], v88 offset:6144
	ds_read_b128 v[134:137], v92 offset:2048
	ds_read_b128 v[138:141], v92 offset:6144
	v_mfma_f32_32x32x16_bf16 v[34:49], v[142:145], v[150:153], v[34:49]
	v_mfma_f32_32x32x16_bf16 v[50:65], v[142:145], v[154:157], v[50:65]
	v_mfma_f32_32x32x16_bf16 v[2:17], v[146:149], v[150:153], v[2:17]
	v_mfma_f32_32x32x16_bf16 v[18:33], v[146:149], v[154:157], v[18:33]
	ds_read_b128 v[142:145], v89 offset:2048
	ds_read_b128 v[146:149], v89 offset:6144
	ds_read_b128 v[150:153], v93 offset:2048
	ds_read_b128 v[154:157], v93 offset:6144
	s_waitcnt lgkmcnt(0)
	s_barrier
	v_mfma_f32_32x32x16_bf16 v[34:49], v[94:97], v[102:105], v[34:49]
	s_add_u32 m0, s14, 0x500
	s_nop 0
	global_load_lds_dwordx4 v[68:69], off offset:768
	s_add_u32 m0, s14, 0x1500
	s_nop 0
	global_load_lds_dwordx4 v[72:73], off offset:768
	v_mfma_f32_32x32x16_bf16 v[50:65], v[94:97], v[106:109], v[50:65]
	s_add_u32 m0, s14, 0x2500
	s_nop 0
	global_load_lds_dwordx4 v[76:77], off offset:768
	s_add_u32 m0, s14, 0x3500
	s_nop 0
	global_load_lds_dwordx4 v[80:81], off offset:768
	v_mfma_f32_32x32x16_bf16 v[2:17], v[98:101], v[102:105], v[2:17]
	s_add_u32 m0, s14, 0x4500
	s_nop 0
	global_load_lds_dwordx4 v[70:71], off offset:768
	s_add_u32 m0, s14, 0x5500
	s_nop 0
	global_load_lds_dwordx4 v[74:75], off offset:768
	v_mfma_f32_32x32x16_bf16 v[18:33], v[98:101], v[106:109], v[18:33]
	s_add_u32 m0, s14, 0x6500
	s_nop 0
	global_load_lds_dwordx4 v[78:79], off offset:768
	s_add_u32 m0, s14, 0x7500
	s_nop 0
	global_load_lds_dwordx4 v[82:83], off offset:768
	s_waitcnt vmcnt(8)
	s_barrier
	ds_read_b128 v[94:97], v86 offset:34816
	ds_read_b128 v[98:101], v86 offset:38912
	ds_read_b128 v[102:105], v90 offset:34816
	ds_read_b128 v[106:109], v90 offset:38912
	v_mfma_f32_32x32x16_bf16 v[34:49], v[110:113], v[118:121], v[34:49]
	v_mfma_f32_32x32x16_bf16 v[50:65], v[110:113], v[122:125], v[50:65]
	v_mfma_f32_32x32x16_bf16 v[2:17], v[114:117], v[118:121], v[2:17]
	v_mfma_f32_32x32x16_bf16 v[18:33], v[114:117], v[122:125], v[18:33]
	ds_read_b128 v[110:113], v87 offset:34816
	ds_read_b128 v[114:117], v87 offset:38912
	ds_read_b128 v[118:121], v91 offset:34816
	ds_read_b128 v[122:125], v91 offset:38912
	v_mfma_f32_32x32x16_bf16 v[34:49], v[126:129], v[134:137], v[34:49]
	v_mfma_f32_32x32x16_bf16 v[50:65], v[126:129], v[138:141], v[50:65]
	v_mfma_f32_32x32x16_bf16 v[2:17], v[130:133], v[134:137], v[2:17]
	v_mfma_f32_32x32x16_bf16 v[18:33], v[130:133], v[138:141], v[18:33]
	ds_read_b128 v[126:129], v88 offset:34816
	ds_read_b128 v[130:133], v88 offset:38912
	ds_read_b128 v[134:137], v92 offset:34816
	ds_read_b128 v[138:141], v92 offset:38912
	v_mfma_f32_32x32x16_bf16 v[34:49], v[142:145], v[150:153], v[34:49]
	v_mfma_f32_32x32x16_bf16 v[50:65], v[142:145], v[154:157], v[50:65]
	v_mfma_f32_32x32x16_bf16 v[2:17], v[146:149], v[150:153], v[2:17]
	v_mfma_f32_32x32x16_bf16 v[18:33], v[146:149], v[154:157], v[18:33]
	ds_read_b128 v[142:145], v89 offset:34816
	ds_read_b128 v[146:149], v89 offset:38912
	ds_read_b128 v[150:153], v93 offset:34816
	ds_read_b128 v[154:157], v93 offset:38912
	s_waitcnt lgkmcnt(0)
	s_barrier
	v_mfma_f32_32x32x16_bf16 v[34:49], v[94:97], v[102:105], v[34:49]
	s_add_u32 m0, s14, 0x8480
	s_nop 0
	global_load_lds_dwordx4 v[68:69], off offset:896
	s_add_u32 m0, s14, 0x9480
	s_nop 0
	global_load_lds_dwordx4 v[72:73], off offset:896
	v_mfma_f32_32x32x16_bf16 v[50:65], v[94:97], v[106:109], v[50:65]
	s_add_u32 m0, s14, 0xa480
	s_nop 0
	global_load_lds_dwordx4 v[76:77], off offset:896
	s_add_u32 m0, s14, 0xb480
	s_nop 0
	global_load_lds_dwordx4 v[80:81], off offset:896
	v_mfma_f32_32x32x16_bf16 v[2:17], v[98:101], v[102:105], v[2:17]
	s_add_u32 m0, s14, 0xc480
	s_nop 0
	global_load_lds_dwordx4 v[70:71], off offset:896
	s_add_u32 m0, s14, 0xd480
	s_nop 0
	global_load_lds_dwordx4 v[74:75], off offset:896
	v_mfma_f32_32x32x16_bf16 v[18:33], v[98:101], v[106:109], v[18:33]
	s_add_u32 m0, s14, 0xe480
	s_nop 0
	global_load_lds_dwordx4 v[78:79], off offset:896
	s_add_u32 m0, s14, 0xf480
	s_nop 0
	global_load_lds_dwordx4 v[82:83], off offset:896
	s_waitcnt vmcnt(8)
	s_barrier
	ds_read_b128 v[94:97], v86 offset:2048
	ds_read_b128 v[98:101], v86 offset:6144
	ds_read_b128 v[102:105], v90 offset:2048
	ds_read_b128 v[106:109], v90 offset:6144
	v_mfma_f32_32x32x16_bf16 v[34:49], v[110:113], v[118:121], v[34:49]
	v_mfma_f32_32x32x16_bf16 v[50:65], v[110:113], v[122:125], v[50:65]
	v_mfma_f32_32x32x16_bf16 v[2:17], v[114:117], v[118:121], v[2:17]
	v_mfma_f32_32x32x16_bf16 v[18:33], v[114:117], v[122:125], v[18:33]
	ds_read_b128 v[110:113], v87 offset:2048
	ds_read_b128 v[114:117], v87 offset:6144
	ds_read_b128 v[118:121], v91 offset:2048
	ds_read_b128 v[122:125], v91 offset:6144
	v_mfma_f32_32x32x16_bf16 v[34:49], v[126:129], v[134:137], v[34:49]
	v_mfma_f32_32x32x16_bf16 v[50:65], v[126:129], v[138:141], v[50:65]
	v_mfma_f32_32x32x16_bf16 v[2:17], v[130:133], v[134:137], v[2:17]
	v_mfma_f32_32x32x16_bf16 v[18:33], v[130:133], v[138:141], v[18:33]
	ds_read_b128 v[126:129], v88 offset:2048
	ds_read_b128 v[130:133], v88 offset:6144
	ds_read_b128 v[134:137], v92 offset:2048
	ds_read_b128 v[138:141], v92 offset:6144
	v_mfma_f32_32x32x16_bf16 v[34:49], v[142:145], v[150:153], v[34:49]
	v_mfma_f32_32x32x16_bf16 v[50:65], v[142:145], v[154:157], v[50:65]
	v_mfma_f32_32x32x16_bf16 v[2:17], v[146:149], v[150:153], v[2:17]
	v_mfma_f32_32x32x16_bf16 v[18:33], v[146:149], v[154:157], v[18:33]
	ds_read_b128 v[142:145], v89 offset:2048
	ds_read_b128 v[146:149], v89 offset:6144
	ds_read_b128 v[150:153], v93 offset:2048
	ds_read_b128 v[154:157], v93 offset:6144
	s_waitcnt lgkmcnt(0)
	s_barrier
	v_mfma_f32_32x32x16_bf16 v[34:49], v[94:97], v[102:105], v[34:49]
	s_add_u32 m0, s14, 0x400
	s_nop 0
	global_load_lds_dwordx4 v[68:69], off offset:1024
	s_add_u32 m0, s14, 0x1400
	s_nop 0
	global_load_lds_dwordx4 v[72:73], off offset:1024
	v_mfma_f32_32x32x16_bf16 v[50:65], v[94:97], v[106:109], v[50:65]
	s_add_u32 m0, s14, 0x2400
	s_nop 0
	global_load_lds_dwordx4 v[76:77], off offset:1024
	s_add_u32 m0, s14, 0x3400
	s_nop 0
	global_load_lds_dwordx4 v[80:81], off offset:1024
	v_mfma_f32_32x32x16_bf16 v[2:17], v[98:101], v[102:105], v[2:17]
	s_add_u32 m0, s14, 0x4400
	s_nop 0
	global_load_lds_dwordx4 v[70:71], off offset:1024
	s_add_u32 m0, s14, 0x5400
	s_nop 0
	global_load_lds_dwordx4 v[74:75], off offset:1024
	v_mfma_f32_32x32x16_bf16 v[18:33], v[98:101], v[106:109], v[18:33]
	s_add_u32 m0, s14, 0x6400
	s_nop 0
	global_load_lds_dwordx4 v[78:79], off offset:1024
	s_add_u32 m0, s14, 0x7400
	s_nop 0
	global_load_lds_dwordx4 v[82:83], off offset:1024
	s_waitcnt vmcnt(8)
	s_barrier
	ds_read_b128 v[94:97], v86 offset:34816
	ds_read_b128 v[98:101], v86 offset:38912
	ds_read_b128 v[102:105], v90 offset:34816
	ds_read_b128 v[106:109], v90 offset:38912
	v_mfma_f32_32x32x16_bf16 v[34:49], v[110:113], v[118:121], v[34:49]
	v_mfma_f32_32x32x16_bf16 v[50:65], v[110:113], v[122:125], v[50:65]
	v_mfma_f32_32x32x16_bf16 v[2:17], v[114:117], v[118:121], v[2:17]
	v_mfma_f32_32x32x16_bf16 v[18:33], v[114:117], v[122:125], v[18:33]
	ds_read_b128 v[110:113], v87 offset:34816
	ds_read_b128 v[114:117], v87 offset:38912
	ds_read_b128 v[118:121], v91 offset:34816
	ds_read_b128 v[122:125], v91 offset:38912
	v_mfma_f32_32x32x16_bf16 v[34:49], v[126:129], v[134:137], v[34:49]
	v_mfma_f32_32x32x16_bf16 v[50:65], v[126:129], v[138:141], v[50:65]
	v_mfma_f32_32x32x16_bf16 v[2:17], v[130:133], v[134:137], v[2:17]
	v_mfma_f32_32x32x16_bf16 v[18:33], v[130:133], v[138:141], v[18:33]
	ds_read_b128 v[126:129], v88 offset:34816
	ds_read_b128 v[130:133], v88 offset:38912
	ds_read_b128 v[134:137], v92 offset:34816
	ds_read_b128 v[138:141], v92 offset:38912
	v_mfma_f32_32x32x16_bf16 v[34:49], v[142:145], v[150:153], v[34:49]
	v_mfma_f32_32x32x16_bf16 v[50:65], v[142:145], v[154:157], v[50:65]
	v_mfma_f32_32x32x16_bf16 v[2:17], v[146:149], v[150:153], v[2:17]
	v_mfma_f32_32x32x16_bf16 v[18:33], v[146:149], v[154:157], v[18:33]
	ds_read_b128 v[142:145], v89 offset:34816
	ds_read_b128 v[146:149], v89 offset:38912
	ds_read_b128 v[150:153], v93 offset:34816
	ds_read_b128 v[154:157], v93 offset:38912
	s_waitcnt lgkmcnt(0)
	s_barrier
	v_mfma_f32_32x32x16_bf16 v[34:49], v[94:97], v[102:105], v[34:49]
	s_add_u32 m0, s14, 0x8380
	s_nop 0
	global_load_lds_dwordx4 v[68:69], off offset:1152
	s_add_u32 m0, s14, 0x9380
	s_nop 0
	global_load_lds_dwordx4 v[72:73], off offset:1152
	v_mfma_f32_32x32x16_bf16 v[50:65], v[94:97], v[106:109], v[50:65]
	s_add_u32 m0, s14, 0xa380
	s_nop 0
	global_load_lds_dwordx4 v[76:77], off offset:1152
	s_add_u32 m0, s14, 0xb380
	s_nop 0
	global_load_lds_dwordx4 v[80:81], off offset:1152
	v_mfma_f32_32x32x16_bf16 v[2:17], v[98:101], v[102:105], v[2:17]
	s_add_u32 m0, s14, 0xc380
	s_nop 0
	global_load_lds_dwordx4 v[70:71], off offset:1152
	s_add_u32 m0, s14, 0xd380
	s_nop 0
	global_load_lds_dwordx4 v[74:75], off offset:1152
	v_mfma_f32_32x32x16_bf16 v[18:33], v[98:101], v[106:109], v[18:33]
	s_add_u32 m0, s14, 0xe380
	s_nop 0
	global_load_lds_dwordx4 v[78:79], off offset:1152
	s_add_u32 m0, s14, 0xf380
	s_nop 0
	global_load_lds_dwordx4 v[82:83], off offset:1152
	s_waitcnt vmcnt(8)
	s_barrier
	ds_read_b128 v[94:97], v86 offset:2048
	ds_read_b128 v[98:101], v86 offset:6144
	ds_read_b128 v[102:105], v90 offset:2048
	ds_read_b128 v[106:109], v90 offset:6144
	v_mfma_f32_32x32x16_bf16 v[34:49], v[110:113], v[118:121], v[34:49]
	v_mfma_f32_32x32x16_bf16 v[50:65], v[110:113], v[122:125], v[50:65]
	v_mfma_f32_32x32x16_bf16 v[2:17], v[114:117], v[118:121], v[2:17]
	v_mfma_f32_32x32x16_bf16 v[18:33], v[114:117], v[122:125], v[18:33]
	ds_read_b128 v[110:113], v87 offset:2048
	ds_read_b128 v[114:117], v87 offset:6144
	ds_read_b128 v[118:121], v91 offset:2048
	ds_read_b128 v[122:125], v91 offset:6144
	v_mfma_f32_32x32x16_bf16 v[34:49], v[126:129], v[134:137], v[34:49]
	v_mfma_f32_32x32x16_bf16 v[50:65], v[126:129], v[138:141], v[50:65]
	v_mfma_f32_32x32x16_bf16 v[2:17], v[130:133], v[134:137], v[2:17]
	v_mfma_f32_32x32x16_bf16 v[18:33], v[130:133], v[138:141], v[18:33]
	ds_read_b128 v[126:129], v88 offset:2048
	ds_read_b128 v[130:133], v88 offset:6144
	ds_read_b128 v[134:137], v92 offset:2048
	ds_read_b128 v[138:141], v92 offset:6144
	v_mfma_f32_32x32x16_bf16 v[34:49], v[142:145], v[150:153], v[34:49]
	v_mfma_f32_32x32x16_bf16 v[50:65], v[142:145], v[154:157], v[50:65]
	v_mfma_f32_32x32x16_bf16 v[2:17], v[146:149], v[150:153], v[2:17]
	v_mfma_f32_32x32x16_bf16 v[18:33], v[146:149], v[154:157], v[18:33]
	ds_read_b128 v[142:145], v89 offset:2048
	ds_read_b128 v[146:149], v89 offset:6144
	ds_read_b128 v[150:153], v93 offset:2048
	ds_read_b128 v[154:157], v93 offset:6144
	s_waitcnt lgkmcnt(0)
	s_barrier
	v_mfma_f32_32x32x16_bf16 v[34:49], v[94:97], v[102:105], v[34:49]
	s_add_u32 m0, s14, 0x300
	s_nop 0
	global_load_lds_dwordx4 v[68:69], off offset:1280
	s_add_u32 m0, s14, 0x1300
	s_nop 0
	global_load_lds_dwordx4 v[72:73], off offset:1280
	v_mfma_f32_32x32x16_bf16 v[50:65], v[94:97], v[106:109], v[50:65]
	s_add_u32 m0, s14, 0x2300
	s_nop 0
	global_load_lds_dwordx4 v[76:77], off offset:1280
	s_add_u32 m0, s14, 0x3300
	s_nop 0
	global_load_lds_dwordx4 v[80:81], off offset:1280
	v_mfma_f32_32x32x16_bf16 v[2:17], v[98:101], v[102:105], v[2:17]
	s_add_u32 m0, s14, 0x4300
	s_nop 0
	global_load_lds_dwordx4 v[70:71], off offset:1280
	s_add_u32 m0, s14, 0x5300
	s_nop 0
	global_load_lds_dwordx4 v[74:75], off offset:1280
	v_mfma_f32_32x32x16_bf16 v[18:33], v[98:101], v[106:109], v[18:33]
	s_add_u32 m0, s14, 0x6300
	s_nop 0
	global_load_lds_dwordx4 v[78:79], off offset:1280
	s_add_u32 m0, s14, 0x7300
	s_nop 0
	global_load_lds_dwordx4 v[82:83], off offset:1280
	s_waitcnt vmcnt(8)
	s_barrier
	ds_read_b128 v[94:97], v86 offset:34816
	ds_read_b128 v[98:101], v86 offset:38912
	ds_read_b128 v[102:105], v90 offset:34816
	ds_read_b128 v[106:109], v90 offset:38912
	v_mfma_f32_32x32x16_bf16 v[34:49], v[110:113], v[118:121], v[34:49]
	v_mfma_f32_32x32x16_bf16 v[50:65], v[110:113], v[122:125], v[50:65]
	v_mfma_f32_32x32x16_bf16 v[2:17], v[114:117], v[118:121], v[2:17]
	v_mfma_f32_32x32x16_bf16 v[18:33], v[114:117], v[122:125], v[18:33]
	ds_read_b128 v[110:113], v87 offset:34816
	ds_read_b128 v[114:117], v87 offset:38912
	ds_read_b128 v[118:121], v91 offset:34816
	ds_read_b128 v[122:125], v91 offset:38912
	v_mfma_f32_32x32x16_bf16 v[34:49], v[126:129], v[134:137], v[34:49]
	v_mfma_f32_32x32x16_bf16 v[50:65], v[126:129], v[138:141], v[50:65]
	v_mfma_f32_32x32x16_bf16 v[2:17], v[130:133], v[134:137], v[2:17]
	v_mfma_f32_32x32x16_bf16 v[18:33], v[130:133], v[138:141], v[18:33]
	ds_read_b128 v[126:129], v88 offset:34816
	ds_read_b128 v[130:133], v88 offset:38912
	ds_read_b128 v[134:137], v92 offset:34816
	ds_read_b128 v[138:141], v92 offset:38912
	v_mfma_f32_32x32x16_bf16 v[34:49], v[142:145], v[150:153], v[34:49]
	v_mfma_f32_32x32x16_bf16 v[50:65], v[142:145], v[154:157], v[50:65]
	v_mfma_f32_32x32x16_bf16 v[2:17], v[146:149], v[150:153], v[2:17]
	v_mfma_f32_32x32x16_bf16 v[18:33], v[146:149], v[154:157], v[18:33]
	ds_read_b128 v[142:145], v89 offset:34816
	ds_read_b128 v[146:149], v89 offset:38912
	ds_read_b128 v[150:153], v93 offset:34816
	ds_read_b128 v[154:157], v93 offset:38912
	s_waitcnt lgkmcnt(0)
	s_barrier
	v_mfma_f32_32x32x16_bf16 v[34:49], v[94:97], v[102:105], v[34:49]
	s_add_u32 m0, s14, 0x8280
	s_nop 0
	global_load_lds_dwordx4 v[68:69], off offset:1408
	s_add_u32 m0, s14, 0x9280
	s_nop 0
	global_load_lds_dwordx4 v[72:73], off offset:1408
	v_mfma_f32_32x32x16_bf16 v[50:65], v[94:97], v[106:109], v[50:65]
	s_add_u32 m0, s14, 0xa280
	s_nop 0
	global_load_lds_dwordx4 v[76:77], off offset:1408
	s_add_u32 m0, s14, 0xb280
	s_nop 0
	global_load_lds_dwordx4 v[80:81], off offset:1408
	v_mfma_f32_32x32x16_bf16 v[2:17], v[98:101], v[102:105], v[2:17]
	s_add_u32 m0, s14, 0xc280
	s_nop 0
	global_load_lds_dwordx4 v[70:71], off offset:1408
	s_add_u32 m0, s14, 0xd280
	s_nop 0
	global_load_lds_dwordx4 v[74:75], off offset:1408
	v_mfma_f32_32x32x16_bf16 v[18:33], v[98:101], v[106:109], v[18:33]
	s_add_u32 m0, s14, 0xe280
	s_nop 0
	global_load_lds_dwordx4 v[78:79], off offset:1408
	s_add_u32 m0, s14, 0xf280
	s_nop 0
	global_load_lds_dwordx4 v[82:83], off offset:1408
	s_waitcnt vmcnt(8)
	s_barrier
	ds_read_b128 v[94:97], v86 offset:2048
	ds_read_b128 v[98:101], v86 offset:6144
	ds_read_b128 v[102:105], v90 offset:2048
	ds_read_b128 v[106:109], v90 offset:6144
	v_mfma_f32_32x32x16_bf16 v[34:49], v[110:113], v[118:121], v[34:49]
	v_mfma_f32_32x32x16_bf16 v[50:65], v[110:113], v[122:125], v[50:65]
	v_mfma_f32_32x32x16_bf16 v[2:17], v[114:117], v[118:121], v[2:17]
	v_mfma_f32_32x32x16_bf16 v[18:33], v[114:117], v[122:125], v[18:33]
	ds_read_b128 v[110:113], v87 offset:2048
	ds_read_b128 v[114:117], v87 offset:6144
	ds_read_b128 v[118:121], v91 offset:2048
	ds_read_b128 v[122:125], v91 offset:6144
	v_mfma_f32_32x32x16_bf16 v[34:49], v[126:129], v[134:137], v[34:49]
	v_mfma_f32_32x32x16_bf16 v[50:65], v[126:129], v[138:141], v[50:65]
	v_mfma_f32_32x32x16_bf16 v[2:17], v[130:133], v[134:137], v[2:17]
	v_mfma_f32_32x32x16_bf16 v[18:33], v[130:133], v[138:141], v[18:33]
	ds_read_b128 v[126:129], v88 offset:2048
	ds_read_b128 v[130:133], v88 offset:6144
	ds_read_b128 v[134:137], v92 offset:2048
	ds_read_b128 v[138:141], v92 offset:6144
	v_mfma_f32_32x32x16_bf16 v[34:49], v[142:145], v[150:153], v[34:49]
	v_mfma_f32_32x32x16_bf16 v[50:65], v[142:145], v[154:157], v[50:65]
	v_mfma_f32_32x32x16_bf16 v[2:17], v[146:149], v[150:153], v[2:17]
	v_mfma_f32_32x32x16_bf16 v[18:33], v[146:149], v[154:157], v[18:33]
	ds_read_b128 v[142:145], v89 offset:2048
	ds_read_b128 v[146:149], v89 offset:6144
	ds_read_b128 v[150:153], v93 offset:2048
	ds_read_b128 v[154:157], v93 offset:6144
	s_waitcnt lgkmcnt(0)
	s_barrier
	v_mfma_f32_32x32x16_bf16 v[34:49], v[94:97], v[102:105], v[34:49]
	s_add_u32 m0, s14, 0x200
	s_nop 0
	global_load_lds_dwordx4 v[68:69], off offset:1536
	s_add_u32 m0, s14, 0x1200
	s_nop 0
	global_load_lds_dwordx4 v[72:73], off offset:1536
	v_mfma_f32_32x32x16_bf16 v[50:65], v[94:97], v[106:109], v[50:65]
	s_add_u32 m0, s14, 0x2200
	s_nop 0
	global_load_lds_dwordx4 v[76:77], off offset:1536
	s_add_u32 m0, s14, 0x3200
	s_nop 0
	global_load_lds_dwordx4 v[80:81], off offset:1536
	v_mfma_f32_32x32x16_bf16 v[2:17], v[98:101], v[102:105], v[2:17]
	s_add_u32 m0, s14, 0x4200
	s_nop 0
	global_load_lds_dwordx4 v[70:71], off offset:1536
	s_add_u32 m0, s14, 0x5200
	s_nop 0
	global_load_lds_dwordx4 v[74:75], off offset:1536
	v_mfma_f32_32x32x16_bf16 v[18:33], v[98:101], v[106:109], v[18:33]
	s_add_u32 m0, s14, 0x6200
	s_nop 0
	global_load_lds_dwordx4 v[78:79], off offset:1536
	s_add_u32 m0, s14, 0x7200
	s_nop 0
	global_load_lds_dwordx4 v[82:83], off offset:1536
	s_waitcnt vmcnt(8)
	s_barrier
	ds_read_b128 v[94:97], v86 offset:34816
	ds_read_b128 v[98:101], v86 offset:38912
	ds_read_b128 v[102:105], v90 offset:34816
	ds_read_b128 v[106:109], v90 offset:38912
	v_mfma_f32_32x32x16_bf16 v[34:49], v[110:113], v[118:121], v[34:49]
	v_mfma_f32_32x32x16_bf16 v[50:65], v[110:113], v[122:125], v[50:65]
	v_mfma_f32_32x32x16_bf16 v[2:17], v[114:117], v[118:121], v[2:17]
	v_mfma_f32_32x32x16_bf16 v[18:33], v[114:117], v[122:125], v[18:33]
	ds_read_b128 v[110:113], v87 offset:34816
	ds_read_b128 v[114:117], v87 offset:38912
	ds_read_b128 v[118:121], v91 offset:34816
	ds_read_b128 v[122:125], v91 offset:38912
	v_mfma_f32_32x32x16_bf16 v[34:49], v[126:129], v[134:137], v[34:49]
	v_mfma_f32_32x32x16_bf16 v[50:65], v[126:129], v[138:141], v[50:65]
	v_mfma_f32_32x32x16_bf16 v[2:17], v[130:133], v[134:137], v[2:17]
	v_mfma_f32_32x32x16_bf16 v[18:33], v[130:133], v[138:141], v[18:33]
	ds_read_b128 v[126:129], v88 offset:34816
	ds_read_b128 v[130:133], v88 offset:38912
	ds_read_b128 v[134:137], v92 offset:34816
	ds_read_b128 v[138:141], v92 offset:38912
	v_mfma_f32_32x32x16_bf16 v[34:49], v[142:145], v[150:153], v[34:49]
	v_mfma_f32_32x32x16_bf16 v[50:65], v[142:145], v[154:157], v[50:65]
	v_mfma_f32_32x32x16_bf16 v[2:17], v[146:149], v[150:153], v[2:17]
	v_mfma_f32_32x32x16_bf16 v[18:33], v[146:149], v[154:157], v[18:33]
	ds_read_b128 v[142:145], v89 offset:34816
	ds_read_b128 v[146:149], v89 offset:38912
	ds_read_b128 v[150:153], v93 offset:34816
	ds_read_b128 v[154:157], v93 offset:38912
	s_waitcnt lgkmcnt(0)
	s_barrier
	v_mfma_f32_32x32x16_bf16 v[34:49], v[94:97], v[102:105], v[34:49]
	s_add_u32 m0, s14, 0x8180
	s_nop 0
	global_load_lds_dwordx4 v[68:69], off offset:1664
	s_add_u32 m0, s14, 0x9180
	s_nop 0
	global_load_lds_dwordx4 v[72:73], off offset:1664
	v_mfma_f32_32x32x16_bf16 v[50:65], v[94:97], v[106:109], v[50:65]
	s_add_u32 m0, s14, 0xa180
	s_nop 0
	global_load_lds_dwordx4 v[76:77], off offset:1664
	s_add_u32 m0, s14, 0xb180
	s_nop 0
	global_load_lds_dwordx4 v[80:81], off offset:1664
	v_mfma_f32_32x32x16_bf16 v[2:17], v[98:101], v[102:105], v[2:17]
	s_add_u32 m0, s14, 0xc180
	s_nop 0
	global_load_lds_dwordx4 v[70:71], off offset:1664
	s_add_u32 m0, s14, 0xd180
	s_nop 0
	global_load_lds_dwordx4 v[74:75], off offset:1664
	v_mfma_f32_32x32x16_bf16 v[18:33], v[98:101], v[106:109], v[18:33]
	s_add_u32 m0, s14, 0xe180
	s_nop 0
	global_load_lds_dwordx4 v[78:79], off offset:1664
	s_add_u32 m0, s14, 0xf180
	s_nop 0
	global_load_lds_dwordx4 v[82:83], off offset:1664
	s_waitcnt vmcnt(8)
	s_barrier
	ds_read_b128 v[94:97], v86 offset:2048
	ds_read_b128 v[98:101], v86 offset:6144
	ds_read_b128 v[102:105], v90 offset:2048
	ds_read_b128 v[106:109], v90 offset:6144
	v_mfma_f32_32x32x16_bf16 v[34:49], v[110:113], v[118:121], v[34:49]
	v_mfma_f32_32x32x16_bf16 v[50:65], v[110:113], v[122:125], v[50:65]
	v_mfma_f32_32x32x16_bf16 v[2:17], v[114:117], v[118:121], v[2:17]
	v_mfma_f32_32x32x16_bf16 v[18:33], v[114:117], v[122:125], v[18:33]
	ds_read_b128 v[110:113], v87 offset:2048
	ds_read_b128 v[114:117], v87 offset:6144
	ds_read_b128 v[118:121], v91 offset:2048
	ds_read_b128 v[122:125], v91 offset:6144
	v_mfma_f32_32x32x16_bf16 v[34:49], v[126:129], v[134:137], v[34:49]
	v_mfma_f32_32x32x16_bf16 v[50:65], v[126:129], v[138:141], v[50:65]
	v_mfma_f32_32x32x16_bf16 v[2:17], v[130:133], v[134:137], v[2:17]
	v_mfma_f32_32x32x16_bf16 v[18:33], v[130:133], v[138:141], v[18:33]
	ds_read_b128 v[126:129], v88 offset:2048
	ds_read_b128 v[130:133], v88 offset:6144
	ds_read_b128 v[134:137], v92 offset:2048
	ds_read_b128 v[138:141], v92 offset:6144
	v_mfma_f32_32x32x16_bf16 v[34:49], v[142:145], v[150:153], v[34:49]
	v_mfma_f32_32x32x16_bf16 v[50:65], v[142:145], v[154:157], v[50:65]
	v_mfma_f32_32x32x16_bf16 v[2:17], v[146:149], v[150:153], v[2:17]
	v_mfma_f32_32x32x16_bf16 v[18:33], v[146:149], v[154:157], v[18:33]
	ds_read_b128 v[142:145], v89 offset:2048
	ds_read_b128 v[146:149], v89 offset:6144
	ds_read_b128 v[150:153], v93 offset:2048
	ds_read_b128 v[154:157], v93 offset:6144
	s_waitcnt lgkmcnt(0)
	s_barrier
	v_mfma_f32_32x32x16_bf16 v[34:49], v[94:97], v[102:105], v[34:49]
	s_add_u32 m0, s14, 0x100
	s_nop 0
	global_load_lds_dwordx4 v[68:69], off offset:1792
	s_add_u32 m0, s14, 0x1100
	s_nop 0
	global_load_lds_dwordx4 v[72:73], off offset:1792
	v_mfma_f32_32x32x16_bf16 v[50:65], v[94:97], v[106:109], v[50:65]
	s_add_u32 m0, s14, 0x2100
	s_nop 0
	global_load_lds_dwordx4 v[76:77], off offset:1792
	s_add_u32 m0, s14, 0x3100
	s_nop 0
	global_load_lds_dwordx4 v[80:81], off offset:1792
	v_mfma_f32_32x32x16_bf16 v[2:17], v[98:101], v[102:105], v[2:17]
	s_add_u32 m0, s14, 0x4100
	s_nop 0
	global_load_lds_dwordx4 v[70:71], off offset:1792
	s_add_u32 m0, s14, 0x5100
	s_nop 0
	global_load_lds_dwordx4 v[74:75], off offset:1792
	v_mfma_f32_32x32x16_bf16 v[18:33], v[98:101], v[106:109], v[18:33]
	s_add_u32 m0, s14, 0x6100
	s_nop 0
	global_load_lds_dwordx4 v[78:79], off offset:1792
	s_add_u32 m0, s14, 0x7100
	s_nop 0
	global_load_lds_dwordx4 v[82:83], off offset:1792
	s_waitcnt vmcnt(8)
	s_barrier
	ds_read_b128 v[94:97], v86 offset:34816
	ds_read_b128 v[98:101], v86 offset:38912
	ds_read_b128 v[102:105], v90 offset:34816
	ds_read_b128 v[106:109], v90 offset:38912
	v_mfma_f32_32x32x16_bf16 v[34:49], v[110:113], v[118:121], v[34:49]
	v_mfma_f32_32x32x16_bf16 v[50:65], v[110:113], v[122:125], v[50:65]
	v_mfma_f32_32x32x16_bf16 v[2:17], v[114:117], v[118:121], v[2:17]
	v_mfma_f32_32x32x16_bf16 v[18:33], v[114:117], v[122:125], v[18:33]
	ds_read_b128 v[110:113], v87 offset:34816
	ds_read_b128 v[114:117], v87 offset:38912
	ds_read_b128 v[118:121], v91 offset:34816
	ds_read_b128 v[122:125], v91 offset:38912
	v_mfma_f32_32x32x16_bf16 v[34:49], v[126:129], v[134:137], v[34:49]
	v_mfma_f32_32x32x16_bf16 v[50:65], v[126:129], v[138:141], v[50:65]
	v_mfma_f32_32x32x16_bf16 v[2:17], v[130:133], v[134:137], v[2:17]
	v_mfma_f32_32x32x16_bf16 v[18:33], v[130:133], v[138:141], v[18:33]
	ds_read_b128 v[126:129], v88 offset:34816
	ds_read_b128 v[130:133], v88 offset:38912
	ds_read_b128 v[134:137], v92 offset:34816
	ds_read_b128 v[138:141], v92 offset:38912
	v_mfma_f32_32x32x16_bf16 v[34:49], v[142:145], v[150:153], v[34:49]
	v_mfma_f32_32x32x16_bf16 v[50:65], v[142:145], v[154:157], v[50:65]
	v_mfma_f32_32x32x16_bf16 v[2:17], v[146:149], v[150:153], v[2:17]
	v_mfma_f32_32x32x16_bf16 v[18:33], v[146:149], v[154:157], v[18:33]
	ds_read_b128 v[142:145], v89 offset:34816
	ds_read_b128 v[146:149], v89 offset:38912
	ds_read_b128 v[150:153], v93 offset:34816
	ds_read_b128 v[154:157], v93 offset:38912
	s_waitcnt lgkmcnt(0)
	s_barrier
	v_mfma_f32_32x32x16_bf16 v[34:49], v[94:97], v[102:105], v[34:49]
	s_add_u32 m0, s14, 0x8080
	s_nop 0
	global_load_lds_dwordx4 v[68:69], off offset:1920
	s_add_u32 m0, s14, 0x9080
	s_nop 0
	global_load_lds_dwordx4 v[72:73], off offset:1920
	v_mfma_f32_32x32x16_bf16 v[50:65], v[94:97], v[106:109], v[50:65]
	s_add_u32 m0, s14, 0xa080
	s_nop 0
	global_load_lds_dwordx4 v[76:77], off offset:1920
	s_add_u32 m0, s14, 0xb080
	s_nop 0
	global_load_lds_dwordx4 v[80:81], off offset:1920
	v_mfma_f32_32x32x16_bf16 v[2:17], v[98:101], v[102:105], v[2:17]
	s_add_u32 m0, s14, 0xc080
	s_nop 0
	global_load_lds_dwordx4 v[70:71], off offset:1920
	s_add_u32 m0, s14, 0xd080
	s_nop 0
	global_load_lds_dwordx4 v[74:75], off offset:1920
	v_mfma_f32_32x32x16_bf16 v[18:33], v[98:101], v[106:109], v[18:33]
	s_add_u32 m0, s14, 0xe080
	s_nop 0
	global_load_lds_dwordx4 v[78:79], off offset:1920
	s_add_u32 m0, s14, 0xf080
	s_nop 0
	global_load_lds_dwordx4 v[82:83], off offset:1920
	s_waitcnt vmcnt(8)
	s_barrier
	ds_read_b128 v[94:97], v86 offset:2048
	ds_read_b128 v[98:101], v86 offset:6144
	ds_read_b128 v[102:105], v90 offset:2048
	ds_read_b128 v[106:109], v90 offset:6144
	v_mfma_f32_32x32x16_bf16 v[34:49], v[110:113], v[118:121], v[34:49]
	v_mfma_f32_32x32x16_bf16 v[50:65], v[110:113], v[122:125], v[50:65]
	v_mfma_f32_32x32x16_bf16 v[2:17], v[114:117], v[118:121], v[2:17]
	v_mfma_f32_32x32x16_bf16 v[18:33], v[114:117], v[122:125], v[18:33]
	ds_read_b128 v[110:113], v87 offset:2048
	ds_read_b128 v[114:117], v87 offset:6144
	ds_read_b128 v[118:121], v91 offset:2048
	ds_read_b128 v[122:125], v91 offset:6144
	v_mfma_f32_32x32x16_bf16 v[34:49], v[126:129], v[134:137], v[34:49]
	v_mfma_f32_32x32x16_bf16 v[50:65], v[126:129], v[138:141], v[50:65]
	v_mfma_f32_32x32x16_bf16 v[2:17], v[130:133], v[134:137], v[2:17]
	v_mfma_f32_32x32x16_bf16 v[18:33], v[130:133], v[138:141], v[18:33]
	ds_read_b128 v[126:129], v88 offset:2048
	ds_read_b128 v[130:133], v88 offset:6144
	ds_read_b128 v[134:137], v92 offset:2048
	ds_read_b128 v[138:141], v92 offset:6144
	v_mfma_f32_32x32x16_bf16 v[34:49], v[142:145], v[150:153], v[34:49]
	v_mfma_f32_32x32x16_bf16 v[50:65], v[142:145], v[154:157], v[50:65]
	v_mfma_f32_32x32x16_bf16 v[2:17], v[146:149], v[150:153], v[2:17]
	v_mfma_f32_32x32x16_bf16 v[18:33], v[146:149], v[154:157], v[18:33]
	ds_read_b128 v[142:145], v89 offset:2048
	ds_read_b128 v[146:149], v89 offset:6144
	ds_read_b128 v[150:153], v93 offset:2048
	ds_read_b128 v[154:157], v93 offset:6144
	s_waitcnt lgkmcnt(0)
	v_mfma_f32_32x32x16_bf16 v[34:49], v[94:97], v[102:105], v[34:49]
	v_mfma_f32_32x32x16_bf16 v[50:65], v[94:97], v[106:109], v[50:65]
	v_mfma_f32_32x32x16_bf16 v[2:17], v[98:101], v[102:105], v[2:17]
	v_mfma_f32_32x32x16_bf16 v[18:33], v[98:101], v[106:109], v[18:33]
	s_waitcnt vmcnt(0)
	s_barrier
	ds_read_b128 v[94:97], v86 offset:34816
	ds_read_b128 v[98:101], v86 offset:38912
	ds_read_b128 v[102:105], v90 offset:34816
	ds_read_b128 v[106:109], v90 offset:38912
	v_mfma_f32_32x32x16_bf16 v[34:49], v[110:113], v[118:121], v[34:49]
	v_mfma_f32_32x32x16_bf16 v[50:65], v[110:113], v[122:125], v[50:65]
	v_mfma_f32_32x32x16_bf16 v[2:17], v[114:117], v[118:121], v[2:17]
	v_mfma_f32_32x32x16_bf16 v[18:33], v[114:117], v[122:125], v[18:33]
	ds_read_b128 v[110:113], v87 offset:34816
	ds_read_b128 v[114:117], v87 offset:38912
	ds_read_b128 v[118:121], v91 offset:34816
	ds_read_b128 v[122:125], v91 offset:38912
	v_mfma_f32_32x32x16_bf16 v[34:49], v[126:129], v[134:137], v[34:49]
	v_mfma_f32_32x32x16_bf16 v[50:65], v[126:129], v[138:141], v[50:65]
	v_mfma_f32_32x32x16_bf16 v[2:17], v[130:133], v[134:137], v[2:17]
	v_mfma_f32_32x32x16_bf16 v[18:33], v[130:133], v[138:141], v[18:33]
	ds_read_b128 v[126:129], v88 offset:34816
	ds_read_b128 v[130:133], v88 offset:38912
	ds_read_b128 v[134:137], v92 offset:34816
	ds_read_b128 v[138:141], v92 offset:38912
	v_mfma_f32_32x32x16_bf16 v[34:49], v[142:145], v[150:153], v[34:49]
	v_mfma_f32_32x32x16_bf16 v[50:65], v[142:145], v[154:157], v[50:65]
	v_mfma_f32_32x32x16_bf16 v[2:17], v[146:149], v[150:153], v[2:17]
	v_mfma_f32_32x32x16_bf16 v[18:33], v[146:149], v[154:157], v[18:33]
	ds_read_b128 v[142:145], v89 offset:34816
	ds_read_b128 v[146:149], v89 offset:38912
	ds_read_b128 v[150:153], v93 offset:34816
	ds_read_b128 v[154:157], v93 offset:38912
	s_waitcnt lgkmcnt(0)
	v_mfma_f32_32x32x16_bf16 v[34:49], v[94:97], v[102:105], v[34:49]
	v_mfma_f32_32x32x16_bf16 v[50:65], v[94:97], v[106:109], v[50:65]
	v_mfma_f32_32x32x16_bf16 v[2:17], v[98:101], v[102:105], v[2:17]
	v_mfma_f32_32x32x16_bf16 v[18:33], v[98:101], v[106:109], v[18:33]
	v_mfma_f32_32x32x16_bf16 v[34:49], v[110:113], v[118:121], v[34:49]
	v_mfma_f32_32x32x16_bf16 v[50:65], v[110:113], v[122:125], v[50:65]
	v_mfma_f32_32x32x16_bf16 v[2:17], v[114:117], v[118:121], v[2:17]
	v_mfma_f32_32x32x16_bf16 v[18:33], v[114:117], v[122:125], v[18:33]
	v_mfma_f32_32x32x16_bf16 v[34:49], v[126:129], v[134:137], v[34:49]
	v_mfma_f32_32x32x16_bf16 v[50:65], v[126:129], v[138:141], v[50:65]
	v_mfma_f32_32x32x16_bf16 v[2:17], v[130:133], v[134:137], v[2:17]
	v_mfma_f32_32x32x16_bf16 v[18:33], v[130:133], v[138:141], v[18:33]
	v_mfma_f32_32x32x16_bf16 v[34:49], v[142:145], v[150:153], v[34:49]
	v_mfma_f32_32x32x16_bf16 v[50:65], v[142:145], v[154:157], v[50:65]
	v_mfma_f32_32x32x16_bf16 v[2:17], v[146:149], v[150:153], v[2:17]
	v_mfma_f32_32x32x16_bf16 v[18:33], v[146:149], v[154:157], v[18:33]
	s_setprio 0
	v_mov_b32_e32 v66, v178
	s_waitcnt lgkmcnt(0)
	s_barrier
	s_nop 0
	v_lshrrev_b32_e32 v0, 1, v66
	v_and_b32_e32 v0, 0xfffffc0, v0
	v_lshrrev_b32_e32 v67, 3, v66
	v_and_or_b32 v0, v67, 4, v0
	v_and_b32_e32 v67, 0x5f, v66
	v_mul_lo_u32 v0, v0, s83
	v_lshl_add_u32 v0, v67, 2, v0
	s_nop 0
	s_nop 11
	ds_write2_b32 v0, v34, v50 offset1:32
	ds_write2_b32 v0, v35, v51 offset0:132 offset1:164
	s_nop 0
	v_add_u32_e32 v34, 0x400, v0
	ds_write2_b32 v34, v36, v52 offset0:8 offset1:40
	ds_write2_b32 v34, v37, v53 offset0:140 offset1:172
	v_add_u32_e32 v34, 0x1000, v0
	ds_write2_b32 v34, v38, v54 offset0:32 offset1:64
	ds_write2_b32 v34, v39, v55 offset0:164 offset1:196
	v_add_u32_e32 v34, 0x1400, v0
	ds_write2_b32 v34, v40, v56 offset0:40 offset1:72
	ds_write2_b32 v34, v41, v57 offset0:172 offset1:204
	v_add_u32_e32 v34, 0x2000, v0
	s_nop 0
	ds_write2_b32 v34, v42, v58 offset0:64 offset1:96
	ds_write2_b32 v34, v43, v59 offset0:196 offset1:228
	v_add_u32_e32 v34, 0x2400, v0
	ds_write2_b32 v34, v44, v60 offset0:72 offset1:104
	ds_write2_b32 v34, v45, v61 offset0:204 offset1:236
	v_add_u32_e32 v34, 0x3000, v0
	ds_write2_b32 v34, v46, v62 offset0:96 offset1:128
	v_add_u32_e32 v34, 0x3200, v0
	ds_write2_b32 v34, v47, v63 offset0:100 offset1:132
	s_nop 0
	v_add_u32_e32 v34, 0x3400, v0
	ds_write2_b32 v34, v48, v64 offset0:104 offset1:136
	v_add_u32_e32 v34, 0x3600, v0
	ds_write2_b32 v34, v49, v65 offset0:108 offset1:140
	v_add_u32_e32 v34, 0x4000, v0
	s_nop 0
	s_nop 11
	ds_write2_b32 v34, v2, v18 offset0:128 offset1:160
	v_add_u32_e32 v2, 0x4400, v0
	ds_write2_b32 v2, v3, v19 offset0:4 offset1:36
	ds_write2_b32 v2, v4, v20 offset0:136 offset1:168
	v_add_u32_e32 v2, 0x4800, v0
	ds_write2_b32 v2, v5, v21 offset0:12 offset1:44
	v_add_u32_e32 v2, 0x5000, v0
	ds_write2_b32 v2, v6, v22 offset0:160 offset1:192
	v_add_u32_e32 v2, 0x5400, v0
	ds_write2_b32 v2, v7, v23 offset0:36 offset1:68
	ds_write2_b32 v2, v8, v24 offset0:168 offset1:200
	v_add_u32_e32 v2, 0x5800, v0
	ds_write2_b32 v2, v9, v25 offset0:44 offset1:76
	v_add_u32_e32 v2, 0x6000, v0
	ds_write2_b32 v2, v10, v26 offset0:192 offset1:224
	v_add_u32_e32 v2, 0x6400, v0
	ds_write2_b32 v2, v11, v27 offset0:68 offset1:100
	ds_write2_b32 v2, v12, v28 offset0:200 offset1:232
	v_add_u32_e32 v2, 0x6800, v0
	v_lshlrev_b32_e32 v6, 2, v66
	ds_write2_b32 v2, v13, v29 offset0:76 offset1:108
	v_add_u32_e32 v2, 0x7200, v0
	v_and_b32_e32 v6, 4, v6
	ds_write2_b32 v2, v14, v30 offset0:96 offset1:128
	v_add_u32_e32 v2, 0x7400, v0
	v_cvt_f32_ubyte0_e32 v7, v6
	ds_write2_b32 v2, v15, v31 offset0:100 offset1:132
	v_add_u32_e32 v2, 0x7600, v0
	v_add_u32_e32 v0, 0x7800, v0
	v_mul_f32_e32 v7, 0xbfd49a78, v7
	ds_write2_b32 v0, v17, v33 offset0:108 offset1:140
	v_lshlrev_b32_e32 v0, 3, v66
	v_exp_f32_e32 v15, v7
	v_or_b32_e32 v7, 1, v6
	v_and_b32_e32 v0, 0x78, v0
	v_cvt_f32_ubyte0_e32 v7, v7
	ds_write2_b32 v2, v16, v32 offset0:104 offset1:136
	v_or_b32_e32 v2, s0, v0
	v_mov_b32_e32 v4, s0
	s_movk_i32 s0, 0xffe0
	v_mul_f32_e32 v7, 0xbfd49a78, v7
	v_lshlrev_b32_e32 v14, 2, v0
	v_bitop3_b32 v0, v0, s0, v4 bitop3:0xc8
	s_movk_i32 s0, 0x280
	v_exp_f32_e32 v28, v7
	v_or_b32_e32 v7, 2, v6
	v_or_b32_e32 v6, 3, v6
	v_cmp_ne_u32_e64 s[40:41], s0, v0
	s_movk_i32 s0, 0x149f
	v_cvt_f32_ubyte0_e32 v7, v7
	v_cvt_f32_ubyte0_e32 v6, v6
	v_cmp_gt_i32_e64 s[38:39], s1, v2
	v_cmp_lt_i32_e64 s[42:43], s0, v2
	v_mul_f32_e32 v7, 0xbfd49a78, v7
	v_mul_f32_e32 v6, 0xbfd49a78, v6
	v_readlane_b32 s0, v251, 35
	v_mov_b32_e32 v4, v2
	v_mov_b32_e32 v5, v1
	v_exp_f32_e32 v29, v7
	v_exp_f32_e32 v30, v6
	v_readlane_b32 s1, v251, 36
	v_ashrrev_i32_e32 v3, 31, v2
	v_add_u32_e32 v0, 0xfffffd80, v2
	v_lshl_add_u64 v[18:19], v[4:5], 2, s[0:1]
	v_readlane_b32 s0, v249, 11
	v_readlane_b32 s1, v249, 12
	v_cmp_gt_u32_e64 s[44:45], 16, v0
	v_cmp_gt_u32_e64 s[46:47], 14, v0
	v_cmp_gt_u32_e64 s[48:49], 12, v0
	v_cmp_gt_u32_e64 s[50:51], 10, v0
	v_lshl_add_u64 v[16:17], v[2:3], 1, s[78:79]
	v_lshl_add_u64 v[20:21], v[0:1], 1, s[0:1]
	s_waitcnt lgkmcnt(0)
	s_barrier
	s_branch .LBB0_465

.LBB0_582:
	s_add_i32 s0, s25, 0xfffffc00
	s_lshr_b32 s1, s0, 1
	s_lshl_b32 s0, s25, 7
	s_and_b32 s0, s0, 0x80
	s_waitcnt vmcnt(12)
	v_mov_b32_e32 v36, v178
	s_or_b32 s0, s0, 0x300
	s_lshl_b32 s12, s1, 18
	v_readlane_b32 s22, v251, 31
	v_readlane_b32 s23, v251, 32
	v_ashrrev_i32_e32 v34, 3, v36
	s_add_u32 s12, s22, s12
	v_lshlrev_b32_e32 v0, 3, v36
	v_ashrrev_i32_e32 v35, 31, v34
	s_addc_u32 s13, s23, 0
	s_lshl_b32 s22, s0, 11
	v_and_b32_e32 v37, 56, v0
	s_waitcnt vmcnt(5)
	v_lshlrev_b64 v[2:3], 11, v[34:35]
	s_add_u32 s22, s92, s22
	v_lshl_add_u64 v[4:5], s[12:13], 0, v[2:3]
	v_lshlrev_b32_e32 v0, 1, v37
	s_addc_u32 s23, s93, 0
	v_lshl_add_u64 v[68:69], v[4:5], 0, v[0:1]
	v_lshl_add_u64 v[2:3], s[22:23], 0, v[2:3]
	v_lshl_add_u64 v[70:71], v[2:3], 0, v[0:1]
	v_and_b32_e32 v0, 7, v36
	v_bfe_u32 v66, v36, 4, 3
	v_xor_b32_e32 v66, v66, v0
	v_sub_u32_e32 v66, v66, v0
	v_lshlrev_b32_e32 v66, 4, v66
	v_ashrrev_i32_e32 v67, 31, v66
	v_lshl_add_u64 v[68:69], v[68:69], 0, v[66:67]
	v_lshl_add_u64 v[70:71], v[70:71], 0, v[66:67]
	v_add_co_u32_e32 v72, vcc, s73, v68
	s_nop 1
	v_addc_co_u32_e32 v73, vcc, 0, v69, vcc
	v_add_co_u32_e32 v74, vcc, s73, v70
	s_nop 1
	v_addc_co_u32_e32 v75, vcc, 0, v71, vcc
	v_add_co_u32_e32 v76, vcc, s52, v68
	s_nop 1
	v_addc_co_u32_e32 v77, vcc, 0, v69, vcc
	v_add_co_u32_e32 v78, vcc, s52, v70
	s_nop 1
	v_addc_co_u32_e32 v79, vcc, 0, v71, vcc
	v_add_co_u32_e32 v80, vcc, s53, v68
	s_nop 1
	v_addc_co_u32_e32 v81, vcc, 0, v69, vcc
	v_add_co_u32_e32 v82, vcc, s53, v70
	s_nop 1
	v_addc_co_u32_e32 v83, vcc, 0, v71, vcc
	v_and_b32_e32 v0, 31, v36
	v_bfe_u32 v66, v36, 5, 1
	v_bfe_u32 v67, v36, 1, 3
	v_xor_b32_e32 v66, v66, v67
	v_lshlrev_b32_e32 v66, 4, v66
	v_lshl_add_u32 v66, v0, 7, v66
	v_bfe_u32 v67, v36, 7, 1
	v_lshl_add_u32 v86, v67, 13, v66
	v_bfe_u32 v67, v36, 6, 1
	v_lshl_add_u32 v90, v67, 13, v66
	v_add_u32_e32 v90, 0x4000, v90
	v_xor_b32_e32 v87, 32, v86
	v_xor_b32_e32 v91, 32, v90
	v_xor_b32_e32 v88, 64, v86
	v_xor_b32_e32 v92, 64, v90
	v_xor_b32_e32 v89, 96, v86
	v_xor_b32_e32 v93, 96, v90
	v_lshrrev_b32_e32 v66, 6, v36
	v_lshlrev_b32_e32 v66, 10, v66
	s_nop 1
	v_readfirstlane_b32 s14, v66
	s_mov_b32 s12, 0
	s_lshl_b32 s1, s1, 7
	v_readlane_b32 s15, v251, 0
	s_cmpk_lt_u32 s15, 0x100
	s_cbranch_scc1 .Lgp_g1
	s_setprio 1
.Lgp_g1:
	s_add_u32 m0, s14, 0x800
	s_nop 0
	global_load_lds_dwordx4 v[68:69], off
	s_add_u32 m0, s14, 0x1800
	s_nop 0
	global_load_lds_dwordx4 v[72:73], off
	s_add_u32 m0, s14, 0x2800
	s_nop 0
	global_load_lds_dwordx4 v[76:77], off
	s_add_u32 m0, s14, 0x3800
	s_nop 0
	global_load_lds_dwordx4 v[80:81], off
	s_add_u32 m0, s14, 0x4800
	s_nop 0
	global_load_lds_dwordx4 v[70:71], off
	s_add_u32 m0, s14, 0x5800
	s_nop 0
	global_load_lds_dwordx4 v[74:75], off
	s_add_u32 m0, s14, 0x6800
	s_nop 0
	global_load_lds_dwordx4 v[78:79], off
	s_add_u32 m0, s14, 0x7800
	s_nop 0
	global_load_lds_dwordx4 v[82:83], off
	s_add_u32 m0, s14, 0x8780
	s_nop 0
	global_load_lds_dwordx4 v[68:69], off offset:128
	s_add_u32 m0, s14, 0x9780
	s_nop 0
	global_load_lds_dwordx4 v[72:73], off offset:128
	s_add_u32 m0, s14, 0xa780
	s_nop 0
	global_load_lds_dwordx4 v[76:77], off offset:128
	s_add_u32 m0, s14, 0xb780
	s_nop 0
	global_load_lds_dwordx4 v[80:81], off offset:128
	s_add_u32 m0, s14, 0xc780
	s_nop 0
	global_load_lds_dwordx4 v[70:71], off offset:128
	s_add_u32 m0, s14, 0xd780
	s_nop 0
	global_load_lds_dwordx4 v[74:75], off offset:128
	s_add_u32 m0, s14, 0xe780
	s_nop 0
	global_load_lds_dwordx4 v[78:79], off offset:128
	s_add_u32 m0, s14, 0xf780
	s_nop 0
	global_load_lds_dwordx4 v[82:83], off offset:128
	s_waitcnt vmcnt(8)
	s_barrier
	ds_read_b128 v[94:97], v86 offset:2048
	ds_read_b128 v[98:101], v86 offset:6144
	ds_read_b128 v[102:105], v90 offset:2048
	ds_read_b128 v[106:109], v90 offset:6144
	ds_read_b128 v[110:113], v87 offset:2048
	ds_read_b128 v[114:117], v87 offset:6144
	ds_read_b128 v[118:121], v91 offset:2048
	ds_read_b128 v[122:125], v91 offset:6144
	ds_read_b128 v[126:129], v88 offset:2048
	ds_read_b128 v[130:133], v88 offset:6144
	ds_read_b128 v[134:137], v92 offset:2048
	ds_read_b128 v[138:141], v92 offset:6144
	ds_read_b128 v[142:145], v89 offset:2048
	ds_read_b128 v[146:149], v89 offset:6144
	ds_read_b128 v[150:153], v93 offset:2048
	ds_read_b128 v[154:157], v93 offset:6144
	s_waitcnt lgkmcnt(0)
	s_barrier
	s_add_u32 m0, s14, 0x700
	s_nop 0
	global_load_lds_dwordx4 v[68:69], off offset:256
	s_add_u32 m0, s14, 0x1700
	s_nop 0
	global_load_lds_dwordx4 v[72:73], off offset:256
	s_add_u32 m0, s14, 0x2700
	s_nop 0
	global_load_lds_dwordx4 v[76:77], off offset:256
	s_add_u32 m0, s14, 0x3700
	s_nop 0
	global_load_lds_dwordx4 v[80:81], off offset:256
	s_add_u32 m0, s14, 0x4700
	s_nop 0
	global_load_lds_dwordx4 v[70:71], off offset:256
	s_add_u32 m0, s14, 0x5700
	s_nop 0
	global_load_lds_dwordx4 v[74:75], off offset:256
	s_add_u32 m0, s14, 0x6700
	s_nop 0
	global_load_lds_dwordx4 v[78:79], off offset:256
	s_add_u32 m0, s14, 0x7700
	s_nop 0
	global_load_lds_dwordx4 v[82:83], off offset:256
	v_mfma_f32_32x32x16_bf16 v[34:49], v[94:97], v[102:105], 0
	v_mfma_f32_32x32x16_bf16 v[50:65], v[94:97], v[106:109], 0
	v_mfma_f32_32x32x16_bf16 v[2:17], v[98:101], v[102:105], 0
	v_mfma_f32_32x32x16_bf16 v[18:33], v[98:101], v[106:109], 0
	s_waitcnt vmcnt(8)
	s_barrier
	ds_read_b128 v[94:97], v86 offset:34816
	ds_read_b128 v[98:101], v86 offset:38912
	ds_read_b128 v[102:105], v90 offset:34816
	ds_read_b128 v[106:109], v90 offset:38912
	v_mfma_f32_32x32x16_bf16 v[34:49], v[110:113], v[118:121], v[34:49]
	v_mfma_f32_32x32x16_bf16 v[50:65], v[110:113], v[122:125], v[50:65]
	v_mfma_f32_32x32x16_bf16 v[2:17], v[114:117], v[118:121], v[2:17]
	v_mfma_f32_32x32x16_bf16 v[18:33], v[114:117], v[122:125], v[18:33]
	ds_read_b128 v[110:113], v87 offset:34816
	ds_read_b128 v[114:117], v87 offset:38912
	ds_read_b128 v[118:121], v91 offset:34816
	ds_read_b128 v[122:125], v91 offset:38912
	v_mfma_f32_32x32x16_bf16 v[34:49], v[126:129], v[134:137], v[34:49]
	v_mfma_f32_32x32x16_bf16 v[50:65], v[126:129], v[138:141], v[50:65]
	v_mfma_f32_32x32x16_bf16 v[2:17], v[130:133], v[134:137], v[2:17]
	v_mfma_f32_32x32x16_bf16 v[18:33], v[130:133], v[138:141], v[18:33]
	ds_read_b128 v[126:129], v88 offset:34816
	ds_read_b128 v[130:133], v88 offset:38912
	ds_read_b128 v[134:137], v92 offset:34816
	ds_read_b128 v[138:141], v92 offset:38912
	v_mfma_f32_32x32x16_bf16 v[34:49], v[142:145], v[150:153], v[34:49]
	v_mfma_f32_32x32x16_bf16 v[50:65], v[142:145], v[154:157], v[50:65]
	v_mfma_f32_32x32x16_bf16 v[2:17], v[146:149], v[150:153], v[2:17]
	v_mfma_f32_32x32x16_bf16 v[18:33], v[146:149], v[154:157], v[18:33]
	ds_read_b128 v[142:145], v89 offset:34816
	ds_read_b128 v[146:149], v89 offset:38912
	ds_read_b128 v[150:153], v93 offset:34816
	ds_read_b128 v[154:157], v93 offset:38912
	s_waitcnt lgkmcnt(0)
	s_barrier
	v_mfma_f32_32x32x16_bf16 v[34:49], v[94:97], v[102:105], v[34:49]
	s_add_u32 m0, s14, 0x8680
	s_nop 0
	global_load_lds_dwordx4 v[68:69], off offset:384
	s_add_u32 m0, s14, 0x9680
	s_nop 0
	global_load_lds_dwordx4 v[72:73], off offset:384
	v_mfma_f32_32x32x16_bf16 v[50:65], v[94:97], v[106:109], v[50:65]
	s_add_u32 m0, s14, 0xa680
	s_nop 0
	global_load_lds_dwordx4 v[76:77], off offset:384
	s_add_u32 m0, s14, 0xb680
	s_nop 0
	global_load_lds_dwordx4 v[80:81], off offset:384
	v_mfma_f32_32x32x16_bf16 v[2:17], v[98:101], v[102:105], v[2:17]
	s_add_u32 m0, s14, 0xc680
	s_nop 0
	global_load_lds_dwordx4 v[70:71], off offset:384
	s_add_u32 m0, s14, 0xd680
	s_nop 0
	global_load_lds_dwordx4 v[74:75], off offset:384
	v_mfma_f32_32x32x16_bf16 v[18:33], v[98:101], v[106:109], v[18:33]
	s_add_u32 m0, s14, 0xe680
	s_nop 0
	global_load_lds_dwordx4 v[78:79], off offset:384
	s_add_u32 m0, s14, 0xf680
	s_nop 0
	global_load_lds_dwordx4 v[82:83], off offset:384
	s_waitcnt vmcnt(8)
	s_barrier
	ds_read_b128 v[94:97], v86 offset:2048
	ds_read_b128 v[98:101], v86 offset:6144
	ds_read_b128 v[102:105], v90 offset:2048
	ds_read_b128 v[106:109], v90 offset:6144
	v_mfma_f32_32x32x16_bf16 v[34:49], v[110:113], v[118:121], v[34:49]
	v_mfma_f32_32x32x16_bf16 v[50:65], v[110:113], v[122:125], v[50:65]
	v_mfma_f32_32x32x16_bf16 v[2:17], v[114:117], v[118:121], v[2:17]
	v_mfma_f32_32x32x16_bf16 v[18:33], v[114:117], v[122:125], v[18:33]
	ds_read_b128 v[110:113], v87 offset:2048
	ds_read_b128 v[114:117], v87 offset:6144
	ds_read_b128 v[118:121], v91 offset:2048
	ds_read_b128 v[122:125], v91 offset:6144
	v_mfma_f32_32x32x16_bf16 v[34:49], v[126:129], v[134:137], v[34:49]
	v_mfma_f32_32x32x16_bf16 v[50:65], v[126:129], v[138:141], v[50:65]
	v_mfma_f32_32x32x16_bf16 v[2:17], v[130:133], v[134:137], v[2:17]
	v_mfma_f32_32x32x16_bf16 v[18:33], v[130:133], v[138:141], v[18:33]
	ds_read_b128 v[126:129], v88 offset:2048
	ds_read_b128 v[130:133], v88 offset:6144
	ds_read_b128 v[134:137], v92 offset:2048
	ds_read_b128 v[138:141], v92 offset:6144
	v_mfma_f32_32x32x16_bf16 v[34:49], v[142:145], v[150:153], v[34:49]
	v_mfma_f32_32x32x16_bf16 v[50:65], v[142:145], v[154:157], v[50:65]
	v_mfma_f32_32x32x16_bf16 v[2:17], v[146:149], v[150:153], v[2:17]
	v_mfma_f32_32x32x16_bf16 v[18:33], v[146:149], v[154:157], v[18:33]
	ds_read_b128 v[142:145], v89 offset:2048
	ds_read_b128 v[146:149], v89 offset:6144
	ds_read_b128 v[150:153], v93 offset:2048
	ds_read_b128 v[154:157], v93 offset:6144
	s_waitcnt lgkmcnt(0)
	s_barrier
	v_mfma_f32_32x32x16_bf16 v[34:49], v[94:97], v[102:105], v[34:49]
	s_add_u32 m0, s14, 0x600
	s_nop 0
	global_load_lds_dwordx4 v[68:69], off offset:512
	s_add_u32 m0, s14, 0x1600
	s_nop 0
	global_load_lds_dwordx4 v[72:73], off offset:512
	v_mfma_f32_32x32x16_bf16 v[50:65], v[94:97], v[106:109], v[50:65]
	s_add_u32 m0, s14, 0x2600
	s_nop 0
	global_load_lds_dwordx4 v[76:77], off offset:512
	s_add_u32 m0, s14, 0x3600
	s_nop 0
	global_load_lds_dwordx4 v[80:81], off offset:512
	v_mfma_f32_32x32x16_bf16 v[2:17], v[98:101], v[102:105], v[2:17]
	s_add_u32 m0, s14, 0x4600
	s_nop 0
	global_load_lds_dwordx4 v[70:71], off offset:512
	s_add_u32 m0, s14, 0x5600
	s_nop 0
	global_load_lds_dwordx4 v[74:75], off offset:512
	v_mfma_f32_32x32x16_bf16 v[18:33], v[98:101], v[106:109], v[18:33]
	s_add_u32 m0, s14, 0x6600
	s_nop 0
	global_load_lds_dwordx4 v[78:79], off offset:512
	s_add_u32 m0, s14, 0x7600
	s_nop 0
	global_load_lds_dwordx4 v[82:83], off offset:512
	s_waitcnt vmcnt(8)
	s_barrier
	ds_read_b128 v[94:97], v86 offset:34816
	ds_read_b128 v[98:101], v86 offset:38912
	ds_read_b128 v[102:105], v90 offset:34816
	ds_read_b128 v[106:109], v90 offset:38912
	v_mfma_f32_32x32x16_bf16 v[34:49], v[110:113], v[118:121], v[34:49]
	v_mfma_f32_32x32x16_bf16 v[50:65], v[110:113], v[122:125], v[50:65]
	v_mfma_f32_32x32x16_bf16 v[2:17], v[114:117], v[118:121], v[2:17]
	v_mfma_f32_32x32x16_bf16 v[18:33], v[114:117], v[122:125], v[18:33]
	ds_read_b128 v[110:113], v87 offset:34816
	ds_read_b128 v[114:117], v87 offset:38912
	ds_read_b128 v[118:121], v91 offset:34816
	ds_read_b128 v[122:125], v91 offset:38912
	v_mfma_f32_32x32x16_bf16 v[34:49], v[126:129], v[134:137], v[34:49]
	v_mfma_f32_32x32x16_bf16 v[50:65], v[126:129], v[138:141], v[50:65]
	v_mfma_f32_32x32x16_bf16 v[2:17], v[130:133], v[134:137], v[2:17]
	v_mfma_f32_32x32x16_bf16 v[18:33], v[130:133], v[138:141], v[18:33]
	ds_read_b128 v[126:129], v88 offset:34816
	ds_read_b128 v[130:133], v88 offset:38912
	ds_read_b128 v[134:137], v92 offset:34816
	ds_read_b128 v[138:141], v92 offset:38912
	v_mfma_f32_32x32x16_bf16 v[34:49], v[142:145], v[150:153], v[34:49]
	v_mfma_f32_32x32x16_bf16 v[50:65], v[142:145], v[154:157], v[50:65]
	v_mfma_f32_32x32x16_bf16 v[2:17], v[146:149], v[150:153], v[2:17]
	v_mfma_f32_32x32x16_bf16 v[18:33], v[146:149], v[154:157], v[18:33]
	ds_read_b128 v[142:145], v89 offset:34816
	ds_read_b128 v[146:149], v89 offset:38912
	ds_read_b128 v[150:153], v93 offset:34816
	ds_read_b128 v[154:157], v93 offset:38912
	s_waitcnt lgkmcnt(0)
	s_barrier
	v_mfma_f32_32x32x16_bf16 v[34:49], v[94:97], v[102:105], v[34:49]
	s_add_u32 m0, s14, 0x8580
	s_nop 0
	global_load_lds_dwordx4 v[68:69], off offset:640
	s_add_u32 m0, s14, 0x9580
	s_nop 0
	global_load_lds_dwordx4 v[72:73], off offset:640
	v_mfma_f32_32x32x16_bf16 v[50:65], v[94:97], v[106:109], v[50:65]
	s_add_u32 m0, s14, 0xa580
	s_nop 0
	global_load_lds_dwordx4 v[76:77], off offset:640
	s_add_u32 m0, s14, 0xb580
	s_nop 0
	global_load_lds_dwordx4 v[80:81], off offset:640
	v_mfma_f32_32x32x16_bf16 v[2:17], v[98:101], v[102:105], v[2:17]
	s_add_u32 m0, s14, 0xc580
	s_nop 0
	global_load_lds_dwordx4 v[70:71], off offset:640
	s_add_u32 m0, s14, 0xd580
	s_nop 0
	global_load_lds_dwordx4 v[74:75], off offset:640
	v_mfma_f32_32x32x16_bf16 v[18:33], v[98:101], v[106:109], v[18:33]
	s_add_u32 m0, s14, 0xe580
	s_nop 0
	global_load_lds_dwordx4 v[78:79], off offset:640
	s_add_u32 m0, s14, 0xf580
	s_nop 0
	global_load_lds_dwordx4 v[82:83], off offset:640
	s_waitcnt vmcnt(8)
	s_barrier
	ds_read_b128 v[94:97], v86 offset:2048
	ds_read_b128 v[98:101], v86 offset:6144
	ds_read_b128 v[102:105], v90 offset:2048
	ds_read_b128 v[106:109], v90 offset:6144
	v_mfma_f32_32x32x16_bf16 v[34:49], v[110:113], v[118:121], v[34:49]
	v_mfma_f32_32x32x16_bf16 v[50:65], v[110:113], v[122:125], v[50:65]
	v_mfma_f32_32x32x16_bf16 v[2:17], v[114:117], v[118:121], v[2:17]
	v_mfma_f32_32x32x16_bf16 v[18:33], v[114:117], v[122:125], v[18:33]
	ds_read_b128 v[110:113], v87 offset:2048
	ds_read_b128 v[114:117], v87 offset:6144
	ds_read_b128 v[118:121], v91 offset:2048
	ds_read_b128 v[122:125], v91 offset:6144
	v_mfma_f32_32x32x16_bf16 v[34:49], v[126:129], v[134:137], v[34:49]
	v_mfma_f32_32x32x16_bf16 v[50:65], v[126:129], v[138:141], v[50:65]
	v_mfma_f32_32x32x16_bf16 v[2:17], v[130:133], v[134:137], v[2:17]
	v_mfma_f32_32x32x16_bf16 v[18:33], v[130:133], v[138:141], v[18:33]
	ds_read_b128 v[126:129], v88 offset:2048
	ds_read_b128 v[130:133], v88 offset:6144
	ds_read_b128 v[134:137], v92 offset:2048
	ds_read_b128 v[138:141], v92 offset:6144
	v_mfma_f32_32x32x16_bf16 v[34:49], v[142:145], v[150:153], v[34:49]
	v_mfma_f32_32x32x16_bf16 v[50:65], v[142:145], v[154:157], v[50:65]
	v_mfma_f32_32x32x16_bf16 v[2:17], v[146:149], v[150:153], v[2:17]
	v_mfma_f32_32x32x16_bf16 v[18:33], v[146:149], v[154:157], v[18:33]
	ds_read_b128 v[142:145], v89 offset:2048
	ds_read_b128 v[146:149], v89 offset:6144
	ds_read_b128 v[150:153], v93 offset:2048
	ds_read_b128 v[154:157], v93 offset:6144
	s_waitcnt lgkmcnt(0)
	s_barrier
	v_mfma_f32_32x32x16_bf16 v[34:49], v[94:97], v[102:105], v[34:49]
	s_add_u32 m0, s14, 0x500
	s_nop 0
	global_load_lds_dwordx4 v[68:69], off offset:768
	s_add_u32 m0, s14, 0x1500
	s_nop 0
	global_load_lds_dwordx4 v[72:73], off offset:768
	v_mfma_f32_32x32x16_bf16 v[50:65], v[94:97], v[106:109], v[50:65]
	s_add_u32 m0, s14, 0x2500
	s_nop 0
	global_load_lds_dwordx4 v[76:77], off offset:768
	s_add_u32 m0, s14, 0x3500
	s_nop 0
	global_load_lds_dwordx4 v[80:81], off offset:768
	v_mfma_f32_32x32x16_bf16 v[2:17], v[98:101], v[102:105], v[2:17]
	s_add_u32 m0, s14, 0x4500
	s_nop 0
	global_load_lds_dwordx4 v[70:71], off offset:768
	s_add_u32 m0, s14, 0x5500
	s_nop 0
	global_load_lds_dwordx4 v[74:75], off offset:768
	v_mfma_f32_32x32x16_bf16 v[18:33], v[98:101], v[106:109], v[18:33]
	s_add_u32 m0, s14, 0x6500
	s_nop 0
	global_load_lds_dwordx4 v[78:79], off offset:768
	s_add_u32 m0, s14, 0x7500
	s_nop 0
	global_load_lds_dwordx4 v[82:83], off offset:768
	s_waitcnt vmcnt(8)
	s_barrier
	ds_read_b128 v[94:97], v86 offset:34816
	ds_read_b128 v[98:101], v86 offset:38912
	ds_read_b128 v[102:105], v90 offset:34816
	ds_read_b128 v[106:109], v90 offset:38912
	v_mfma_f32_32x32x16_bf16 v[34:49], v[110:113], v[118:121], v[34:49]
	v_mfma_f32_32x32x16_bf16 v[50:65], v[110:113], v[122:125], v[50:65]
	v_mfma_f32_32x32x16_bf16 v[2:17], v[114:117], v[118:121], v[2:17]
	v_mfma_f32_32x32x16_bf16 v[18:33], v[114:117], v[122:125], v[18:33]
	ds_read_b128 v[110:113], v87 offset:34816
	ds_read_b128 v[114:117], v87 offset:38912
	ds_read_b128 v[118:121], v91 offset:34816
	ds_read_b128 v[122:125], v91 offset:38912
	v_mfma_f32_32x32x16_bf16 v[34:49], v[126:129], v[134:137], v[34:49]
	v_mfma_f32_32x32x16_bf16 v[50:65], v[126:129], v[138:141], v[50:65]
	v_mfma_f32_32x32x16_bf16 v[2:17], v[130:133], v[134:137], v[2:17]
	v_mfma_f32_32x32x16_bf16 v[18:33], v[130:133], v[138:141], v[18:33]
	ds_read_b128 v[126:129], v88 offset:34816
	ds_read_b128 v[130:133], v88 offset:38912
	ds_read_b128 v[134:137], v92 offset:34816
	ds_read_b128 v[138:141], v92 offset:38912
	v_mfma_f32_32x32x16_bf16 v[34:49], v[142:145], v[150:153], v[34:49]
	v_mfma_f32_32x32x16_bf16 v[50:65], v[142:145], v[154:157], v[50:65]
	v_mfma_f32_32x32x16_bf16 v[2:17], v[146:149], v[150:153], v[2:17]
	v_mfma_f32_32x32x16_bf16 v[18:33], v[146:149], v[154:157], v[18:33]
	ds_read_b128 v[142:145], v89 offset:34816
	ds_read_b128 v[146:149], v89 offset:38912
	ds_read_b128 v[150:153], v93 offset:34816
	ds_read_b128 v[154:157], v93 offset:38912
	s_waitcnt lgkmcnt(0)
	s_barrier
	v_mfma_f32_32x32x16_bf16 v[34:49], v[94:97], v[102:105], v[34:49]
	s_add_u32 m0, s14, 0x8480
	s_nop 0
	global_load_lds_dwordx4 v[68:69], off offset:896
	s_add_u32 m0, s14, 0x9480
	s_nop 0
	global_load_lds_dwordx4 v[72:73], off offset:896
	v_mfma_f32_32x32x16_bf16 v[50:65], v[94:97], v[106:109], v[50:65]
	s_add_u32 m0, s14, 0xa480
	s_nop 0
	global_load_lds_dwordx4 v[76:77], off offset:896
	s_add_u32 m0, s14, 0xb480
	s_nop 0
	global_load_lds_dwordx4 v[80:81], off offset:896
	v_mfma_f32_32x32x16_bf16 v[2:17], v[98:101], v[102:105], v[2:17]
	s_add_u32 m0, s14, 0xc480
	s_nop 0
	global_load_lds_dwordx4 v[70:71], off offset:896
	s_add_u32 m0, s14, 0xd480
	s_nop 0
	global_load_lds_dwordx4 v[74:75], off offset:896
	v_mfma_f32_32x32x16_bf16 v[18:33], v[98:101], v[106:109], v[18:33]
	s_add_u32 m0, s14, 0xe480
	s_nop 0
	global_load_lds_dwordx4 v[78:79], off offset:896
	s_add_u32 m0, s14, 0xf480
	s_nop 0
	global_load_lds_dwordx4 v[82:83], off offset:896
	s_waitcnt vmcnt(8)
	s_barrier
	ds_read_b128 v[94:97], v86 offset:2048
	ds_read_b128 v[98:101], v86 offset:6144
	ds_read_b128 v[102:105], v90 offset:2048
	ds_read_b128 v[106:109], v90 offset:6144
	v_mfma_f32_32x32x16_bf16 v[34:49], v[110:113], v[118:121], v[34:49]
	v_mfma_f32_32x32x16_bf16 v[50:65], v[110:113], v[122:125], v[50:65]
	v_mfma_f32_32x32x16_bf16 v[2:17], v[114:117], v[118:121], v[2:17]
	v_mfma_f32_32x32x16_bf16 v[18:33], v[114:117], v[122:125], v[18:33]
	ds_read_b128 v[110:113], v87 offset:2048
	ds_read_b128 v[114:117], v87 offset:6144
	ds_read_b128 v[118:121], v91 offset:2048
	ds_read_b128 v[122:125], v91 offset:6144
	v_mfma_f32_32x32x16_bf16 v[34:49], v[126:129], v[134:137], v[34:49]
	v_mfma_f32_32x32x16_bf16 v[50:65], v[126:129], v[138:141], v[50:65]
	v_mfma_f32_32x32x16_bf16 v[2:17], v[130:133], v[134:137], v[2:17]
	v_mfma_f32_32x32x16_bf16 v[18:33], v[130:133], v[138:141], v[18:33]
	ds_read_b128 v[126:129], v88 offset:2048
	ds_read_b128 v[130:133], v88 offset:6144
	ds_read_b128 v[134:137], v92 offset:2048
	ds_read_b128 v[138:141], v92 offset:6144
	v_mfma_f32_32x32x16_bf16 v[34:49], v[142:145], v[150:153], v[34:49]
	v_mfma_f32_32x32x16_bf16 v[50:65], v[142:145], v[154:157], v[50:65]
	v_mfma_f32_32x32x16_bf16 v[2:17], v[146:149], v[150:153], v[2:17]
	v_mfma_f32_32x32x16_bf16 v[18:33], v[146:149], v[154:157], v[18:33]
	ds_read_b128 v[142:145], v89 offset:2048
	ds_read_b128 v[146:149], v89 offset:6144
	ds_read_b128 v[150:153], v93 offset:2048
	ds_read_b128 v[154:157], v93 offset:6144
	s_waitcnt lgkmcnt(0)
	s_barrier
	v_mfma_f32_32x32x16_bf16 v[34:49], v[94:97], v[102:105], v[34:49]
	s_add_u32 m0, s14, 0x400
	s_nop 0
	global_load_lds_dwordx4 v[68:69], off offset:1024
	s_add_u32 m0, s14, 0x1400
	s_nop 0
	global_load_lds_dwordx4 v[72:73], off offset:1024
	v_mfma_f32_32x32x16_bf16 v[50:65], v[94:97], v[106:109], v[50:65]
	s_add_u32 m0, s14, 0x2400
	s_nop 0
	global_load_lds_dwordx4 v[76:77], off offset:1024
	s_add_u32 m0, s14, 0x3400
	s_nop 0
	global_load_lds_dwordx4 v[80:81], off offset:1024
	v_mfma_f32_32x32x16_bf16 v[2:17], v[98:101], v[102:105], v[2:17]
	s_add_u32 m0, s14, 0x4400
	s_nop 0
	global_load_lds_dwordx4 v[70:71], off offset:1024
	s_add_u32 m0, s14, 0x5400
	s_nop 0
	global_load_lds_dwordx4 v[74:75], off offset:1024
	v_mfma_f32_32x32x16_bf16 v[18:33], v[98:101], v[106:109], v[18:33]
	s_add_u32 m0, s14, 0x6400
	s_nop 0
	global_load_lds_dwordx4 v[78:79], off offset:1024
	s_add_u32 m0, s14, 0x7400
	s_nop 0
	global_load_lds_dwordx4 v[82:83], off offset:1024
	s_waitcnt vmcnt(8)
	s_barrier
	ds_read_b128 v[94:97], v86 offset:34816
	ds_read_b128 v[98:101], v86 offset:38912
	ds_read_b128 v[102:105], v90 offset:34816
	ds_read_b128 v[106:109], v90 offset:38912
	v_mfma_f32_32x32x16_bf16 v[34:49], v[110:113], v[118:121], v[34:49]
	v_mfma_f32_32x32x16_bf16 v[50:65], v[110:113], v[122:125], v[50:65]
	v_mfma_f32_32x32x16_bf16 v[2:17], v[114:117], v[118:121], v[2:17]
	v_mfma_f32_32x32x16_bf16 v[18:33], v[114:117], v[122:125], v[18:33]
	ds_read_b128 v[110:113], v87 offset:34816
	ds_read_b128 v[114:117], v87 offset:38912
	ds_read_b128 v[118:121], v91 offset:34816
	ds_read_b128 v[122:125], v91 offset:38912
	v_mfma_f32_32x32x16_bf16 v[34:49], v[126:129], v[134:137], v[34:49]
	v_mfma_f32_32x32x16_bf16 v[50:65], v[126:129], v[138:141], v[50:65]
	v_mfma_f32_32x32x16_bf16 v[2:17], v[130:133], v[134:137], v[2:17]
	v_mfma_f32_32x32x16_bf16 v[18:33], v[130:133], v[138:141], v[18:33]
	ds_read_b128 v[126:129], v88 offset:34816
	ds_read_b128 v[130:133], v88 offset:38912
	ds_read_b128 v[134:137], v92 offset:34816
	ds_read_b128 v[138:141], v92 offset:38912
	v_mfma_f32_32x32x16_bf16 v[34:49], v[142:145], v[150:153], v[34:49]
	v_mfma_f32_32x32x16_bf16 v[50:65], v[142:145], v[154:157], v[50:65]
	v_mfma_f32_32x32x16_bf16 v[2:17], v[146:149], v[150:153], v[2:17]
	v_mfma_f32_32x32x16_bf16 v[18:33], v[146:149], v[154:157], v[18:33]
	ds_read_b128 v[142:145], v89 offset:34816
	ds_read_b128 v[146:149], v89 offset:38912
	ds_read_b128 v[150:153], v93 offset:34816
	ds_read_b128 v[154:157], v93 offset:38912
	s_waitcnt lgkmcnt(0)
	s_barrier
	v_mfma_f32_32x32x16_bf16 v[34:49], v[94:97], v[102:105], v[34:49]
	s_add_u32 m0, s14, 0x8380
	s_nop 0
	global_load_lds_dwordx4 v[68:69], off offset:1152
	s_add_u32 m0, s14, 0x9380
	s_nop 0
	global_load_lds_dwordx4 v[72:73], off offset:1152
	v_mfma_f32_32x32x16_bf16 v[50:65], v[94:97], v[106:109], v[50:65]
	s_add_u32 m0, s14, 0xa380
	s_nop 0
	global_load_lds_dwordx4 v[76:77], off offset:1152
	s_add_u32 m0, s14, 0xb380
	s_nop 0
	global_load_lds_dwordx4 v[80:81], off offset:1152
	v_mfma_f32_32x32x16_bf16 v[2:17], v[98:101], v[102:105], v[2:17]
	s_add_u32 m0, s14, 0xc380
	s_nop 0
	global_load_lds_dwordx4 v[70:71], off offset:1152
	s_add_u32 m0, s14, 0xd380
	s_nop 0
	global_load_lds_dwordx4 v[74:75], off offset:1152
	v_mfma_f32_32x32x16_bf16 v[18:33], v[98:101], v[106:109], v[18:33]
	s_add_u32 m0, s14, 0xe380
	s_nop 0
	global_load_lds_dwordx4 v[78:79], off offset:1152
	s_add_u32 m0, s14, 0xf380
	s_nop 0
	global_load_lds_dwordx4 v[82:83], off offset:1152
	s_waitcnt vmcnt(8)
	s_barrier
	ds_read_b128 v[94:97], v86 offset:2048
	ds_read_b128 v[98:101], v86 offset:6144
	ds_read_b128 v[102:105], v90 offset:2048
	ds_read_b128 v[106:109], v90 offset:6144
	v_mfma_f32_32x32x16_bf16 v[34:49], v[110:113], v[118:121], v[34:49]
	v_mfma_f32_32x32x16_bf16 v[50:65], v[110:113], v[122:125], v[50:65]
	v_mfma_f32_32x32x16_bf16 v[2:17], v[114:117], v[118:121], v[2:17]
	v_mfma_f32_32x32x16_bf16 v[18:33], v[114:117], v[122:125], v[18:33]
	ds_read_b128 v[110:113], v87 offset:2048
	ds_read_b128 v[114:117], v87 offset:6144
	ds_read_b128 v[118:121], v91 offset:2048
	ds_read_b128 v[122:125], v91 offset:6144
	v_mfma_f32_32x32x16_bf16 v[34:49], v[126:129], v[134:137], v[34:49]
	v_mfma_f32_32x32x16_bf16 v[50:65], v[126:129], v[138:141], v[50:65]
	v_mfma_f32_32x32x16_bf16 v[2:17], v[130:133], v[134:137], v[2:17]
	v_mfma_f32_32x32x16_bf16 v[18:33], v[130:133], v[138:141], v[18:33]
	ds_read_b128 v[126:129], v88 offset:2048
	ds_read_b128 v[130:133], v88 offset:6144
	ds_read_b128 v[134:137], v92 offset:2048
	ds_read_b128 v[138:141], v92 offset:6144
	v_mfma_f32_32x32x16_bf16 v[34:49], v[142:145], v[150:153], v[34:49]
	v_mfma_f32_32x32x16_bf16 v[50:65], v[142:145], v[154:157], v[50:65]
	v_mfma_f32_32x32x16_bf16 v[2:17], v[146:149], v[150:153], v[2:17]
	v_mfma_f32_32x32x16_bf16 v[18:33], v[146:149], v[154:157], v[18:33]
	ds_read_b128 v[142:145], v89 offset:2048
	ds_read_b128 v[146:149], v89 offset:6144
	ds_read_b128 v[150:153], v93 offset:2048
	ds_read_b128 v[154:157], v93 offset:6144
	s_waitcnt lgkmcnt(0)
	s_barrier
	v_mfma_f32_32x32x16_bf16 v[34:49], v[94:97], v[102:105], v[34:49]
	s_add_u32 m0, s14, 0x300
	s_nop 0
	global_load_lds_dwordx4 v[68:69], off offset:1280
	s_add_u32 m0, s14, 0x1300
	s_nop 0
	global_load_lds_dwordx4 v[72:73], off offset:1280
	v_mfma_f32_32x32x16_bf16 v[50:65], v[94:97], v[106:109], v[50:65]
	s_add_u32 m0, s14, 0x2300
	s_nop 0
	global_load_lds_dwordx4 v[76:77], off offset:1280
	s_add_u32 m0, s14, 0x3300
	s_nop 0
	global_load_lds_dwordx4 v[80:81], off offset:1280
	v_mfma_f32_32x32x16_bf16 v[2:17], v[98:101], v[102:105], v[2:17]
	s_add_u32 m0, s14, 0x4300
	s_nop 0
	global_load_lds_dwordx4 v[70:71], off offset:1280
	s_add_u32 m0, s14, 0x5300
	s_nop 0
	global_load_lds_dwordx4 v[74:75], off offset:1280
	v_mfma_f32_32x32x16_bf16 v[18:33], v[98:101], v[106:109], v[18:33]
	s_add_u32 m0, s14, 0x6300
	s_nop 0
	global_load_lds_dwordx4 v[78:79], off offset:1280
	s_add_u32 m0, s14, 0x7300
	s_nop 0
	global_load_lds_dwordx4 v[82:83], off offset:1280
	s_waitcnt vmcnt(8)
	s_barrier
	ds_read_b128 v[94:97], v86 offset:34816
	ds_read_b128 v[98:101], v86 offset:38912
	ds_read_b128 v[102:105], v90 offset:34816
	ds_read_b128 v[106:109], v90 offset:38912
	v_mfma_f32_32x32x16_bf16 v[34:49], v[110:113], v[118:121], v[34:49]
	v_mfma_f32_32x32x16_bf16 v[50:65], v[110:113], v[122:125], v[50:65]
	v_mfma_f32_32x32x16_bf16 v[2:17], v[114:117], v[118:121], v[2:17]
	v_mfma_f32_32x32x16_bf16 v[18:33], v[114:117], v[122:125], v[18:33]
	ds_read_b128 v[110:113], v87 offset:34816
	ds_read_b128 v[114:117], v87 offset:38912
	ds_read_b128 v[118:121], v91 offset:34816
	ds_read_b128 v[122:125], v91 offset:38912
	v_mfma_f32_32x32x16_bf16 v[34:49], v[126:129], v[134:137], v[34:49]
	v_mfma_f32_32x32x16_bf16 v[50:65], v[126:129], v[138:141], v[50:65]
	v_mfma_f32_32x32x16_bf16 v[2:17], v[130:133], v[134:137], v[2:17]
	v_mfma_f32_32x32x16_bf16 v[18:33], v[130:133], v[138:141], v[18:33]
	ds_read_b128 v[126:129], v88 offset:34816
	ds_read_b128 v[130:133], v88 offset:38912
	ds_read_b128 v[134:137], v92 offset:34816
	ds_read_b128 v[138:141], v92 offset:38912
	v_mfma_f32_32x32x16_bf16 v[34:49], v[142:145], v[150:153], v[34:49]
	v_mfma_f32_32x32x16_bf16 v[50:65], v[142:145], v[154:157], v[50:65]
	v_mfma_f32_32x32x16_bf16 v[2:17], v[146:149], v[150:153], v[2:17]
	v_mfma_f32_32x32x16_bf16 v[18:33], v[146:149], v[154:157], v[18:33]
	ds_read_b128 v[142:145], v89 offset:34816
	ds_read_b128 v[146:149], v89 offset:38912
	ds_read_b128 v[150:153], v93 offset:34816
	ds_read_b128 v[154:157], v93 offset:38912
	s_waitcnt lgkmcnt(0)
	s_barrier
	v_mfma_f32_32x32x16_bf16 v[34:49], v[94:97], v[102:105], v[34:49]
	s_add_u32 m0, s14, 0x8280
	s_nop 0
	global_load_lds_dwordx4 v[68:69], off offset:1408
	s_add_u32 m0, s14, 0x9280
	s_nop 0
	global_load_lds_dwordx4 v[72:73], off offset:1408
	v_mfma_f32_32x32x16_bf16 v[50:65], v[94:97], v[106:109], v[50:65]
	s_add_u32 m0, s14, 0xa280
	s_nop 0
	global_load_lds_dwordx4 v[76:77], off offset:1408
	s_add_u32 m0, s14, 0xb280
	s_nop 0
	global_load_lds_dwordx4 v[80:81], off offset:1408
	v_mfma_f32_32x32x16_bf16 v[2:17], v[98:101], v[102:105], v[2:17]
	s_add_u32 m0, s14, 0xc280
	s_nop 0
	global_load_lds_dwordx4 v[70:71], off offset:1408
	s_add_u32 m0, s14, 0xd280
	s_nop 0
	global_load_lds_dwordx4 v[74:75], off offset:1408
	v_mfma_f32_32x32x16_bf16 v[18:33], v[98:101], v[106:109], v[18:33]
	s_add_u32 m0, s14, 0xe280
	s_nop 0
	global_load_lds_dwordx4 v[78:79], off offset:1408
	s_add_u32 m0, s14, 0xf280
	s_nop 0
	global_load_lds_dwordx4 v[82:83], off offset:1408
	s_waitcnt vmcnt(8)
	s_barrier
	ds_read_b128 v[94:97], v86 offset:2048
	ds_read_b128 v[98:101], v86 offset:6144
	ds_read_b128 v[102:105], v90 offset:2048
	ds_read_b128 v[106:109], v90 offset:6144
	v_mfma_f32_32x32x16_bf16 v[34:49], v[110:113], v[118:121], v[34:49]
	v_mfma_f32_32x32x16_bf16 v[50:65], v[110:113], v[122:125], v[50:65]
	v_mfma_f32_32x32x16_bf16 v[2:17], v[114:117], v[118:121], v[2:17]
	v_mfma_f32_32x32x16_bf16 v[18:33], v[114:117], v[122:125], v[18:33]
	ds_read_b128 v[110:113], v87 offset:2048
	ds_read_b128 v[114:117], v87 offset:6144
	ds_read_b128 v[118:121], v91 offset:2048
	ds_read_b128 v[122:125], v91 offset:6144
	v_mfma_f32_32x32x16_bf16 v[34:49], v[126:129], v[134:137], v[34:49]
	v_mfma_f32_32x32x16_bf16 v[50:65], v[126:129], v[138:141], v[50:65]
	v_mfma_f32_32x32x16_bf16 v[2:17], v[130:133], v[134:137], v[2:17]
	v_mfma_f32_32x32x16_bf16 v[18:33], v[130:133], v[138:141], v[18:33]
	ds_read_b128 v[126:129], v88 offset:2048
	ds_read_b128 v[130:133], v88 offset:6144
	ds_read_b128 v[134:137], v92 offset:2048
	ds_read_b128 v[138:141], v92 offset:6144
	v_mfma_f32_32x32x16_bf16 v[34:49], v[142:145], v[150:153], v[34:49]
	v_mfma_f32_32x32x16_bf16 v[50:65], v[142:145], v[154:157], v[50:65]
	v_mfma_f32_32x32x16_bf16 v[2:17], v[146:149], v[150:153], v[2:17]
	v_mfma_f32_32x32x16_bf16 v[18:33], v[146:149], v[154:157], v[18:33]
	ds_read_b128 v[142:145], v89 offset:2048
	ds_read_b128 v[146:149], v89 offset:6144
	ds_read_b128 v[150:153], v93 offset:2048
	ds_read_b128 v[154:157], v93 offset:6144
	s_waitcnt lgkmcnt(0)
	s_barrier
	v_mfma_f32_32x32x16_bf16 v[34:49], v[94:97], v[102:105], v[34:49]
	s_add_u32 m0, s14, 0x200
	s_nop 0
	global_load_lds_dwordx4 v[68:69], off offset:1536
	s_add_u32 m0, s14, 0x1200
	s_nop 0
	global_load_lds_dwordx4 v[72:73], off offset:1536
	v_mfma_f32_32x32x16_bf16 v[50:65], v[94:97], v[106:109], v[50:65]
	s_add_u32 m0, s14, 0x2200
	s_nop 0
	global_load_lds_dwordx4 v[76:77], off offset:1536
	s_add_u32 m0, s14, 0x3200
	s_nop 0
	global_load_lds_dwordx4 v[80:81], off offset:1536
	v_mfma_f32_32x32x16_bf16 v[2:17], v[98:101], v[102:105], v[2:17]
	s_add_u32 m0, s14, 0x4200
	s_nop 0
	global_load_lds_dwordx4 v[70:71], off offset:1536
	s_add_u32 m0, s14, 0x5200
	s_nop 0
	global_load_lds_dwordx4 v[74:75], off offset:1536
	v_mfma_f32_32x32x16_bf16 v[18:33], v[98:101], v[106:109], v[18:33]
	s_add_u32 m0, s14, 0x6200
	s_nop 0
	global_load_lds_dwordx4 v[78:79], off offset:1536
	s_add_u32 m0, s14, 0x7200
	s_nop 0
	global_load_lds_dwordx4 v[82:83], off offset:1536
	s_waitcnt vmcnt(8)
	s_barrier
	ds_read_b128 v[94:97], v86 offset:34816
	ds_read_b128 v[98:101], v86 offset:38912
	ds_read_b128 v[102:105], v90 offset:34816
	ds_read_b128 v[106:109], v90 offset:38912
	v_mfma_f32_32x32x16_bf16 v[34:49], v[110:113], v[118:121], v[34:49]
	v_mfma_f32_32x32x16_bf16 v[50:65], v[110:113], v[122:125], v[50:65]
	v_mfma_f32_32x32x16_bf16 v[2:17], v[114:117], v[118:121], v[2:17]
	v_mfma_f32_32x32x16_bf16 v[18:33], v[114:117], v[122:125], v[18:33]
	ds_read_b128 v[110:113], v87 offset:34816
	ds_read_b128 v[114:117], v87 offset:38912
	ds_read_b128 v[118:121], v91 offset:34816
	ds_read_b128 v[122:125], v91 offset:38912
	v_mfma_f32_32x32x16_bf16 v[34:49], v[126:129], v[134:137], v[34:49]
	v_mfma_f32_32x32x16_bf16 v[50:65], v[126:129], v[138:141], v[50:65]
	v_mfma_f32_32x32x16_bf16 v[2:17], v[130:133], v[134:137], v[2:17]
	v_mfma_f32_32x32x16_bf16 v[18:33], v[130:133], v[138:141], v[18:33]
	ds_read_b128 v[126:129], v88 offset:34816
	ds_read_b128 v[130:133], v88 offset:38912
	ds_read_b128 v[134:137], v92 offset:34816
	ds_read_b128 v[138:141], v92 offset:38912
	v_mfma_f32_32x32x16_bf16 v[34:49], v[142:145], v[150:153], v[34:49]
	v_mfma_f32_32x32x16_bf16 v[50:65], v[142:145], v[154:157], v[50:65]
	v_mfma_f32_32x32x16_bf16 v[2:17], v[146:149], v[150:153], v[2:17]
	v_mfma_f32_32x32x16_bf16 v[18:33], v[146:149], v[154:157], v[18:33]
	ds_read_b128 v[142:145], v89 offset:34816
	ds_read_b128 v[146:149], v89 offset:38912
	ds_read_b128 v[150:153], v93 offset:34816
	ds_read_b128 v[154:157], v93 offset:38912
	s_waitcnt lgkmcnt(0)
	s_barrier
	v_mfma_f32_32x32x16_bf16 v[34:49], v[94:97], v[102:105], v[34:49]
	s_add_u32 m0, s14, 0x8180
	s_nop 0
	global_load_lds_dwordx4 v[68:69], off offset:1664
	s_add_u32 m0, s14, 0x9180
	s_nop 0
	global_load_lds_dwordx4 v[72:73], off offset:1664
	v_mfma_f32_32x32x16_bf16 v[50:65], v[94:97], v[106:109], v[50:65]
	s_add_u32 m0, s14, 0xa180
	s_nop 0
	global_load_lds_dwordx4 v[76:77], off offset:1664
	s_add_u32 m0, s14, 0xb180
	s_nop 0
	global_load_lds_dwordx4 v[80:81], off offset:1664
	v_mfma_f32_32x32x16_bf16 v[2:17], v[98:101], v[102:105], v[2:17]
	s_add_u32 m0, s14, 0xc180
	s_nop 0
	global_load_lds_dwordx4 v[70:71], off offset:1664
	s_add_u32 m0, s14, 0xd180
	s_nop 0
	global_load_lds_dwordx4 v[74:75], off offset:1664
	v_mfma_f32_32x32x16_bf16 v[18:33], v[98:101], v[106:109], v[18:33]
	s_add_u32 m0, s14, 0xe180
	s_nop 0
	global_load_lds_dwordx4 v[78:79], off offset:1664
	s_add_u32 m0, s14, 0xf180
	s_nop 0
	global_load_lds_dwordx4 v[82:83], off offset:1664
	s_waitcnt vmcnt(8)
	s_barrier
	ds_read_b128 v[94:97], v86 offset:2048
	ds_read_b128 v[98:101], v86 offset:6144
	ds_read_b128 v[102:105], v90 offset:2048
	ds_read_b128 v[106:109], v90 offset:6144
	v_mfma_f32_32x32x16_bf16 v[34:49], v[110:113], v[118:121], v[34:49]
	v_mfma_f32_32x32x16_bf16 v[50:65], v[110:113], v[122:125], v[50:65]
	v_mfma_f32_32x32x16_bf16 v[2:17], v[114:117], v[118:121], v[2:17]
	v_mfma_f32_32x32x16_bf16 v[18:33], v[114:117], v[122:125], v[18:33]
	ds_read_b128 v[110:113], v87 offset:2048
	ds_read_b128 v[114:117], v87 offset:6144
	ds_read_b128 v[118:121], v91 offset:2048
	ds_read_b128 v[122:125], v91 offset:6144
	v_mfma_f32_32x32x16_bf16 v[34:49], v[126:129], v[134:137], v[34:49]
	v_mfma_f32_32x32x16_bf16 v[50:65], v[126:129], v[138:141], v[50:65]
	v_mfma_f32_32x32x16_bf16 v[2:17], v[130:133], v[134:137], v[2:17]
	v_mfma_f32_32x32x16_bf16 v[18:33], v[130:133], v[138:141], v[18:33]
	ds_read_b128 v[126:129], v88 offset:2048
	ds_read_b128 v[130:133], v88 offset:6144
	ds_read_b128 v[134:137], v92 offset:2048
	ds_read_b128 v[138:141], v92 offset:6144
	v_mfma_f32_32x32x16_bf16 v[34:49], v[142:145], v[150:153], v[34:49]
	v_mfma_f32_32x32x16_bf16 v[50:65], v[142:145], v[154:157], v[50:65]
	v_mfma_f32_32x32x16_bf16 v[2:17], v[146:149], v[150:153], v[2:17]
	v_mfma_f32_32x32x16_bf16 v[18:33], v[146:149], v[154:157], v[18:33]
	ds_read_b128 v[142:145], v89 offset:2048
	ds_read_b128 v[146:149], v89 offset:6144
	ds_read_b128 v[150:153], v93 offset:2048
	ds_read_b128 v[154:157], v93 offset:6144
	s_waitcnt lgkmcnt(0)
	s_barrier
	v_mfma_f32_32x32x16_bf16 v[34:49], v[94:97], v[102:105], v[34:49]
	s_add_u32 m0, s14, 0x100
	s_nop 0
	global_load_lds_dwordx4 v[68:69], off offset:1792
	s_add_u32 m0, s14, 0x1100
	s_nop 0
	global_load_lds_dwordx4 v[72:73], off offset:1792
	v_mfma_f32_32x32x16_bf16 v[50:65], v[94:97], v[106:109], v[50:65]
	s_add_u32 m0, s14, 0x2100
	s_nop 0
	global_load_lds_dwordx4 v[76:77], off offset:1792
	s_add_u32 m0, s14, 0x3100
	s_nop 0
	global_load_lds_dwordx4 v[80:81], off offset:1792
	v_mfma_f32_32x32x16_bf16 v[2:17], v[98:101], v[102:105], v[2:17]
	s_add_u32 m0, s14, 0x4100
	s_nop 0
	global_load_lds_dwordx4 v[70:71], off offset:1792
	s_add_u32 m0, s14, 0x5100
	s_nop 0
	global_load_lds_dwordx4 v[74:75], off offset:1792
	v_mfma_f32_32x32x16_bf16 v[18:33], v[98:101], v[106:109], v[18:33]
	s_add_u32 m0, s14, 0x6100
	s_nop 0
	global_load_lds_dwordx4 v[78:79], off offset:1792
	s_add_u32 m0, s14, 0x7100
	s_nop 0
	global_load_lds_dwordx4 v[82:83], off offset:1792
	s_waitcnt vmcnt(8)
	s_barrier
	ds_read_b128 v[94:97], v86 offset:34816
	ds_read_b128 v[98:101], v86 offset:38912
	ds_read_b128 v[102:105], v90 offset:34816
	ds_read_b128 v[106:109], v90 offset:38912
	v_mfma_f32_32x32x16_bf16 v[34:49], v[110:113], v[118:121], v[34:49]
	v_mfma_f32_32x32x16_bf16 v[50:65], v[110:113], v[122:125], v[50:65]
	v_mfma_f32_32x32x16_bf16 v[2:17], v[114:117], v[118:121], v[2:17]
	v_mfma_f32_32x32x16_bf16 v[18:33], v[114:117], v[122:125], v[18:33]
	ds_read_b128 v[110:113], v87 offset:34816
	ds_read_b128 v[114:117], v87 offset:38912
	ds_read_b128 v[118:121], v91 offset:34816
	ds_read_b128 v[122:125], v91 offset:38912
	v_mfma_f32_32x32x16_bf16 v[34:49], v[126:129], v[134:137], v[34:49]
	v_mfma_f32_32x32x16_bf16 v[50:65], v[126:129], v[138:141], v[50:65]
	v_mfma_f32_32x32x16_bf16 v[2:17], v[130:133], v[134:137], v[2:17]
	v_mfma_f32_32x32x16_bf16 v[18:33], v[130:133], v[138:141], v[18:33]
	ds_read_b128 v[126:129], v88 offset:34816
	ds_read_b128 v[130:133], v88 offset:38912
	ds_read_b128 v[134:137], v92 offset:34816
	ds_read_b128 v[138:141], v92 offset:38912
	v_mfma_f32_32x32x16_bf16 v[34:49], v[142:145], v[150:153], v[34:49]
	v_mfma_f32_32x32x16_bf16 v[50:65], v[142:145], v[154:157], v[50:65]
	v_mfma_f32_32x32x16_bf16 v[2:17], v[146:149], v[150:153], v[2:17]
	v_mfma_f32_32x32x16_bf16 v[18:33], v[146:149], v[154:157], v[18:33]
	ds_read_b128 v[142:145], v89 offset:34816
	ds_read_b128 v[146:149], v89 offset:38912
	ds_read_b128 v[150:153], v93 offset:34816
	ds_read_b128 v[154:157], v93 offset:38912
	s_waitcnt lgkmcnt(0)
	s_barrier
	v_mfma_f32_32x32x16_bf16 v[34:49], v[94:97], v[102:105], v[34:49]
	s_add_u32 m0, s14, 0x8080
	s_nop 0
	global_load_lds_dwordx4 v[68:69], off offset:1920
	s_add_u32 m0, s14, 0x9080
	s_nop 0
	global_load_lds_dwordx4 v[72:73], off offset:1920
	v_mfma_f32_32x32x16_bf16 v[50:65], v[94:97], v[106:109], v[50:65]
	s_add_u32 m0, s14, 0xa080
	s_nop 0
	global_load_lds_dwordx4 v[76:77], off offset:1920
	s_add_u32 m0, s14, 0xb080
	s_nop 0
	global_load_lds_dwordx4 v[80:81], off offset:1920
	v_mfma_f32_32x32x16_bf16 v[2:17], v[98:101], v[102:105], v[2:17]
	s_add_u32 m0, s14, 0xc080
	s_nop 0
	global_load_lds_dwordx4 v[70:71], off offset:1920
	s_add_u32 m0, s14, 0xd080
	s_nop 0
	global_load_lds_dwordx4 v[74:75], off offset:1920
	v_mfma_f32_32x32x16_bf16 v[18:33], v[98:101], v[106:109], v[18:33]
	s_add_u32 m0, s14, 0xe080
	s_nop 0
	global_load_lds_dwordx4 v[78:79], off offset:1920
	s_add_u32 m0, s14, 0xf080
	s_nop 0
	global_load_lds_dwordx4 v[82:83], off offset:1920
	s_waitcnt vmcnt(8)
	s_barrier
	ds_read_b128 v[94:97], v86 offset:2048
	ds_read_b128 v[98:101], v86 offset:6144
	ds_read_b128 v[102:105], v90 offset:2048
	ds_read_b128 v[106:109], v90 offset:6144
	v_mfma_f32_32x32x16_bf16 v[34:49], v[110:113], v[118:121], v[34:49]
	v_mfma_f32_32x32x16_bf16 v[50:65], v[110:113], v[122:125], v[50:65]
	v_mfma_f32_32x32x16_bf16 v[2:17], v[114:117], v[118:121], v[2:17]
	v_mfma_f32_32x32x16_bf16 v[18:33], v[114:117], v[122:125], v[18:33]
	ds_read_b128 v[110:113], v87 offset:2048
	ds_read_b128 v[114:117], v87 offset:6144
	ds_read_b128 v[118:121], v91 offset:2048
	ds_read_b128 v[122:125], v91 offset:6144
	v_mfma_f32_32x32x16_bf16 v[34:49], v[126:129], v[134:137], v[34:49]
	v_mfma_f32_32x32x16_bf16 v[50:65], v[126:129], v[138:141], v[50:65]
	v_mfma_f32_32x32x16_bf16 v[2:17], v[130:133], v[134:137], v[2:17]
	v_mfma_f32_32x32x16_bf16 v[18:33], v[130:133], v[138:141], v[18:33]
	ds_read_b128 v[126:129], v88 offset:2048
	ds_read_b128 v[130:133], v88 offset:6144
	ds_read_b128 v[134:137], v92 offset:2048
	ds_read_b128 v[138:141], v92 offset:6144
	v_mfma_f32_32x32x16_bf16 v[34:49], v[142:145], v[150:153], v[34:49]
	v_mfma_f32_32x32x16_bf16 v[50:65], v[142:145], v[154:157], v[50:65]
	v_mfma_f32_32x32x16_bf16 v[2:17], v[146:149], v[150:153], v[2:17]
	v_mfma_f32_32x32x16_bf16 v[18:33], v[146:149], v[154:157], v[18:33]
	ds_read_b128 v[142:145], v89 offset:2048
	ds_read_b128 v[146:149], v89 offset:6144
	ds_read_b128 v[150:153], v93 offset:2048
	ds_read_b128 v[154:157], v93 offset:6144
	s_waitcnt lgkmcnt(0)
	v_mfma_f32_32x32x16_bf16 v[34:49], v[94:97], v[102:105], v[34:49]
	v_mfma_f32_32x32x16_bf16 v[50:65], v[94:97], v[106:109], v[50:65]
	v_mfma_f32_32x32x16_bf16 v[2:17], v[98:101], v[102:105], v[2:17]
	v_mfma_f32_32x32x16_bf16 v[18:33], v[98:101], v[106:109], v[18:33]
	s_waitcnt vmcnt(0)
	s_barrier
	ds_read_b128 v[94:97], v86 offset:34816
	ds_read_b128 v[98:101], v86 offset:38912
	ds_read_b128 v[102:105], v90 offset:34816
	ds_read_b128 v[106:109], v90 offset:38912
	v_mfma_f32_32x32x16_bf16 v[34:49], v[110:113], v[118:121], v[34:49]
	v_mfma_f32_32x32x16_bf16 v[50:65], v[110:113], v[122:125], v[50:65]
	v_mfma_f32_32x32x16_bf16 v[2:17], v[114:117], v[118:121], v[2:17]
	v_mfma_f32_32x32x16_bf16 v[18:33], v[114:117], v[122:125], v[18:33]
	ds_read_b128 v[110:113], v87 offset:34816
	ds_read_b128 v[114:117], v87 offset:38912
	ds_read_b128 v[118:121], v91 offset:34816
	ds_read_b128 v[122:125], v91 offset:38912
	v_mfma_f32_32x32x16_bf16 v[34:49], v[126:129], v[134:137], v[34:49]
	v_mfma_f32_32x32x16_bf16 v[50:65], v[126:129], v[138:141], v[50:65]
	v_mfma_f32_32x32x16_bf16 v[2:17], v[130:133], v[134:137], v[2:17]
	v_mfma_f32_32x32x16_bf16 v[18:33], v[130:133], v[138:141], v[18:33]
	ds_read_b128 v[126:129], v88 offset:34816
	ds_read_b128 v[130:133], v88 offset:38912
	ds_read_b128 v[134:137], v92 offset:34816
	ds_read_b128 v[138:141], v92 offset:38912
	v_mfma_f32_32x32x16_bf16 v[34:49], v[142:145], v[150:153], v[34:49]
	v_mfma_f32_32x32x16_bf16 v[50:65], v[142:145], v[154:157], v[50:65]
	v_mfma_f32_32x32x16_bf16 v[2:17], v[146:149], v[150:153], v[2:17]
	v_mfma_f32_32x32x16_bf16 v[18:33], v[146:149], v[154:157], v[18:33]
	ds_read_b128 v[142:145], v89 offset:34816
	ds_read_b128 v[146:149], v89 offset:38912
	ds_read_b128 v[150:153], v93 offset:34816
	ds_read_b128 v[154:157], v93 offset:38912
	s_waitcnt lgkmcnt(0)
	v_mfma_f32_32x32x16_bf16 v[34:49], v[94:97], v[102:105], v[34:49]
	v_mfma_f32_32x32x16_bf16 v[50:65], v[94:97], v[106:109], v[50:65]
	v_mfma_f32_32x32x16_bf16 v[2:17], v[98:101], v[102:105], v[2:17]
	v_mfma_f32_32x32x16_bf16 v[18:33], v[98:101], v[106:109], v[18:33]
	v_mfma_f32_32x32x16_bf16 v[34:49], v[110:113], v[118:121], v[34:49]
	v_mfma_f32_32x32x16_bf16 v[50:65], v[110:113], v[122:125], v[50:65]
	v_mfma_f32_32x32x16_bf16 v[2:17], v[114:117], v[118:121], v[2:17]
	v_mfma_f32_32x32x16_bf16 v[18:33], v[114:117], v[122:125], v[18:33]
	v_mfma_f32_32x32x16_bf16 v[34:49], v[126:129], v[134:137], v[34:49]
	v_mfma_f32_32x32x16_bf16 v[50:65], v[126:129], v[138:141], v[50:65]
	v_mfma_f32_32x32x16_bf16 v[2:17], v[130:133], v[134:137], v[2:17]
	v_mfma_f32_32x32x16_bf16 v[18:33], v[130:133], v[138:141], v[18:33]
	v_mfma_f32_32x32x16_bf16 v[34:49], v[142:145], v[150:153], v[34:49]
	v_mfma_f32_32x32x16_bf16 v[50:65], v[142:145], v[154:157], v[50:65]
	v_mfma_f32_32x32x16_bf16 v[2:17], v[146:149], v[150:153], v[2:17]
	v_mfma_f32_32x32x16_bf16 v[18:33], v[146:149], v[154:157], v[18:33]
	s_setprio 0
	v_mov_b32_e32 v66, v178
	s_waitcnt lgkmcnt(0)
	s_barrier
	s_nop 0
	v_lshrrev_b32_e32 v0, 1, v66
	v_and_b32_e32 v0, 0xfffffc0, v0
	v_lshrrev_b32_e32 v67, 3, v66
	v_and_or_b32 v0, v67, 4, v0
	v_and_b32_e32 v67, 0x5f, v66
	v_mul_lo_u32 v0, v0, s83
	v_lshl_add_u32 v0, v67, 2, v0
	s_nop 0
	s_nop 11
	ds_write2_b32 v0, v34, v50 offset1:32
	ds_write2_b32 v0, v35, v51 offset0:132 offset1:164
	s_nop 0
	v_add_u32_e32 v34, 0x400, v0
	ds_write2_b32 v34, v36, v52 offset0:8 offset1:40
	ds_write2_b32 v34, v37, v53 offset0:140 offset1:172
	v_add_u32_e32 v34, 0x1000, v0
	ds_write2_b32 v34, v38, v54 offset0:32 offset1:64
	ds_write2_b32 v34, v39, v55 offset0:164 offset1:196
	v_add_u32_e32 v34, 0x1400, v0
	ds_write2_b32 v34, v40, v56 offset0:40 offset1:72
	ds_write2_b32 v34, v41, v57 offset0:172 offset1:204
	v_add_u32_e32 v34, 0x2000, v0
	s_nop 0
	ds_write2_b32 v34, v42, v58 offset0:64 offset1:96
	ds_write2_b32 v34, v43, v59 offset0:196 offset1:228
	v_add_u32_e32 v34, 0x2400, v0
	ds_write2_b32 v34, v44, v60 offset0:72 offset1:104
	ds_write2_b32 v34, v45, v61 offset0:204 offset1:236
	v_add_u32_e32 v34, 0x3000, v0
	ds_write2_b32 v34, v46, v62 offset0:96 offset1:128
	v_add_u32_e32 v34, 0x3200, v0
	ds_write2_b32 v34, v47, v63 offset0:100 offset1:132
	s_nop 0
	v_add_u32_e32 v34, 0x3400, v0
	ds_write2_b32 v34, v48, v64 offset0:104 offset1:136
	v_add_u32_e32 v34, 0x3600, v0
	ds_write2_b32 v34, v49, v65 offset0:108 offset1:140
	v_add_u32_e32 v34, 0x4000, v0
	s_nop 0
	s_nop 11
	ds_write2_b32 v34, v2, v18 offset0:128 offset1:160
	v_add_u32_e32 v2, 0x4400, v0
	ds_write2_b32 v2, v3, v19 offset0:4 offset1:36
	ds_write2_b32 v2, v4, v20 offset0:136 offset1:168
	v_add_u32_e32 v2, 0x4800, v0
	ds_write2_b32 v2, v5, v21 offset0:12 offset1:44
	v_add_u32_e32 v2, 0x5000, v0
	ds_write2_b32 v2, v6, v22 offset0:160 offset1:192
	v_add_u32_e32 v2, 0x5400, v0
	ds_write2_b32 v2, v7, v23 offset0:36 offset1:68
	ds_write2_b32 v2, v8, v24 offset0:168 offset1:200
	v_add_u32_e32 v2, 0x5800, v0
	ds_write2_b32 v2, v9, v25 offset0:44 offset1:76
	v_add_u32_e32 v2, 0x6000, v0
	ds_write2_b32 v2, v10, v26 offset0:192 offset1:224
	v_add_u32_e32 v2, 0x6400, v0
	ds_write2_b32 v2, v11, v27 offset0:68 offset1:100
	ds_write2_b32 v2, v12, v28 offset0:200 offset1:232
	v_add_u32_e32 v2, 0x6800, v0
	ds_write2_b32 v2, v13, v29 offset0:76 offset1:108
	v_add_u32_e32 v2, 0x7200, v0
	ds_write2_b32 v2, v14, v30 offset0:96 offset1:128
	v_add_u32_e32 v2, 0x7400, v0
	ds_write2_b32 v2, v15, v31 offset0:100 offset1:132
	v_add_u32_e32 v2, 0x7600, v0
	v_add_u32_e32 v0, 0x7800, v0
	ds_write2_b32 v0, v17, v33 offset0:108 offset1:140
	v_lshlrev_b32_e32 v0, 3, v66
	v_and_b32_e32 v0, 0x78, v0
	ds_write2_b32 v2, v16, v32 offset0:104 offset1:136
	v_lshlrev_b32_e32 v2, 2, v0
	v_or_b32_e32 v0, s0, v0
	v_lshlrev_b32_e32 v0, 1, v0
	s_waitcnt lgkmcnt(0)
	s_barrier
	v_lshl_add_u64 v[4:5], s[78:79], 0, v[0:1]

.LBB0_855:
	s_lshl_b32 s0, s45, 10
	s_waitcnt vmcnt(3)
	v_mov_b32_e32 v6, v178
	s_add_i32 s0, s24, s0
	s_ashr_i32 s1, s0, 31
	v_ashrrev_i32_e32 v34, 3, v6
	v_lshlrev_b32_e32 v0, 3, v6
	v_ashrrev_i32_e32 v35, 31, v34
	s_lshl_b64 s[0:1], s[0:1], 11
	v_and_b32_e32 v36, 56, v0
	v_lshlrev_b64 v[2:3], 11, v[34:35]
	s_add_u32 s0, s92, s0
	v_lshl_add_u64 v[4:5], s[40:41], 0, v[2:3]
	v_lshlrev_b32_e32 v0, 1, v36
	s_addc_u32 s1, s93, s1
	v_lshl_add_u64 v[148:149], v[4:5], 0, v[0:1]
	v_lshl_add_u64 v[2:3], s[0:1], 0, v[2:3]
	v_lshl_add_u64 v[150:151], v[2:3], 0, v[0:1]
	v_and_b32_e32 v0, 7, v178
	v_bfe_u32 v146, v178, 4, 3
	v_xor_b32_e32 v146, v146, v0
	v_sub_u32_e32 v146, v146, v0
	v_lshlrev_b32_e32 v146, 4, v146
	v_ashrrev_i32_e32 v147, 31, v146
	v_lshl_add_u64 v[148:149], v[148:149], 0, v[146:147]
	v_lshl_add_u64 v[150:151], v[150:151], 0, v[146:147]
	v_add_co_u32_e32 v152, vcc, s73, v148
	s_nop 1
	v_addc_co_u32_e32 v153, vcc, 0, v149, vcc
	v_add_co_u32_e32 v154, vcc, s73, v150
	s_nop 1
	v_addc_co_u32_e32 v155, vcc, 0, v151, vcc
	v_add_co_u32_e32 v156, vcc, s52, v148
	s_nop 1
	v_addc_co_u32_e32 v157, vcc, 0, v149, vcc
	v_add_co_u32_e32 v158, vcc, s52, v150
	s_nop 1
	v_addc_co_u32_e32 v159, vcc, 0, v151, vcc
	v_add_co_u32_e32 v160, vcc, s53, v148
	s_nop 1
	v_addc_co_u32_e32 v161, vcc, 0, v149, vcc
	v_add_co_u32_e32 v162, vcc, s53, v150
	s_nop 1
	v_addc_co_u32_e32 v163, vcc, 0, v151, vcc
	v_and_b32_e32 v0, 31, v178
	v_bfe_u32 v146, v178, 5, 1
	v_bfe_u32 v147, v178, 1, 3
	v_xor_b32_e32 v146, v146, v147
	v_lshlrev_b32_e32 v146, 4, v146
	v_lshl_add_u32 v146, v0, 7, v146
	v_bfe_u32 v147, v178, 7, 1
	v_lshl_add_u32 v130, v147, 13, v146
	v_bfe_u32 v147, v178, 6, 1
	v_lshl_add_u32 v134, v147, 13, v146
	v_add_u32_e32 v134, 0x4000, v134
	v_xor_b32_e32 v131, 32, v130
	v_xor_b32_e32 v135, 32, v134
	v_xor_b32_e32 v132, 64, v130
	v_xor_b32_e32 v136, 64, v134
	v_xor_b32_e32 v133, 96, v130
	v_xor_b32_e32 v137, 96, v134
	v_lshrrev_b32_e32 v146, 6, v178
	v_lshlrev_b32_e32 v146, 10, v146
	s_nop 1
	v_readfirstlane_b32 s14, v146
	v_readlane_b32 s15, v251, 0
	s_cmpk_lt_u32 s15, 0x100
	s_cbranch_scc1 .Lgp_ma
	s_setprio 1
.Lgp_ma:
	s_add_u32 m0, s14, 0x800
	s_nop 0
	global_load_lds_dwordx4 v[148:149], off
	s_add_u32 m0, s14, 0x1800
	s_nop 0
	global_load_lds_dwordx4 v[152:153], off
	s_add_u32 m0, s14, 0x2800
	s_nop 0
	global_load_lds_dwordx4 v[156:157], off
	s_add_u32 m0, s14, 0x3800
	s_nop 0
	global_load_lds_dwordx4 v[160:161], off
	s_add_u32 m0, s14, 0x4800
	s_nop 0
	global_load_lds_dwordx4 v[150:151], off
	s_add_u32 m0, s14, 0x5800
	s_nop 0
	global_load_lds_dwordx4 v[154:155], off
	s_add_u32 m0, s14, 0x6800
	s_nop 0
	global_load_lds_dwordx4 v[158:159], off
	s_add_u32 m0, s14, 0x7800
	s_nop 0
	global_load_lds_dwordx4 v[162:163], off
	s_add_u32 m0, s14, 0x8780
	s_nop 0
	global_load_lds_dwordx4 v[148:149], off offset:128
	s_add_u32 m0, s14, 0x9780
	s_nop 0
	global_load_lds_dwordx4 v[152:153], off offset:128
	s_add_u32 m0, s14, 0xa780
	s_nop 0
	global_load_lds_dwordx4 v[156:157], off offset:128
	s_add_u32 m0, s14, 0xb780
	s_nop 0
	global_load_lds_dwordx4 v[160:161], off offset:128
	s_add_u32 m0, s14, 0xc780
	s_nop 0
	global_load_lds_dwordx4 v[150:151], off offset:128
	s_add_u32 m0, s14, 0xd780
	s_nop 0
	global_load_lds_dwordx4 v[154:155], off offset:128
	s_add_u32 m0, s14, 0xe780
	s_nop 0
	global_load_lds_dwordx4 v[158:159], off offset:128
	s_add_u32 m0, s14, 0xf780
	s_nop 0
	global_load_lds_dwordx4 v[162:163], off offset:128
	s_waitcnt vmcnt(8)
	s_barrier
	ds_read_b128 v[66:69], v130 offset:2048
	ds_read_b128 v[70:73], v130 offset:6144
	ds_read_b128 v[74:77], v134 offset:2048
	ds_read_b128 v[78:81], v134 offset:6144
	ds_read_b128 v[82:85], v131 offset:2048
	ds_read_b128 v[86:89], v131 offset:6144
	ds_read_b128 v[90:93], v135 offset:2048
	ds_read_b128 v[94:97], v135 offset:6144
	ds_read_b128 v[98:101], v132 offset:2048
	ds_read_b128 v[102:105], v132 offset:6144
	ds_read_b128 v[106:109], v136 offset:2048
	ds_read_b128 v[110:113], v136 offset:6144
	ds_read_b128 v[114:117], v133 offset:2048
	ds_read_b128 v[118:121], v133 offset:6144
	ds_read_b128 v[122:125], v137 offset:2048
	ds_read_b128 v[126:129], v137 offset:6144
	s_waitcnt lgkmcnt(0)
	s_barrier
	s_add_u32 m0, s14, 0x700
	s_nop 0
	global_load_lds_dwordx4 v[148:149], off offset:256
	s_add_u32 m0, s14, 0x1700
	s_nop 0
	global_load_lds_dwordx4 v[152:153], off offset:256
	s_add_u32 m0, s14, 0x2700
	s_nop 0
	global_load_lds_dwordx4 v[156:157], off offset:256
	s_add_u32 m0, s14, 0x3700
	s_nop 0
	global_load_lds_dwordx4 v[160:161], off offset:256
	s_add_u32 m0, s14, 0x4700
	s_nop 0
	global_load_lds_dwordx4 v[150:151], off offset:256
	s_add_u32 m0, s14, 0x5700
	s_nop 0
	global_load_lds_dwordx4 v[154:155], off offset:256
	s_add_u32 m0, s14, 0x6700
	s_nop 0
	global_load_lds_dwordx4 v[158:159], off offset:256
	s_add_u32 m0, s14, 0x7700
	s_nop 0
	global_load_lds_dwordx4 v[162:163], off offset:256
	v_mfma_f32_32x32x16_bf16 v[50:65], v[66:69], v[74:77], 0
	v_mfma_f32_32x32x16_bf16 v[34:49], v[66:69], v[78:81], 0
	v_mfma_f32_32x32x16_bf16 v[18:33], v[70:73], v[74:77], 0
	v_mfma_f32_32x32x16_bf16 v[2:17], v[70:73], v[78:81], 0
	s_waitcnt vmcnt(8)
	s_barrier
	ds_read_b128 v[66:69], v130 offset:34816
	ds_read_b128 v[70:73], v130 offset:38912
	ds_read_b128 v[74:77], v134 offset:34816
	ds_read_b128 v[78:81], v134 offset:38912
	v_mfma_f32_32x32x16_bf16 v[50:65], v[82:85], v[90:93], v[50:65]
	v_mfma_f32_32x32x16_bf16 v[34:49], v[82:85], v[94:97], v[34:49]
	v_mfma_f32_32x32x16_bf16 v[18:33], v[86:89], v[90:93], v[18:33]
	v_mfma_f32_32x32x16_bf16 v[2:17], v[86:89], v[94:97], v[2:17]
	ds_read_b128 v[82:85], v131 offset:34816
	ds_read_b128 v[86:89], v131 offset:38912
	ds_read_b128 v[90:93], v135 offset:34816
	ds_read_b128 v[94:97], v135 offset:38912
	v_mfma_f32_32x32x16_bf16 v[50:65], v[98:101], v[106:109], v[50:65]
	v_mfma_f32_32x32x16_bf16 v[34:49], v[98:101], v[110:113], v[34:49]
	v_mfma_f32_32x32x16_bf16 v[18:33], v[102:105], v[106:109], v[18:33]
	v_mfma_f32_32x32x16_bf16 v[2:17], v[102:105], v[110:113], v[2:17]
	ds_read_b128 v[98:101], v132 offset:34816
	ds_read_b128 v[102:105], v132 offset:38912
	ds_read_b128 v[106:109], v136 offset:34816
	ds_read_b128 v[110:113], v136 offset:38912
	v_mfma_f32_32x32x16_bf16 v[50:65], v[114:117], v[122:125], v[50:65]
	v_mfma_f32_32x32x16_bf16 v[34:49], v[114:117], v[126:129], v[34:49]
	v_mfma_f32_32x32x16_bf16 v[18:33], v[118:121], v[122:125], v[18:33]
	v_mfma_f32_32x32x16_bf16 v[2:17], v[118:121], v[126:129], v[2:17]
	ds_read_b128 v[114:117], v133 offset:34816
	ds_read_b128 v[118:121], v133 offset:38912
	ds_read_b128 v[122:125], v137 offset:34816
	ds_read_b128 v[126:129], v137 offset:38912
	s_waitcnt lgkmcnt(0)
	s_barrier
	v_mfma_f32_32x32x16_bf16 v[50:65], v[66:69], v[74:77], v[50:65]
	s_add_u32 m0, s14, 0x8680
	s_nop 0
	global_load_lds_dwordx4 v[148:149], off offset:384
	s_add_u32 m0, s14, 0x9680
	s_nop 0
	global_load_lds_dwordx4 v[152:153], off offset:384
	v_mfma_f32_32x32x16_bf16 v[34:49], v[66:69], v[78:81], v[34:49]
	s_add_u32 m0, s14, 0xa680
	s_nop 0
	global_load_lds_dwordx4 v[156:157], off offset:384
	s_add_u32 m0, s14, 0xb680
	s_nop 0
	global_load_lds_dwordx4 v[160:161], off offset:384
	v_mfma_f32_32x32x16_bf16 v[18:33], v[70:73], v[74:77], v[18:33]
	s_add_u32 m0, s14, 0xc680
	s_nop 0
	global_load_lds_dwordx4 v[150:151], off offset:384
	s_add_u32 m0, s14, 0xd680
	s_nop 0
	global_load_lds_dwordx4 v[154:155], off offset:384
	v_mfma_f32_32x32x16_bf16 v[2:17], v[70:73], v[78:81], v[2:17]
	s_add_u32 m0, s14, 0xe680
	s_nop 0
	global_load_lds_dwordx4 v[158:159], off offset:384
	s_add_u32 m0, s14, 0xf680
	s_nop 0
	global_load_lds_dwordx4 v[162:163], off offset:384
	s_waitcnt vmcnt(8)
	s_barrier
	ds_read_b128 v[66:69], v130 offset:2048
	ds_read_b128 v[70:73], v130 offset:6144
	ds_read_b128 v[74:77], v134 offset:2048
	ds_read_b128 v[78:81], v134 offset:6144
	v_mfma_f32_32x32x16_bf16 v[50:65], v[82:85], v[90:93], v[50:65]
	v_mfma_f32_32x32x16_bf16 v[34:49], v[82:85], v[94:97], v[34:49]
	v_mfma_f32_32x32x16_bf16 v[18:33], v[86:89], v[90:93], v[18:33]
	v_mfma_f32_32x32x16_bf16 v[2:17], v[86:89], v[94:97], v[2:17]
	ds_read_b128 v[82:85], v131 offset:2048
	ds_read_b128 v[86:89], v131 offset:6144
	ds_read_b128 v[90:93], v135 offset:2048
	ds_read_b128 v[94:97], v135 offset:6144
	v_mfma_f32_32x32x16_bf16 v[50:65], v[98:101], v[106:109], v[50:65]
	v_mfma_f32_32x32x16_bf16 v[34:49], v[98:101], v[110:113], v[34:49]
	v_mfma_f32_32x32x16_bf16 v[18:33], v[102:105], v[106:109], v[18:33]
	v_mfma_f32_32x32x16_bf16 v[2:17], v[102:105], v[110:113], v[2:17]
	ds_read_b128 v[98:101], v132 offset:2048
	ds_read_b128 v[102:105], v132 offset:6144
	ds_read_b128 v[106:109], v136 offset:2048
	ds_read_b128 v[110:113], v136 offset:6144
	v_mfma_f32_32x32x16_bf16 v[50:65], v[114:117], v[122:125], v[50:65]
	v_mfma_f32_32x32x16_bf16 v[34:49], v[114:117], v[126:129], v[34:49]
	v_mfma_f32_32x32x16_bf16 v[18:33], v[118:121], v[122:125], v[18:33]
	v_mfma_f32_32x32x16_bf16 v[2:17], v[118:121], v[126:129], v[2:17]
	ds_read_b128 v[114:117], v133 offset:2048
	ds_read_b128 v[118:121], v133 offset:6144
	ds_read_b128 v[122:125], v137 offset:2048
	ds_read_b128 v[126:129], v137 offset:6144
	s_waitcnt lgkmcnt(0)
	s_barrier
	v_mfma_f32_32x32x16_bf16 v[50:65], v[66:69], v[74:77], v[50:65]
	s_add_u32 m0, s14, 0x600
	s_nop 0
	global_load_lds_dwordx4 v[148:149], off offset:512
	s_add_u32 m0, s14, 0x1600
	s_nop 0
	global_load_lds_dwordx4 v[152:153], off offset:512
	v_mfma_f32_32x32x16_bf16 v[34:49], v[66:69], v[78:81], v[34:49]
	s_add_u32 m0, s14, 0x2600
	s_nop 0
	global_load_lds_dwordx4 v[156:157], off offset:512
	s_add_u32 m0, s14, 0x3600
	s_nop 0
	global_load_lds_dwordx4 v[160:161], off offset:512
	v_mfma_f32_32x32x16_bf16 v[18:33], v[70:73], v[74:77], v[18:33]
	s_add_u32 m0, s14, 0x4600
	s_nop 0
	global_load_lds_dwordx4 v[150:151], off offset:512
	s_add_u32 m0, s14, 0x5600
	s_nop 0
	global_load_lds_dwordx4 v[154:155], off offset:512
	v_mfma_f32_32x32x16_bf16 v[2:17], v[70:73], v[78:81], v[2:17]
	s_add_u32 m0, s14, 0x6600
	s_nop 0
	global_load_lds_dwordx4 v[158:159], off offset:512
	s_add_u32 m0, s14, 0x7600
	s_nop 0
	global_load_lds_dwordx4 v[162:163], off offset:512
	s_waitcnt vmcnt(8)
	s_barrier
	ds_read_b128 v[66:69], v130 offset:34816
	ds_read_b128 v[70:73], v130 offset:38912
	ds_read_b128 v[74:77], v134 offset:34816
	ds_read_b128 v[78:81], v134 offset:38912
	v_mfma_f32_32x32x16_bf16 v[50:65], v[82:85], v[90:93], v[50:65]
	v_mfma_f32_32x32x16_bf16 v[34:49], v[82:85], v[94:97], v[34:49]
	v_mfma_f32_32x32x16_bf16 v[18:33], v[86:89], v[90:93], v[18:33]
	v_mfma_f32_32x32x16_bf16 v[2:17], v[86:89], v[94:97], v[2:17]
	ds_read_b128 v[82:85], v131 offset:34816
	ds_read_b128 v[86:89], v131 offset:38912
	ds_read_b128 v[90:93], v135 offset:34816
	ds_read_b128 v[94:97], v135 offset:38912
	v_mfma_f32_32x32x16_bf16 v[50:65], v[98:101], v[106:109], v[50:65]
	v_mfma_f32_32x32x16_bf16 v[34:49], v[98:101], v[110:113], v[34:49]
	v_mfma_f32_32x32x16_bf16 v[18:33], v[102:105], v[106:109], v[18:33]
	v_mfma_f32_32x32x16_bf16 v[2:17], v[102:105], v[110:113], v[2:17]
	ds_read_b128 v[98:101], v132 offset:34816
	ds_read_b128 v[102:105], v132 offset:38912
	ds_read_b128 v[106:109], v136 offset:34816
	ds_read_b128 v[110:113], v136 offset:38912
	v_mfma_f32_32x32x16_bf16 v[50:65], v[114:117], v[122:125], v[50:65]
	v_mfma_f32_32x32x16_bf16 v[34:49], v[114:117], v[126:129], v[34:49]
	v_mfma_f32_32x32x16_bf16 v[18:33], v[118:121], v[122:125], v[18:33]
	v_mfma_f32_32x32x16_bf16 v[2:17], v[118:121], v[126:129], v[2:17]
	ds_read_b128 v[114:117], v133 offset:34816
	ds_read_b128 v[118:121], v133 offset:38912
	ds_read_b128 v[122:125], v137 offset:34816
	ds_read_b128 v[126:129], v137 offset:38912
	s_waitcnt lgkmcnt(0)
	s_barrier
	v_mfma_f32_32x32x16_bf16 v[50:65], v[66:69], v[74:77], v[50:65]
	s_add_u32 m0, s14, 0x8580
	s_nop 0
	global_load_lds_dwordx4 v[148:149], off offset:640
	s_add_u32 m0, s14, 0x9580
	s_nop 0
	global_load_lds_dwordx4 v[152:153], off offset:640
	v_mfma_f32_32x32x16_bf16 v[34:49], v[66:69], v[78:81], v[34:49]
	s_add_u32 m0, s14, 0xa580
	s_nop 0
	global_load_lds_dwordx4 v[156:157], off offset:640
	s_add_u32 m0, s14, 0xb580
	s_nop 0
	global_load_lds_dwordx4 v[160:161], off offset:640
	v_mfma_f32_32x32x16_bf16 v[18:33], v[70:73], v[74:77], v[18:33]
	s_add_u32 m0, s14, 0xc580
	s_nop 0
	global_load_lds_dwordx4 v[150:151], off offset:640
	s_add_u32 m0, s14, 0xd580
	s_nop 0
	global_load_lds_dwordx4 v[154:155], off offset:640
	v_mfma_f32_32x32x16_bf16 v[2:17], v[70:73], v[78:81], v[2:17]
	s_add_u32 m0, s14, 0xe580
	s_nop 0
	global_load_lds_dwordx4 v[158:159], off offset:640
	s_add_u32 m0, s14, 0xf580
	s_nop 0
	global_load_lds_dwordx4 v[162:163], off offset:640
	s_waitcnt vmcnt(8)
	s_barrier
	ds_read_b128 v[66:69], v130 offset:2048
	ds_read_b128 v[70:73], v130 offset:6144
	ds_read_b128 v[74:77], v134 offset:2048
	ds_read_b128 v[78:81], v134 offset:6144
	v_mfma_f32_32x32x16_bf16 v[50:65], v[82:85], v[90:93], v[50:65]
	v_mfma_f32_32x32x16_bf16 v[34:49], v[82:85], v[94:97], v[34:49]
	v_mfma_f32_32x32x16_bf16 v[18:33], v[86:89], v[90:93], v[18:33]
	v_mfma_f32_32x32x16_bf16 v[2:17], v[86:89], v[94:97], v[2:17]
	ds_read_b128 v[82:85], v131 offset:2048
	ds_read_b128 v[86:89], v131 offset:6144
	ds_read_b128 v[90:93], v135 offset:2048
	ds_read_b128 v[94:97], v135 offset:6144
	v_mfma_f32_32x32x16_bf16 v[50:65], v[98:101], v[106:109], v[50:65]
	v_mfma_f32_32x32x16_bf16 v[34:49], v[98:101], v[110:113], v[34:49]
	v_mfma_f32_32x32x16_bf16 v[18:33], v[102:105], v[106:109], v[18:33]
	v_mfma_f32_32x32x16_bf16 v[2:17], v[102:105], v[110:113], v[2:17]
	ds_read_b128 v[98:101], v132 offset:2048
	ds_read_b128 v[102:105], v132 offset:6144
	ds_read_b128 v[106:109], v136 offset:2048
	ds_read_b128 v[110:113], v136 offset:6144
	v_mfma_f32_32x32x16_bf16 v[50:65], v[114:117], v[122:125], v[50:65]
	v_mfma_f32_32x32x16_bf16 v[34:49], v[114:117], v[126:129], v[34:49]
	v_mfma_f32_32x32x16_bf16 v[18:33], v[118:121], v[122:125], v[18:33]
	v_mfma_f32_32x32x16_bf16 v[2:17], v[118:121], v[126:129], v[2:17]
	ds_read_b128 v[114:117], v133 offset:2048
	ds_read_b128 v[118:121], v133 offset:6144
	ds_read_b128 v[122:125], v137 offset:2048
	ds_read_b128 v[126:129], v137 offset:6144
	s_waitcnt lgkmcnt(0)
	s_barrier
	v_mfma_f32_32x32x16_bf16 v[50:65], v[66:69], v[74:77], v[50:65]
	s_add_u32 m0, s14, 0x500
	s_nop 0
	global_load_lds_dwordx4 v[148:149], off offset:768
	s_add_u32 m0, s14, 0x1500
	s_nop 0
	global_load_lds_dwordx4 v[152:153], off offset:768
	v_mfma_f32_32x32x16_bf16 v[34:49], v[66:69], v[78:81], v[34:49]
	s_add_u32 m0, s14, 0x2500
	s_nop 0
	global_load_lds_dwordx4 v[156:157], off offset:768
	s_add_u32 m0, s14, 0x3500
	s_nop 0
	global_load_lds_dwordx4 v[160:161], off offset:768
	v_mfma_f32_32x32x16_bf16 v[18:33], v[70:73], v[74:77], v[18:33]
	s_add_u32 m0, s14, 0x4500
	s_nop 0
	global_load_lds_dwordx4 v[150:151], off offset:768
	s_add_u32 m0, s14, 0x5500
	s_nop 0
	global_load_lds_dwordx4 v[154:155], off offset:768
	v_mfma_f32_32x32x16_bf16 v[2:17], v[70:73], v[78:81], v[2:17]
	s_add_u32 m0, s14, 0x6500
	s_nop 0
	global_load_lds_dwordx4 v[158:159], off offset:768
	s_add_u32 m0, s14, 0x7500
	s_nop 0
	global_load_lds_dwordx4 v[162:163], off offset:768
	s_waitcnt vmcnt(8)
	s_barrier
	ds_read_b128 v[66:69], v130 offset:34816
	ds_read_b128 v[70:73], v130 offset:38912
	ds_read_b128 v[74:77], v134 offset:34816
	ds_read_b128 v[78:81], v134 offset:38912
	v_mfma_f32_32x32x16_bf16 v[50:65], v[82:85], v[90:93], v[50:65]
	v_mfma_f32_32x32x16_bf16 v[34:49], v[82:85], v[94:97], v[34:49]
	v_mfma_f32_32x32x16_bf16 v[18:33], v[86:89], v[90:93], v[18:33]
	v_mfma_f32_32x32x16_bf16 v[2:17], v[86:89], v[94:97], v[2:17]
	ds_read_b128 v[82:85], v131 offset:34816
	ds_read_b128 v[86:89], v131 offset:38912
	ds_read_b128 v[90:93], v135 offset:34816
	ds_read_b128 v[94:97], v135 offset:38912
	v_mfma_f32_32x32x16_bf16 v[50:65], v[98:101], v[106:109], v[50:65]
	v_mfma_f32_32x32x16_bf16 v[34:49], v[98:101], v[110:113], v[34:49]
	v_mfma_f32_32x32x16_bf16 v[18:33], v[102:105], v[106:109], v[18:33]
	v_mfma_f32_32x32x16_bf16 v[2:17], v[102:105], v[110:113], v[2:17]
	ds_read_b128 v[98:101], v132 offset:34816
	ds_read_b128 v[102:105], v132 offset:38912
	ds_read_b128 v[106:109], v136 offset:34816
	ds_read_b128 v[110:113], v136 offset:38912
	v_mfma_f32_32x32x16_bf16 v[50:65], v[114:117], v[122:125], v[50:65]
	v_mfma_f32_32x32x16_bf16 v[34:49], v[114:117], v[126:129], v[34:49]
	v_mfma_f32_32x32x16_bf16 v[18:33], v[118:121], v[122:125], v[18:33]
	v_mfma_f32_32x32x16_bf16 v[2:17], v[118:121], v[126:129], v[2:17]
	ds_read_b128 v[114:117], v133 offset:34816
	ds_read_b128 v[118:121], v133 offset:38912
	ds_read_b128 v[122:125], v137 offset:34816
	ds_read_b128 v[126:129], v137 offset:38912
	s_waitcnt lgkmcnt(0)
	s_barrier
	v_mfma_f32_32x32x16_bf16 v[50:65], v[66:69], v[74:77], v[50:65]
	s_add_u32 m0, s14, 0x8480
	s_nop 0
	global_load_lds_dwordx4 v[148:149], off offset:896
	s_add_u32 m0, s14, 0x9480
	s_nop 0
	global_load_lds_dwordx4 v[152:153], off offset:896
	v_mfma_f32_32x32x16_bf16 v[34:49], v[66:69], v[78:81], v[34:49]
	s_add_u32 m0, s14, 0xa480
	s_nop 0
	global_load_lds_dwordx4 v[156:157], off offset:896
	s_add_u32 m0, s14, 0xb480
	s_nop 0
	global_load_lds_dwordx4 v[160:161], off offset:896
	v_mfma_f32_32x32x16_bf16 v[18:33], v[70:73], v[74:77], v[18:33]
	s_add_u32 m0, s14, 0xc480
	s_nop 0
	global_load_lds_dwordx4 v[150:151], off offset:896
	s_add_u32 m0, s14, 0xd480
	s_nop 0
	global_load_lds_dwordx4 v[154:155], off offset:896
	v_mfma_f32_32x32x16_bf16 v[2:17], v[70:73], v[78:81], v[2:17]
	s_add_u32 m0, s14, 0xe480
	s_nop 0
	global_load_lds_dwordx4 v[158:159], off offset:896
	s_add_u32 m0, s14, 0xf480
	s_nop 0
	global_load_lds_dwordx4 v[162:163], off offset:896
	s_waitcnt vmcnt(8)
	s_barrier
	ds_read_b128 v[66:69], v130 offset:2048
	ds_read_b128 v[70:73], v130 offset:6144
	ds_read_b128 v[74:77], v134 offset:2048
	ds_read_b128 v[78:81], v134 offset:6144
	v_mfma_f32_32x32x16_bf16 v[50:65], v[82:85], v[90:93], v[50:65]
	v_mfma_f32_32x32x16_bf16 v[34:49], v[82:85], v[94:97], v[34:49]
	v_mfma_f32_32x32x16_bf16 v[18:33], v[86:89], v[90:93], v[18:33]
	v_mfma_f32_32x32x16_bf16 v[2:17], v[86:89], v[94:97], v[2:17]
	ds_read_b128 v[82:85], v131 offset:2048
	ds_read_b128 v[86:89], v131 offset:6144
	ds_read_b128 v[90:93], v135 offset:2048
	ds_read_b128 v[94:97], v135 offset:6144
	v_mfma_f32_32x32x16_bf16 v[50:65], v[98:101], v[106:109], v[50:65]
	v_mfma_f32_32x32x16_bf16 v[34:49], v[98:101], v[110:113], v[34:49]
	v_mfma_f32_32x32x16_bf16 v[18:33], v[102:105], v[106:109], v[18:33]
	v_mfma_f32_32x32x16_bf16 v[2:17], v[102:105], v[110:113], v[2:17]
	ds_read_b128 v[98:101], v132 offset:2048
	ds_read_b128 v[102:105], v132 offset:6144
	ds_read_b128 v[106:109], v136 offset:2048
	ds_read_b128 v[110:113], v136 offset:6144
	v_mfma_f32_32x32x16_bf16 v[50:65], v[114:117], v[122:125], v[50:65]
	v_mfma_f32_32x32x16_bf16 v[34:49], v[114:117], v[126:129], v[34:49]
	v_mfma_f32_32x32x16_bf16 v[18:33], v[118:121], v[122:125], v[18:33]
	v_mfma_f32_32x32x16_bf16 v[2:17], v[118:121], v[126:129], v[2:17]
	ds_read_b128 v[114:117], v133 offset:2048
	ds_read_b128 v[118:121], v133 offset:6144
	ds_read_b128 v[122:125], v137 offset:2048
	ds_read_b128 v[126:129], v137 offset:6144
	s_waitcnt lgkmcnt(0)
	s_barrier
	v_mfma_f32_32x32x16_bf16 v[50:65], v[66:69], v[74:77], v[50:65]
	s_add_u32 m0, s14, 0x400
	s_nop 0
	global_load_lds_dwordx4 v[148:149], off offset:1024
	s_add_u32 m0, s14, 0x1400
	s_nop 0
	global_load_lds_dwordx4 v[152:153], off offset:1024
	v_mfma_f32_32x32x16_bf16 v[34:49], v[66:69], v[78:81], v[34:49]
	s_add_u32 m0, s14, 0x2400
	s_nop 0
	global_load_lds_dwordx4 v[156:157], off offset:1024
	s_add_u32 m0, s14, 0x3400
	s_nop 0
	global_load_lds_dwordx4 v[160:161], off offset:1024
	v_mfma_f32_32x32x16_bf16 v[18:33], v[70:73], v[74:77], v[18:33]
	s_add_u32 m0, s14, 0x4400
	s_nop 0
	global_load_lds_dwordx4 v[150:151], off offset:1024
	s_add_u32 m0, s14, 0x5400
	s_nop 0
	global_load_lds_dwordx4 v[154:155], off offset:1024
	v_mfma_f32_32x32x16_bf16 v[2:17], v[70:73], v[78:81], v[2:17]
	s_add_u32 m0, s14, 0x6400
	s_nop 0
	global_load_lds_dwordx4 v[158:159], off offset:1024
	s_add_u32 m0, s14, 0x7400
	s_nop 0
	global_load_lds_dwordx4 v[162:163], off offset:1024
	s_waitcnt vmcnt(8)
	s_barrier
	ds_read_b128 v[66:69], v130 offset:34816
	ds_read_b128 v[70:73], v130 offset:38912
	ds_read_b128 v[74:77], v134 offset:34816
	ds_read_b128 v[78:81], v134 offset:38912
	v_mfma_f32_32x32x16_bf16 v[50:65], v[82:85], v[90:93], v[50:65]
	v_mfma_f32_32x32x16_bf16 v[34:49], v[82:85], v[94:97], v[34:49]
	v_mfma_f32_32x32x16_bf16 v[18:33], v[86:89], v[90:93], v[18:33]
	v_mfma_f32_32x32x16_bf16 v[2:17], v[86:89], v[94:97], v[2:17]
	ds_read_b128 v[82:85], v131 offset:34816
	ds_read_b128 v[86:89], v131 offset:38912
	ds_read_b128 v[90:93], v135 offset:34816
	ds_read_b128 v[94:97], v135 offset:38912
	v_mfma_f32_32x32x16_bf16 v[50:65], v[98:101], v[106:109], v[50:65]
	v_mfma_f32_32x32x16_bf16 v[34:49], v[98:101], v[110:113], v[34:49]
	v_mfma_f32_32x32x16_bf16 v[18:33], v[102:105], v[106:109], v[18:33]
	v_mfma_f32_32x32x16_bf16 v[2:17], v[102:105], v[110:113], v[2:17]
	ds_read_b128 v[98:101], v132 offset:34816
	ds_read_b128 v[102:105], v132 offset:38912
	ds_read_b128 v[106:109], v136 offset:34816
	ds_read_b128 v[110:113], v136 offset:38912
	v_mfma_f32_32x32x16_bf16 v[50:65], v[114:117], v[122:125], v[50:65]
	v_mfma_f32_32x32x16_bf16 v[34:49], v[114:117], v[126:129], v[34:49]
	v_mfma_f32_32x32x16_bf16 v[18:33], v[118:121], v[122:125], v[18:33]
	v_mfma_f32_32x32x16_bf16 v[2:17], v[118:121], v[126:129], v[2:17]
	ds_read_b128 v[114:117], v133 offset:34816
	ds_read_b128 v[118:121], v133 offset:38912
	ds_read_b128 v[122:125], v137 offset:34816
	ds_read_b128 v[126:129], v137 offset:38912
	s_waitcnt lgkmcnt(0)
	s_barrier
	v_mfma_f32_32x32x16_bf16 v[50:65], v[66:69], v[74:77], v[50:65]
	s_add_u32 m0, s14, 0x8380
	s_nop 0
	global_load_lds_dwordx4 v[148:149], off offset:1152
	s_add_u32 m0, s14, 0x9380
	s_nop 0
	global_load_lds_dwordx4 v[152:153], off offset:1152
	v_mfma_f32_32x32x16_bf16 v[34:49], v[66:69], v[78:81], v[34:49]
	s_add_u32 m0, s14, 0xa380
	s_nop 0
	global_load_lds_dwordx4 v[156:157], off offset:1152
	s_add_u32 m0, s14, 0xb380
	s_nop 0
	global_load_lds_dwordx4 v[160:161], off offset:1152
	v_mfma_f32_32x32x16_bf16 v[18:33], v[70:73], v[74:77], v[18:33]
	s_add_u32 m0, s14, 0xc380
	s_nop 0
	global_load_lds_dwordx4 v[150:151], off offset:1152
	s_add_u32 m0, s14, 0xd380
	s_nop 0
	global_load_lds_dwordx4 v[154:155], off offset:1152
	v_mfma_f32_32x32x16_bf16 v[2:17], v[70:73], v[78:81], v[2:17]
	s_add_u32 m0, s14, 0xe380
	s_nop 0
	global_load_lds_dwordx4 v[158:159], off offset:1152
	s_add_u32 m0, s14, 0xf380
	s_nop 0
	global_load_lds_dwordx4 v[162:163], off offset:1152
	s_waitcnt vmcnt(8)
	s_barrier
	ds_read_b128 v[66:69], v130 offset:2048
	ds_read_b128 v[70:73], v130 offset:6144
	ds_read_b128 v[74:77], v134 offset:2048
	ds_read_b128 v[78:81], v134 offset:6144
	v_mfma_f32_32x32x16_bf16 v[50:65], v[82:85], v[90:93], v[50:65]
	v_mfma_f32_32x32x16_bf16 v[34:49], v[82:85], v[94:97], v[34:49]
	v_mfma_f32_32x32x16_bf16 v[18:33], v[86:89], v[90:93], v[18:33]
	v_mfma_f32_32x32x16_bf16 v[2:17], v[86:89], v[94:97], v[2:17]
	ds_read_b128 v[82:85], v131 offset:2048
	ds_read_b128 v[86:89], v131 offset:6144
	ds_read_b128 v[90:93], v135 offset:2048
	ds_read_b128 v[94:97], v135 offset:6144
	v_mfma_f32_32x32x16_bf16 v[50:65], v[98:101], v[106:109], v[50:65]
	v_mfma_f32_32x32x16_bf16 v[34:49], v[98:101], v[110:113], v[34:49]
	v_mfma_f32_32x32x16_bf16 v[18:33], v[102:105], v[106:109], v[18:33]
	v_mfma_f32_32x32x16_bf16 v[2:17], v[102:105], v[110:113], v[2:17]
	ds_read_b128 v[98:101], v132 offset:2048
	ds_read_b128 v[102:105], v132 offset:6144
	ds_read_b128 v[106:109], v136 offset:2048
	ds_read_b128 v[110:113], v136 offset:6144
	v_mfma_f32_32x32x16_bf16 v[50:65], v[114:117], v[122:125], v[50:65]
	v_mfma_f32_32x32x16_bf16 v[34:49], v[114:117], v[126:129], v[34:49]
	v_mfma_f32_32x32x16_bf16 v[18:33], v[118:121], v[122:125], v[18:33]
	v_mfma_f32_32x32x16_bf16 v[2:17], v[118:121], v[126:129], v[2:17]
	ds_read_b128 v[114:117], v133 offset:2048
	ds_read_b128 v[118:121], v133 offset:6144
	ds_read_b128 v[122:125], v137 offset:2048
	ds_read_b128 v[126:129], v137 offset:6144
	s_waitcnt lgkmcnt(0)
	s_barrier
	v_mfma_f32_32x32x16_bf16 v[50:65], v[66:69], v[74:77], v[50:65]
	s_add_u32 m0, s14, 0x300
	s_nop 0
	global_load_lds_dwordx4 v[148:149], off offset:1280
	s_add_u32 m0, s14, 0x1300
	s_nop 0
	global_load_lds_dwordx4 v[152:153], off offset:1280
	v_mfma_f32_32x32x16_bf16 v[34:49], v[66:69], v[78:81], v[34:49]
	s_add_u32 m0, s14, 0x2300
	s_nop 0
	global_load_lds_dwordx4 v[156:157], off offset:1280
	s_add_u32 m0, s14, 0x3300
	s_nop 0
	global_load_lds_dwordx4 v[160:161], off offset:1280
	v_mfma_f32_32x32x16_bf16 v[18:33], v[70:73], v[74:77], v[18:33]
	s_add_u32 m0, s14, 0x4300
	s_nop 0
	global_load_lds_dwordx4 v[150:151], off offset:1280
	s_add_u32 m0, s14, 0x5300
	s_nop 0
	global_load_lds_dwordx4 v[154:155], off offset:1280
	v_mfma_f32_32x32x16_bf16 v[2:17], v[70:73], v[78:81], v[2:17]
	s_add_u32 m0, s14, 0x6300
	s_nop 0
	global_load_lds_dwordx4 v[158:159], off offset:1280
	s_add_u32 m0, s14, 0x7300
	s_nop 0
	global_load_lds_dwordx4 v[162:163], off offset:1280
	s_waitcnt vmcnt(8)
	s_barrier
	ds_read_b128 v[66:69], v130 offset:34816
	ds_read_b128 v[70:73], v130 offset:38912
	ds_read_b128 v[74:77], v134 offset:34816
	ds_read_b128 v[78:81], v134 offset:38912
	v_mfma_f32_32x32x16_bf16 v[50:65], v[82:85], v[90:93], v[50:65]
	v_mfma_f32_32x32x16_bf16 v[34:49], v[82:85], v[94:97], v[34:49]
	v_mfma_f32_32x32x16_bf16 v[18:33], v[86:89], v[90:93], v[18:33]
	v_mfma_f32_32x32x16_bf16 v[2:17], v[86:89], v[94:97], v[2:17]
	ds_read_b128 v[82:85], v131 offset:34816
	ds_read_b128 v[86:89], v131 offset:38912
	ds_read_b128 v[90:93], v135 offset:34816
	ds_read_b128 v[94:97], v135 offset:38912
	v_mfma_f32_32x32x16_bf16 v[50:65], v[98:101], v[106:109], v[50:65]
	v_mfma_f32_32x32x16_bf16 v[34:49], v[98:101], v[110:113], v[34:49]
	v_mfma_f32_32x32x16_bf16 v[18:33], v[102:105], v[106:109], v[18:33]
	v_mfma_f32_32x32x16_bf16 v[2:17], v[102:105], v[110:113], v[2:17]
	ds_read_b128 v[98:101], v132 offset:34816
	ds_read_b128 v[102:105], v132 offset:38912
	ds_read_b128 v[106:109], v136 offset:34816
	ds_read_b128 v[110:113], v136 offset:38912
	v_mfma_f32_32x32x16_bf16 v[50:65], v[114:117], v[122:125], v[50:65]
	v_mfma_f32_32x32x16_bf16 v[34:49], v[114:117], v[126:129], v[34:49]
	v_mfma_f32_32x32x16_bf16 v[18:33], v[118:121], v[122:125], v[18:33]
	v_mfma_f32_32x32x16_bf16 v[2:17], v[118:121], v[126:129], v[2:17]
	ds_read_b128 v[114:117], v133 offset:34816
	ds_read_b128 v[118:121], v133 offset:38912
	ds_read_b128 v[122:125], v137 offset:34816
	ds_read_b128 v[126:129], v137 offset:38912
	s_waitcnt lgkmcnt(0)
	s_barrier
	v_mfma_f32_32x32x16_bf16 v[50:65], v[66:69], v[74:77], v[50:65]
	s_add_u32 m0, s14, 0x8280
	s_nop 0
	global_load_lds_dwordx4 v[148:149], off offset:1408
	s_add_u32 m0, s14, 0x9280
	s_nop 0
	global_load_lds_dwordx4 v[152:153], off offset:1408
	v_mfma_f32_32x32x16_bf16 v[34:49], v[66:69], v[78:81], v[34:49]
	s_add_u32 m0, s14, 0xa280
	s_nop 0
	global_load_lds_dwordx4 v[156:157], off offset:1408
	s_add_u32 m0, s14, 0xb280
	s_nop 0
	global_load_lds_dwordx4 v[160:161], off offset:1408
	v_mfma_f32_32x32x16_bf16 v[18:33], v[70:73], v[74:77], v[18:33]
	s_add_u32 m0, s14, 0xc280
	s_nop 0
	global_load_lds_dwordx4 v[150:151], off offset:1408
	s_add_u32 m0, s14, 0xd280
	s_nop 0
	global_load_lds_dwordx4 v[154:155], off offset:1408
	v_mfma_f32_32x32x16_bf16 v[2:17], v[70:73], v[78:81], v[2:17]
	s_add_u32 m0, s14, 0xe280
	s_nop 0
	global_load_lds_dwordx4 v[158:159], off offset:1408
	s_add_u32 m0, s14, 0xf280
	s_nop 0
	global_load_lds_dwordx4 v[162:163], off offset:1408
	s_waitcnt vmcnt(8)
	s_barrier
	ds_read_b128 v[66:69], v130 offset:2048
	ds_read_b128 v[70:73], v130 offset:6144
	ds_read_b128 v[74:77], v134 offset:2048
	ds_read_b128 v[78:81], v134 offset:6144
	v_mfma_f32_32x32x16_bf16 v[50:65], v[82:85], v[90:93], v[50:65]
	v_mfma_f32_32x32x16_bf16 v[34:49], v[82:85], v[94:97], v[34:49]
	v_mfma_f32_32x32x16_bf16 v[18:33], v[86:89], v[90:93], v[18:33]
	v_mfma_f32_32x32x16_bf16 v[2:17], v[86:89], v[94:97], v[2:17]
	ds_read_b128 v[82:85], v131 offset:2048
	ds_read_b128 v[86:89], v131 offset:6144
	ds_read_b128 v[90:93], v135 offset:2048
	ds_read_b128 v[94:97], v135 offset:6144
	v_mfma_f32_32x32x16_bf16 v[50:65], v[98:101], v[106:109], v[50:65]
	v_mfma_f32_32x32x16_bf16 v[34:49], v[98:101], v[110:113], v[34:49]
	v_mfma_f32_32x32x16_bf16 v[18:33], v[102:105], v[106:109], v[18:33]
	v_mfma_f32_32x32x16_bf16 v[2:17], v[102:105], v[110:113], v[2:17]
	ds_read_b128 v[98:101], v132 offset:2048
	ds_read_b128 v[102:105], v132 offset:6144
	ds_read_b128 v[106:109], v136 offset:2048
	ds_read_b128 v[110:113], v136 offset:6144
	v_mfma_f32_32x32x16_bf16 v[50:65], v[114:117], v[122:125], v[50:65]
	v_mfma_f32_32x32x16_bf16 v[34:49], v[114:117], v[126:129], v[34:49]
	v_mfma_f32_32x32x16_bf16 v[18:33], v[118:121], v[122:125], v[18:33]
	v_mfma_f32_32x32x16_bf16 v[2:17], v[118:121], v[126:129], v[2:17]
	ds_read_b128 v[114:117], v133 offset:2048
	ds_read_b128 v[118:121], v133 offset:6144
	ds_read_b128 v[122:125], v137 offset:2048
	ds_read_b128 v[126:129], v137 offset:6144
	s_waitcnt lgkmcnt(0)
	s_barrier
	v_mfma_f32_32x32x16_bf16 v[50:65], v[66:69], v[74:77], v[50:65]
	s_add_u32 m0, s14, 0x200
	s_nop 0
	global_load_lds_dwordx4 v[148:149], off offset:1536
	s_add_u32 m0, s14, 0x1200
	s_nop 0
	global_load_lds_dwordx4 v[152:153], off offset:1536
	v_mfma_f32_32x32x16_bf16 v[34:49], v[66:69], v[78:81], v[34:49]
	s_add_u32 m0, s14, 0x2200
	s_nop 0
	global_load_lds_dwordx4 v[156:157], off offset:1536
	s_add_u32 m0, s14, 0x3200
	s_nop 0
	global_load_lds_dwordx4 v[160:161], off offset:1536
	v_mfma_f32_32x32x16_bf16 v[18:33], v[70:73], v[74:77], v[18:33]
	s_add_u32 m0, s14, 0x4200
	s_nop 0
	global_load_lds_dwordx4 v[150:151], off offset:1536
	s_add_u32 m0, s14, 0x5200
	s_nop 0
	global_load_lds_dwordx4 v[154:155], off offset:1536
	v_mfma_f32_32x32x16_bf16 v[2:17], v[70:73], v[78:81], v[2:17]
	s_add_u32 m0, s14, 0x6200
	s_nop 0
	global_load_lds_dwordx4 v[158:159], off offset:1536
	s_add_u32 m0, s14, 0x7200
	s_nop 0
	global_load_lds_dwordx4 v[162:163], off offset:1536
	s_waitcnt vmcnt(8)
	s_barrier
	ds_read_b128 v[66:69], v130 offset:34816
	ds_read_b128 v[70:73], v130 offset:38912
	ds_read_b128 v[74:77], v134 offset:34816
	ds_read_b128 v[78:81], v134 offset:38912
	v_mfma_f32_32x32x16_bf16 v[50:65], v[82:85], v[90:93], v[50:65]
	v_mfma_f32_32x32x16_bf16 v[34:49], v[82:85], v[94:97], v[34:49]
	v_mfma_f32_32x32x16_bf16 v[18:33], v[86:89], v[90:93], v[18:33]
	v_mfma_f32_32x32x16_bf16 v[2:17], v[86:89], v[94:97], v[2:17]
	ds_read_b128 v[82:85], v131 offset:34816
	ds_read_b128 v[86:89], v131 offset:38912
	ds_read_b128 v[90:93], v135 offset:34816
	ds_read_b128 v[94:97], v135 offset:38912
	v_mfma_f32_32x32x16_bf16 v[50:65], v[98:101], v[106:109], v[50:65]
	v_mfma_f32_32x32x16_bf16 v[34:49], v[98:101], v[110:113], v[34:49]
	v_mfma_f32_32x32x16_bf16 v[18:33], v[102:105], v[106:109], v[18:33]
	v_mfma_f32_32x32x16_bf16 v[2:17], v[102:105], v[110:113], v[2:17]
	ds_read_b128 v[98:101], v132 offset:34816
	ds_read_b128 v[102:105], v132 offset:38912
	ds_read_b128 v[106:109], v136 offset:34816
	ds_read_b128 v[110:113], v136 offset:38912
	v_mfma_f32_32x32x16_bf16 v[50:65], v[114:117], v[122:125], v[50:65]
	v_mfma_f32_32x32x16_bf16 v[34:49], v[114:117], v[126:129], v[34:49]
	v_mfma_f32_32x32x16_bf16 v[18:33], v[118:121], v[122:125], v[18:33]
	v_mfma_f32_32x32x16_bf16 v[2:17], v[118:121], v[126:129], v[2:17]
	ds_read_b128 v[114:117], v133 offset:34816
	ds_read_b128 v[118:121], v133 offset:38912
	ds_read_b128 v[122:125], v137 offset:34816
	ds_read_b128 v[126:129], v137 offset:38912
	s_waitcnt lgkmcnt(0)
	s_barrier
	v_mfma_f32_32x32x16_bf16 v[50:65], v[66:69], v[74:77], v[50:65]
	s_add_u32 m0, s14, 0x8180
	s_nop 0
	global_load_lds_dwordx4 v[148:149], off offset:1664
	s_add_u32 m0, s14, 0x9180
	s_nop 0
	global_load_lds_dwordx4 v[152:153], off offset:1664
	v_mfma_f32_32x32x16_bf16 v[34:49], v[66:69], v[78:81], v[34:49]
	s_add_u32 m0, s14, 0xa180
	s_nop 0
	global_load_lds_dwordx4 v[156:157], off offset:1664
	s_add_u32 m0, s14, 0xb180
	s_nop 0
	global_load_lds_dwordx4 v[160:161], off offset:1664
	v_mfma_f32_32x32x16_bf16 v[18:33], v[70:73], v[74:77], v[18:33]
	s_add_u32 m0, s14, 0xc180
	s_nop 0
	global_load_lds_dwordx4 v[150:151], off offset:1664
	s_add_u32 m0, s14, 0xd180
	s_nop 0
	global_load_lds_dwordx4 v[154:155], off offset:1664
	v_mfma_f32_32x32x16_bf16 v[2:17], v[70:73], v[78:81], v[2:17]
	s_add_u32 m0, s14, 0xe180
	s_nop 0
	global_load_lds_dwordx4 v[158:159], off offset:1664
	s_add_u32 m0, s14, 0xf180
	s_nop 0
	global_load_lds_dwordx4 v[162:163], off offset:1664
	s_waitcnt vmcnt(8)
	s_barrier
	ds_read_b128 v[66:69], v130 offset:2048
	ds_read_b128 v[70:73], v130 offset:6144
	ds_read_b128 v[74:77], v134 offset:2048
	ds_read_b128 v[78:81], v134 offset:6144
	v_mfma_f32_32x32x16_bf16 v[50:65], v[82:85], v[90:93], v[50:65]
	v_mfma_f32_32x32x16_bf16 v[34:49], v[82:85], v[94:97], v[34:49]
	v_mfma_f32_32x32x16_bf16 v[18:33], v[86:89], v[90:93], v[18:33]
	v_mfma_f32_32x32x16_bf16 v[2:17], v[86:89], v[94:97], v[2:17]
	ds_read_b128 v[82:85], v131 offset:2048
	ds_read_b128 v[86:89], v131 offset:6144
	ds_read_b128 v[90:93], v135 offset:2048
	ds_read_b128 v[94:97], v135 offset:6144
	v_mfma_f32_32x32x16_bf16 v[50:65], v[98:101], v[106:109], v[50:65]
	v_mfma_f32_32x32x16_bf16 v[34:49], v[98:101], v[110:113], v[34:49]
	v_mfma_f32_32x32x16_bf16 v[18:33], v[102:105], v[106:109], v[18:33]
	v_mfma_f32_32x32x16_bf16 v[2:17], v[102:105], v[110:113], v[2:17]
	ds_read_b128 v[98:101], v132 offset:2048
	ds_read_b128 v[102:105], v132 offset:6144
	ds_read_b128 v[106:109], v136 offset:2048
	ds_read_b128 v[110:113], v136 offset:6144
	v_mfma_f32_32x32x16_bf16 v[50:65], v[114:117], v[122:125], v[50:65]
	v_mfma_f32_32x32x16_bf16 v[34:49], v[114:117], v[126:129], v[34:49]
	v_mfma_f32_32x32x16_bf16 v[18:33], v[118:121], v[122:125], v[18:33]
	v_mfma_f32_32x32x16_bf16 v[2:17], v[118:121], v[126:129], v[2:17]
	ds_read_b128 v[114:117], v133 offset:2048
	ds_read_b128 v[118:121], v133 offset:6144
	ds_read_b128 v[122:125], v137 offset:2048
	ds_read_b128 v[126:129], v137 offset:6144
	s_waitcnt lgkmcnt(0)
	s_barrier
	v_mfma_f32_32x32x16_bf16 v[50:65], v[66:69], v[74:77], v[50:65]
	s_add_u32 m0, s14, 0x100
	s_nop 0
	global_load_lds_dwordx4 v[148:149], off offset:1792
	s_add_u32 m0, s14, 0x1100
	s_nop 0
	global_load_lds_dwordx4 v[152:153], off offset:1792
	v_mfma_f32_32x32x16_bf16 v[34:49], v[66:69], v[78:81], v[34:49]
	s_add_u32 m0, s14, 0x2100
	s_nop 0
	global_load_lds_dwordx4 v[156:157], off offset:1792
	s_add_u32 m0, s14, 0x3100
	s_nop 0
	global_load_lds_dwordx4 v[160:161], off offset:1792
	v_mfma_f32_32x32x16_bf16 v[18:33], v[70:73], v[74:77], v[18:33]
	s_add_u32 m0, s14, 0x4100
	s_nop 0
	global_load_lds_dwordx4 v[150:151], off offset:1792
	s_add_u32 m0, s14, 0x5100
	s_nop 0
	global_load_lds_dwordx4 v[154:155], off offset:1792
	v_mfma_f32_32x32x16_bf16 v[2:17], v[70:73], v[78:81], v[2:17]
	s_add_u32 m0, s14, 0x6100
	s_nop 0
	global_load_lds_dwordx4 v[158:159], off offset:1792
	s_add_u32 m0, s14, 0x7100
	s_nop 0
	global_load_lds_dwordx4 v[162:163], off offset:1792
	s_waitcnt vmcnt(8)
	s_barrier
	ds_read_b128 v[66:69], v130 offset:34816
	ds_read_b128 v[70:73], v130 offset:38912
	ds_read_b128 v[74:77], v134 offset:34816
	ds_read_b128 v[78:81], v134 offset:38912
	v_mfma_f32_32x32x16_bf16 v[50:65], v[82:85], v[90:93], v[50:65]
	v_mfma_f32_32x32x16_bf16 v[34:49], v[82:85], v[94:97], v[34:49]
	v_mfma_f32_32x32x16_bf16 v[18:33], v[86:89], v[90:93], v[18:33]
	v_mfma_f32_32x32x16_bf16 v[2:17], v[86:89], v[94:97], v[2:17]
	ds_read_b128 v[82:85], v131 offset:34816
	ds_read_b128 v[86:89], v131 offset:38912
	ds_read_b128 v[90:93], v135 offset:34816
	ds_read_b128 v[94:97], v135 offset:38912
	v_mfma_f32_32x32x16_bf16 v[50:65], v[98:101], v[106:109], v[50:65]
	v_mfma_f32_32x32x16_bf16 v[34:49], v[98:101], v[110:113], v[34:49]
	v_mfma_f32_32x32x16_bf16 v[18:33], v[102:105], v[106:109], v[18:33]
	v_mfma_f32_32x32x16_bf16 v[2:17], v[102:105], v[110:113], v[2:17]
	ds_read_b128 v[98:101], v132 offset:34816
	ds_read_b128 v[102:105], v132 offset:38912
	ds_read_b128 v[106:109], v136 offset:34816
	ds_read_b128 v[110:113], v136 offset:38912
	v_mfma_f32_32x32x16_bf16 v[50:65], v[114:117], v[122:125], v[50:65]
	v_mfma_f32_32x32x16_bf16 v[34:49], v[114:117], v[126:129], v[34:49]
	v_mfma_f32_32x32x16_bf16 v[18:33], v[118:121], v[122:125], v[18:33]
	v_mfma_f32_32x32x16_bf16 v[2:17], v[118:121], v[126:129], v[2:17]
	ds_read_b128 v[114:117], v133 offset:34816
	ds_read_b128 v[118:121], v133 offset:38912
	ds_read_b128 v[122:125], v137 offset:34816
	ds_read_b128 v[126:129], v137 offset:38912
	s_waitcnt lgkmcnt(0)
	s_barrier
	v_mfma_f32_32x32x16_bf16 v[50:65], v[66:69], v[74:77], v[50:65]
	s_add_u32 m0, s14, 0x8080
	s_nop 0
	global_load_lds_dwordx4 v[148:149], off offset:1920
	s_add_u32 m0, s14, 0x9080
	s_nop 0
	global_load_lds_dwordx4 v[152:153], off offset:1920
	v_mfma_f32_32x32x16_bf16 v[34:49], v[66:69], v[78:81], v[34:49]
	s_add_u32 m0, s14, 0xa080
	s_nop 0
	global_load_lds_dwordx4 v[156:157], off offset:1920
	s_add_u32 m0, s14, 0xb080
	s_nop 0
	global_load_lds_dwordx4 v[160:161], off offset:1920
	v_mfma_f32_32x32x16_bf16 v[18:33], v[70:73], v[74:77], v[18:33]
	s_add_u32 m0, s14, 0xc080
	s_nop 0
	global_load_lds_dwordx4 v[150:151], off offset:1920
	s_add_u32 m0, s14, 0xd080
	s_nop 0
	global_load_lds_dwordx4 v[154:155], off offset:1920
	v_mfma_f32_32x32x16_bf16 v[2:17], v[70:73], v[78:81], v[2:17]
	s_add_u32 m0, s14, 0xe080
	s_nop 0
	global_load_lds_dwordx4 v[158:159], off offset:1920
	s_add_u32 m0, s14, 0xf080
	s_nop 0
	global_load_lds_dwordx4 v[162:163], off offset:1920
	s_waitcnt vmcnt(8)
	s_barrier
	ds_read_b128 v[66:69], v130 offset:2048
	ds_read_b128 v[70:73], v130 offset:6144
	ds_read_b128 v[74:77], v134 offset:2048
	ds_read_b128 v[78:81], v134 offset:6144
	v_mfma_f32_32x32x16_bf16 v[50:65], v[82:85], v[90:93], v[50:65]
	v_mfma_f32_32x32x16_bf16 v[34:49], v[82:85], v[94:97], v[34:49]
	v_mfma_f32_32x32x16_bf16 v[18:33], v[86:89], v[90:93], v[18:33]
	v_mfma_f32_32x32x16_bf16 v[2:17], v[86:89], v[94:97], v[2:17]
	ds_read_b128 v[82:85], v131 offset:2048
	ds_read_b128 v[86:89], v131 offset:6144
	ds_read_b128 v[90:93], v135 offset:2048
	ds_read_b128 v[94:97], v135 offset:6144
	v_mfma_f32_32x32x16_bf16 v[50:65], v[98:101], v[106:109], v[50:65]
	v_mfma_f32_32x32x16_bf16 v[34:49], v[98:101], v[110:113], v[34:49]
	v_mfma_f32_32x32x16_bf16 v[18:33], v[102:105], v[106:109], v[18:33]
	v_mfma_f32_32x32x16_bf16 v[2:17], v[102:105], v[110:113], v[2:17]
	ds_read_b128 v[98:101], v132 offset:2048
	ds_read_b128 v[102:105], v132 offset:6144
	ds_read_b128 v[106:109], v136 offset:2048
	ds_read_b128 v[110:113], v136 offset:6144
	v_mfma_f32_32x32x16_bf16 v[50:65], v[114:117], v[122:125], v[50:65]
	v_mfma_f32_32x32x16_bf16 v[34:49], v[114:117], v[126:129], v[34:49]
	v_mfma_f32_32x32x16_bf16 v[18:33], v[118:121], v[122:125], v[18:33]
	v_mfma_f32_32x32x16_bf16 v[2:17], v[118:121], v[126:129], v[2:17]
	ds_read_b128 v[114:117], v133 offset:2048
	ds_read_b128 v[118:121], v133 offset:6144
	ds_read_b128 v[122:125], v137 offset:2048
	ds_read_b128 v[126:129], v137 offset:6144
	s_waitcnt lgkmcnt(0)
	v_mfma_f32_32x32x16_bf16 v[50:65], v[66:69], v[74:77], v[50:65]
	v_mfma_f32_32x32x16_bf16 v[34:49], v[66:69], v[78:81], v[34:49]
	v_mfma_f32_32x32x16_bf16 v[18:33], v[70:73], v[74:77], v[18:33]
	v_mfma_f32_32x32x16_bf16 v[2:17], v[70:73], v[78:81], v[2:17]
	s_waitcnt vmcnt(0)
	s_barrier
	ds_read_b128 v[66:69], v130 offset:34816
	ds_read_b128 v[70:73], v130 offset:38912
	ds_read_b128 v[74:77], v134 offset:34816
	ds_read_b128 v[78:81], v134 offset:38912
	v_mfma_f32_32x32x16_bf16 v[50:65], v[82:85], v[90:93], v[50:65]
	v_mfma_f32_32x32x16_bf16 v[34:49], v[82:85], v[94:97], v[34:49]
	v_mfma_f32_32x32x16_bf16 v[18:33], v[86:89], v[90:93], v[18:33]
	v_mfma_f32_32x32x16_bf16 v[2:17], v[86:89], v[94:97], v[2:17]
	ds_read_b128 v[82:85], v131 offset:34816
	ds_read_b128 v[86:89], v131 offset:38912
	ds_read_b128 v[90:93], v135 offset:34816
	ds_read_b128 v[94:97], v135 offset:38912
	v_mfma_f32_32x32x16_bf16 v[50:65], v[98:101], v[106:109], v[50:65]
	v_mfma_f32_32x32x16_bf16 v[34:49], v[98:101], v[110:113], v[34:49]
	v_mfma_f32_32x32x16_bf16 v[18:33], v[102:105], v[106:109], v[18:33]
	v_mfma_f32_32x32x16_bf16 v[2:17], v[102:105], v[110:113], v[2:17]
	ds_read_b128 v[98:101], v132 offset:34816
	ds_read_b128 v[102:105], v132 offset:38912
	ds_read_b128 v[106:109], v136 offset:34816
	ds_read_b128 v[110:113], v136 offset:38912
	v_mfma_f32_32x32x16_bf16 v[50:65], v[114:117], v[122:125], v[50:65]
	v_mfma_f32_32x32x16_bf16 v[34:49], v[114:117], v[126:129], v[34:49]
	v_mfma_f32_32x32x16_bf16 v[18:33], v[118:121], v[122:125], v[18:33]
	v_mfma_f32_32x32x16_bf16 v[2:17], v[118:121], v[126:129], v[2:17]
	ds_read_b128 v[114:117], v133 offset:34816
	ds_read_b128 v[118:121], v133 offset:38912
	ds_read_b128 v[122:125], v137 offset:34816
	ds_read_b128 v[126:129], v137 offset:38912
	s_waitcnt lgkmcnt(0)
	v_mfma_f32_32x32x16_bf16 v[50:65], v[66:69], v[74:77], v[50:65]
	v_mfma_f32_32x32x16_bf16 v[34:49], v[66:69], v[78:81], v[34:49]
	v_mfma_f32_32x32x16_bf16 v[18:33], v[70:73], v[74:77], v[18:33]
	v_mfma_f32_32x32x16_bf16 v[2:17], v[70:73], v[78:81], v[2:17]
	v_mfma_f32_32x32x16_bf16 v[50:65], v[82:85], v[90:93], v[50:65]
	v_mfma_f32_32x32x16_bf16 v[34:49], v[82:85], v[94:97], v[34:49]
	v_mfma_f32_32x32x16_bf16 v[18:33], v[86:89], v[90:93], v[18:33]
	v_mfma_f32_32x32x16_bf16 v[2:17], v[86:89], v[94:97], v[2:17]
	v_mfma_f32_32x32x16_bf16 v[50:65], v[98:101], v[106:109], v[50:65]
	v_mfma_f32_32x32x16_bf16 v[34:49], v[98:101], v[110:113], v[34:49]
	v_mfma_f32_32x32x16_bf16 v[18:33], v[102:105], v[106:109], v[18:33]
	v_mfma_f32_32x32x16_bf16 v[2:17], v[102:105], v[110:113], v[2:17]
	v_mfma_f32_32x32x16_bf16 v[50:65], v[114:117], v[122:125], v[50:65]
	v_mfma_f32_32x32x16_bf16 v[34:49], v[114:117], v[126:129], v[34:49]
	v_mfma_f32_32x32x16_bf16 v[18:33], v[118:121], v[122:125], v[18:33]
	v_mfma_f32_32x32x16_bf16 v[2:17], v[118:121], v[126:129], v[2:17]
	s_setprio 0
	s_cmp_eq_u32 s45, 1
	s_waitcnt lgkmcnt(0)
	s_barrier
	s_nop 0
	s_nop 0
	s_nop 10
	v_mul_f32_e32 v0, 0xbfb8aa3b, v50
	v_exp_f32_e32 v0, v0
	s_nop 0
	v_add_f32_e32 v0, 1.0, v0
	v_div_scale_f32 v50, s[0:1], v0, v0, 1.0
	v_rcp_f32_e32 v66, v50
	s_nop 0
	v_fma_f32 v67, -v50, v66, 1.0
	v_fmac_f32_e32 v66, v67, v66
	v_div_scale_f32 v67, vcc, 1.0, v0, 1.0
	v_mul_f32_e32 v68, v67, v66
	v_fma_f32 v69, -v50, v68, v67
	v_fmac_f32_e32 v68, v69, v66
	v_fma_f32 v50, -v50, v68, v67
	v_div_fmas_f32 v50, v50, v66, v68
	v_div_fixup_f32 v0, v50, v0, 1.0
	v_fma_f32 v0, v0, s80, 0.5
	v_cvt_u32_f32_e32 v116, v0
	v_mul_f32_e32 v0, 0xbfb8aa3b, v51
	v_exp_f32_e32 v0, v0
	s_nop 0
	v_add_f32_e32 v0, 1.0, v0
	v_div_scale_f32 v50, s[0:1], v0, v0, 1.0
	v_rcp_f32_e32 v51, v50
	s_nop 0
	v_fma_f32 v66, -v50, v51, 1.0
	v_fmac_f32_e32 v51, v66, v51
	v_div_scale_f32 v66, vcc, 1.0, v0, 1.0
	v_mul_f32_e32 v67, v66, v51
	v_fma_f32 v68, -v50, v67, v66
	v_fmac_f32_e32 v67, v68, v51
	v_fma_f32 v50, -v50, v67, v66
	v_div_fmas_f32 v50, v50, v51, v67
	v_div_fixup_f32 v0, v50, v0, 1.0
	v_mul_f32_e32 v50, 0xbfb8aa3b, v52
	v_exp_f32_e32 v50, v50
	v_fma_f32 v0, v0, s80, 0.5
	v_cvt_u32_f32_e32 v0, v0
	v_add_f32_e32 v50, 1.0, v50
	v_div_scale_f32 v51, s[0:1], v50, v50, 1.0
	v_rcp_f32_e32 v52, v51
	v_lshl_or_b32 v118, v0, 8, v116
	v_mul_f32_e32 v0, 0xbfb8aa3b, v54
	v_exp_f32_e32 v0, v0
	v_fma_f32 v66, -v51, v52, 1.0
	v_fmac_f32_e32 v52, v66, v52
	v_div_scale_f32 v66, vcc, 1.0, v50, 1.0
	v_mul_f32_e32 v67, v66, v52
	v_fma_f32 v68, -v51, v67, v66
	v_fmac_f32_e32 v67, v68, v52
	v_fma_f32 v51, -v51, v67, v66
	v_div_fmas_f32 v51, v51, v52, v67
	v_div_fixup_f32 v50, v51, v50, 1.0
	v_mul_f32_e32 v51, 0xbfb8aa3b, v53
	v_exp_f32_e32 v51, v51
	v_fma_f32 v50, v50, s80, 0.5
	v_cvt_u32_f32_sdwa v50, v50 dst_sel:WORD_1 dst_unused:UNUSED_PAD src0_sel:DWORD
	v_add_f32_e32 v0, 1.0, v0
	v_add_f32_e32 v51, 1.0, v51
	v_div_scale_f32 v52, s[0:1], v51, v51, 1.0
	v_rcp_f32_e32 v53, v52
	s_nop 0
	v_fma_f32 v66, -v52, v53, 1.0
	v_fmac_f32_e32 v53, v66, v53
	v_div_scale_f32 v66, vcc, 1.0, v51, 1.0
	v_mul_f32_e32 v67, v66, v53
	v_fma_f32 v68, -v52, v67, v66
	v_fmac_f32_e32 v67, v68, v53
	v_fma_f32 v52, -v52, v67, v66
	v_div_fmas_f32 v52, v52, v53, v67
	v_div_fixup_f32 v51, v52, v51, 1.0
	v_fma_f32 v51, v51, s80, 0.5
	v_cvt_u32_f32_sdwa v51, v51 dst_sel:BYTE_3 dst_unused:UNUSED_PAD src0_sel:DWORD
	s_nop 0
	v_or3_b32 v117, v50, v51, v118
	v_div_scale_f32 v50, s[0:1], v0, v0, 1.0
	v_rcp_f32_e32 v51, v50
	s_nop 0
	v_fma_f32 v52, -v50, v51, 1.0
	v_fmac_f32_e32 v51, v52, v51
	v_div_scale_f32 v52, vcc, 1.0, v0, 1.0
	v_mul_f32_e32 v53, v52, v51
	v_fma_f32 v54, -v50, v53, v52
	v_fmac_f32_e32 v53, v54, v51
	v_fma_f32 v50, -v50, v53, v52
	v_div_fmas_f32 v50, v50, v51, v53
	v_div_fixup_f32 v0, v50, v0, 1.0
	v_fma_f32 v0, v0, s80, 0.5
	v_cvt_u32_f32_e32 v119, v0
	v_mul_f32_e32 v0, 0xbfb8aa3b, v55
	v_exp_f32_e32 v0, v0
	s_nop 0
	v_add_f32_e32 v0, 1.0, v0
	v_div_scale_f32 v50, s[0:1], v0, v0, 1.0
	v_rcp_f32_e32 v51, v50
	s_nop 0
	v_fma_f32 v52, -v50, v51, 1.0
	v_fmac_f32_e32 v51, v52, v51
	v_div_scale_f32 v52, vcc, 1.0, v0, 1.0
	v_mul_f32_e32 v53, v52, v51
	v_fma_f32 v54, -v50, v53, v52
	v_fmac_f32_e32 v53, v54, v51
	v_fma_f32 v50, -v50, v53, v52
	v_div_fmas_f32 v50, v50, v51, v53
	v_div_fixup_f32 v0, v50, v0, 1.0
	v_mul_f32_e32 v50, 0xbfb8aa3b, v56
	v_exp_f32_e32 v50, v50
	v_fma_f32 v0, v0, s80, 0.5
	v_cvt_u32_f32_e32 v0, v0
	v_add_f32_e32 v50, 1.0, v50
	v_div_scale_f32 v51, s[0:1], v50, v50, 1.0
	v_rcp_f32_e32 v52, v51
	v_lshl_or_b32 v121, v0, 8, v119
	v_mul_f32_e32 v0, 0xbfb8aa3b, v58
	v_exp_f32_e32 v0, v0
	v_fma_f32 v53, -v51, v52, 1.0
	v_fmac_f32_e32 v52, v53, v52
	v_div_scale_f32 v53, vcc, 1.0, v50, 1.0
	v_mul_f32_e32 v54, v53, v52
	v_fma_f32 v55, -v51, v54, v53
	v_fmac_f32_e32 v54, v55, v52
	v_fma_f32 v51, -v51, v54, v53
	v_div_fmas_f32 v51, v51, v52, v54
	v_div_fixup_f32 v50, v51, v50, 1.0
	v_mul_f32_e32 v51, 0xbfb8aa3b, v57
	v_exp_f32_e32 v51, v51
	v_fma_f32 v50, v50, s80, 0.5
	v_cvt_u32_f32_sdwa v50, v50 dst_sel:WORD_1 dst_unused:UNUSED_PAD src0_sel:DWORD
	v_add_f32_e32 v0, 1.0, v0
	v_add_f32_e32 v51, 1.0, v51
	v_div_scale_f32 v52, s[0:1], v51, v51, 1.0
	v_rcp_f32_e32 v53, v52
	s_nop 0
	v_fma_f32 v54, -v52, v53, 1.0
	v_fmac_f32_e32 v53, v54, v53
	v_div_scale_f32 v54, vcc, 1.0, v51, 1.0
	v_mul_f32_e32 v55, v54, v53
	v_fma_f32 v56, -v52, v55, v54
	v_fmac_f32_e32 v55, v56, v53
	v_fma_f32 v52, -v52, v55, v54
	v_div_fmas_f32 v52, v52, v53, v55
	v_div_fixup_f32 v51, v52, v51, 1.0
	v_fma_f32 v51, v51, s80, 0.5
	v_cvt_u32_f32_sdwa v51, v51 dst_sel:BYTE_3 dst_unused:UNUSED_PAD src0_sel:DWORD
	s_nop 0
	v_or3_b32 v120, v50, v51, v121
	v_div_scale_f32 v50, s[0:1], v0, v0, 1.0
	v_rcp_f32_e32 v51, v50
	s_nop 0
	v_fma_f32 v52, -v50, v51, 1.0
	v_fmac_f32_e32 v51, v52, v51
	v_div_scale_f32 v52, vcc, 1.0, v0, 1.0
	v_mul_f32_e32 v53, v52, v51
	v_fma_f32 v54, -v50, v53, v52
	v_fmac_f32_e32 v53, v54, v51
	v_fma_f32 v50, -v50, v53, v52
	v_div_fmas_f32 v50, v50, v51, v53
	v_div_fixup_f32 v0, v50, v0, 1.0
	v_fma_f32 v0, v0, s80, 0.5
	v_cvt_u32_f32_e32 v122, v0
	v_mul_f32_e32 v0, 0xbfb8aa3b, v59
	v_exp_f32_e32 v0, v0
	s_nop 0
	v_add_f32_e32 v0, 1.0, v0
	v_div_scale_f32 v50, s[0:1], v0, v0, 1.0
	v_rcp_f32_e32 v51, v50
	s_nop 0
	v_fma_f32 v52, -v50, v51, 1.0
	v_fmac_f32_e32 v51, v52, v51
	v_div_scale_f32 v52, vcc, 1.0, v0, 1.0
	v_mul_f32_e32 v53, v52, v51
	v_fma_f32 v54, -v50, v53, v52
	v_fmac_f32_e32 v53, v54, v51
	v_fma_f32 v50, -v50, v53, v52
	v_div_fmas_f32 v50, v50, v51, v53
	v_div_fixup_f32 v0, v50, v0, 1.0
	v_mul_f32_e32 v50, 0xbfb8aa3b, v60
	v_exp_f32_e32 v50, v50
	v_fma_f32 v0, v0, s80, 0.5
	v_cvt_u32_f32_e32 v0, v0
	v_add_f32_e32 v50, 1.0, v50
	v_div_scale_f32 v51, s[0:1], v50, v50, 1.0
	v_rcp_f32_e32 v52, v51
	v_lshl_or_b32 v124, v0, 8, v122
	v_mul_f32_e32 v0, 0xbfb8aa3b, v62
	v_exp_f32_e32 v0, v0
	v_fma_f32 v53, -v51, v52, 1.0
	v_fmac_f32_e32 v52, v53, v52
	v_div_scale_f32 v53, vcc, 1.0, v50, 1.0
	v_mul_f32_e32 v54, v53, v52
	v_fma_f32 v55, -v51, v54, v53
	v_fmac_f32_e32 v54, v55, v52
	v_fma_f32 v51, -v51, v54, v53
	v_div_fmas_f32 v51, v51, v52, v54
	v_div_fixup_f32 v50, v51, v50, 1.0
	v_mul_f32_e32 v51, 0xbfb8aa3b, v61
	v_exp_f32_e32 v51, v51
	v_fma_f32 v50, v50, s80, 0.5
	v_cvt_u32_f32_sdwa v50, v50 dst_sel:WORD_1 dst_unused:UNUSED_PAD src0_sel:DWORD
	v_add_f32_e32 v0, 1.0, v0
	v_add_f32_e32 v51, 1.0, v51
	v_div_scale_f32 v52, s[0:1], v51, v51, 1.0
	v_rcp_f32_e32 v53, v52
	s_nop 0
	v_fma_f32 v54, -v52, v53, 1.0
	v_fmac_f32_e32 v53, v54, v53
	v_div_scale_f32 v54, vcc, 1.0, v51, 1.0
	v_mul_f32_e32 v55, v54, v53
	v_fma_f32 v56, -v52, v55, v54
	v_fmac_f32_e32 v55, v56, v53
	v_fma_f32 v52, -v52, v55, v54
	v_div_fmas_f32 v52, v52, v53, v55
	v_div_fixup_f32 v51, v52, v51, 1.0
	v_fma_f32 v51, v51, s80, 0.5
	v_cvt_u32_f32_sdwa v51, v51 dst_sel:BYTE_3 dst_unused:UNUSED_PAD src0_sel:DWORD
	s_nop 0
	v_or3_b32 v123, v50, v51, v124
	v_div_scale_f32 v50, s[0:1], v0, v0, 1.0
	v_rcp_f32_e32 v51, v50
	s_nop 0
	v_fma_f32 v52, -v50, v51, 1.0
	v_fmac_f32_e32 v51, v52, v51
	v_div_scale_f32 v52, vcc, 1.0, v0, 1.0
	v_mul_f32_e32 v53, v52, v51
	v_fma_f32 v54, -v50, v53, v52
	v_fmac_f32_e32 v53, v54, v51
	v_fma_f32 v50, -v50, v53, v52
	v_div_fmas_f32 v50, v50, v51, v53
	v_div_fixup_f32 v0, v50, v0, 1.0
	v_fma_f32 v0, v0, s80, 0.5
	v_cvt_u32_f32_e32 v125, v0
	v_mul_f32_e32 v0, 0xbfb8aa3b, v63
	v_exp_f32_e32 v0, v0
	s_nop 0
	v_add_f32_e32 v0, 1.0, v0
	v_div_scale_f32 v50, s[0:1], v0, v0, 1.0
	v_rcp_f32_e32 v51, v50
	s_nop 0
	v_fma_f32 v52, -v50, v51, 1.0
	v_fmac_f32_e32 v51, v52, v51
	v_div_scale_f32 v52, vcc, 1.0, v0, 1.0
	v_mul_f32_e32 v53, v52, v51
	v_fma_f32 v54, -v50, v53, v52
	v_fmac_f32_e32 v53, v54, v51
	v_fma_f32 v50, -v50, v53, v52
	v_div_fmas_f32 v50, v50, v51, v53
	v_div_fixup_f32 v0, v50, v0, 1.0
	v_mul_f32_e32 v50, 0xbfb8aa3b, v64
	v_exp_f32_e32 v50, v50
	v_fma_f32 v0, v0, s80, 0.5
	v_cvt_u32_f32_e32 v0, v0
	v_add_f32_e32 v50, 1.0, v50
	v_div_scale_f32 v51, s[0:1], v50, v50, 1.0
	v_rcp_f32_e32 v52, v51
	v_lshl_or_b32 v127, v0, 8, v125
	v_mul_f32_e32 v0, 0xbfb8aa3b, v34
	v_exp_f32_e32 v0, v0
	v_fma_f32 v53, -v51, v52, 1.0
	v_fmac_f32_e32 v52, v53, v52
	v_div_scale_f32 v53, vcc, 1.0, v50, 1.0
	v_mul_f32_e32 v54, v53, v52
	v_fma_f32 v55, -v51, v54, v53
	v_fmac_f32_e32 v54, v55, v52
	v_fma_f32 v51, -v51, v54, v53
	v_div_fmas_f32 v51, v51, v52, v54
	v_div_fixup_f32 v50, v51, v50, 1.0
	v_mul_f32_e32 v51, 0xbfb8aa3b, v65
	v_exp_f32_e32 v51, v51
	v_fma_f32 v50, v50, s80, 0.5
	v_cvt_u32_f32_sdwa v50, v50 dst_sel:WORD_1 dst_unused:UNUSED_PAD src0_sel:DWORD
	v_add_f32_e32 v0, 1.0, v0
	v_add_f32_e32 v51, 1.0, v51
	v_div_scale_f32 v52, s[0:1], v51, v51, 1.0
	v_rcp_f32_e32 v53, v52
	v_div_scale_f32 v34, s[0:1], v0, v0, 1.0
	v_fma_f32 v54, -v52, v53, 1.0
	v_fmac_f32_e32 v53, v54, v53
	v_div_scale_f32 v54, vcc, 1.0, v51, 1.0
	v_mul_f32_e32 v55, v54, v53
	v_fma_f32 v56, -v52, v55, v54
	v_fmac_f32_e32 v55, v56, v53
	v_fma_f32 v52, -v52, v55, v54
	v_div_fmas_f32 v52, v52, v53, v55
	v_div_fixup_f32 v51, v52, v51, 1.0
	v_fma_f32 v51, v51, s80, 0.5
	v_cvt_u32_f32_sdwa v51, v51 dst_sel:BYTE_3 dst_unused:UNUSED_PAD src0_sel:DWORD
	s_nop 0
	v_or3_b32 v126, v50, v51, v127
	v_rcp_f32_e32 v50, v34
	s_nop 0
	v_fma_f32 v51, -v34, v50, 1.0
	v_fmac_f32_e32 v50, v51, v50
	v_div_scale_f32 v51, vcc, 1.0, v0, 1.0
	v_mul_f32_e32 v52, v51, v50
	v_fma_f32 v53, -v34, v52, v51
	v_fmac_f32_e32 v52, v53, v50
	v_fma_f32 v34, -v34, v52, v51
	v_div_fmas_f32 v34, v34, v50, v52
	v_div_fixup_f32 v0, v34, v0, 1.0
	v_fma_f32 v0, v0, s80, 0.5
	v_cvt_u32_f32_e32 v128, v0
	v_mul_f32_e32 v0, 0xbfb8aa3b, v35
	v_exp_f32_e32 v0, v0
	s_nop 0
	v_add_f32_e32 v0, 1.0, v0
	v_div_scale_f32 v34, s[0:1], v0, v0, 1.0
	v_rcp_f32_e32 v35, v34
	s_nop 0
	v_fma_f32 v50, -v34, v35, 1.0
	v_fmac_f32_e32 v35, v50, v35
	v_div_scale_f32 v50, vcc, 1.0, v0, 1.0
	v_mul_f32_e32 v51, v50, v35
	v_fma_f32 v52, -v34, v51, v50
	v_fmac_f32_e32 v51, v52, v35
	v_fma_f32 v34, -v34, v51, v50
	v_div_fmas_f32 v34, v34, v35, v51
	v_div_fixup_f32 v0, v34, v0, 1.0
	v_mul_f32_e32 v34, 0xbfb8aa3b, v36
	v_exp_f32_e32 v34, v34
	v_fma_f32 v0, v0, s80, 0.5
	v_cvt_u32_f32_e32 v0, v0
	v_add_f32_e32 v34, 1.0, v34
	v_div_scale_f32 v35, s[0:1], v34, v34, 1.0
	v_rcp_f32_e32 v36, v35
	v_lshl_or_b32 v130, v0, 8, v128
	v_mul_f32_e32 v0, 0xbfb8aa3b, v38
	v_exp_f32_e32 v0, v0
	v_fma_f32 v50, -v35, v36, 1.0
	v_fmac_f32_e32 v36, v50, v36
	v_div_scale_f32 v50, vcc, 1.0, v34, 1.0
	v_mul_f32_e32 v51, v50, v36
	v_fma_f32 v52, -v35, v51, v50
	v_fmac_f32_e32 v51, v52, v36
	v_fma_f32 v35, -v35, v51, v50
	v_div_fmas_f32 v35, v35, v36, v51
	v_div_fixup_f32 v34, v35, v34, 1.0
	v_mul_f32_e32 v35, 0xbfb8aa3b, v37
	v_exp_f32_e32 v35, v35
	v_fma_f32 v34, v34, s80, 0.5
	v_cvt_u32_f32_sdwa v34, v34 dst_sel:WORD_1 dst_unused:UNUSED_PAD src0_sel:DWORD
	v_add_f32_e32 v0, 1.0, v0
	v_add_f32_e32 v35, 1.0, v35
	v_div_scale_f32 v36, s[0:1], v35, v35, 1.0
	v_rcp_f32_e32 v37, v36
	s_nop 0
	v_fma_f32 v50, -v36, v37, 1.0
	v_fmac_f32_e32 v37, v50, v37
	v_div_scale_f32 v50, vcc, 1.0, v35, 1.0
	v_mul_f32_e32 v51, v50, v37
	v_fma_f32 v52, -v36, v51, v50
	v_fmac_f32_e32 v51, v52, v37
	v_fma_f32 v36, -v36, v51, v50
	v_div_fmas_f32 v36, v36, v37, v51
	v_div_fixup_f32 v35, v36, v35, 1.0
	v_fma_f32 v35, v35, s80, 0.5
	v_cvt_u32_f32_sdwa v35, v35 dst_sel:BYTE_3 dst_unused:UNUSED_PAD src0_sel:DWORD
	s_nop 0
	v_or3_b32 v129, v34, v35, v130
	v_div_scale_f32 v34, s[0:1], v0, v0, 1.0
	v_rcp_f32_e32 v35, v34
	s_nop 0
	v_fma_f32 v36, -v34, v35, 1.0
	v_fmac_f32_e32 v35, v36, v35
	v_div_scale_f32 v36, vcc, 1.0, v0, 1.0
	v_mul_f32_e32 v37, v36, v35
	v_fma_f32 v38, -v34, v37, v36
	v_fmac_f32_e32 v37, v38, v35
	v_fma_f32 v34, -v34, v37, v36
	v_div_fmas_f32 v34, v34, v35, v37
	v_div_fixup_f32 v0, v34, v0, 1.0
	v_fma_f32 v0, v0, s80, 0.5
	v_cvt_u32_f32_e32 v131, v0
	v_mul_f32_e32 v0, 0xbfb8aa3b, v39
	v_exp_f32_e32 v0, v0
	s_nop 0
	v_add_f32_e32 v0, 1.0, v0
	v_div_scale_f32 v34, s[0:1], v0, v0, 1.0
	v_rcp_f32_e32 v35, v34
	s_nop 0
	v_fma_f32 v36, -v34, v35, 1.0
	v_fmac_f32_e32 v35, v36, v35
	v_div_scale_f32 v36, vcc, 1.0, v0, 1.0
	v_mul_f32_e32 v37, v36, v35
	v_fma_f32 v38, -v34, v37, v36
	v_fmac_f32_e32 v37, v38, v35
	v_fma_f32 v34, -v34, v37, v36
	v_div_fmas_f32 v34, v34, v35, v37
	v_div_fixup_f32 v0, v34, v0, 1.0
	v_mul_f32_e32 v34, 0xbfb8aa3b, v40
	v_exp_f32_e32 v34, v34
	v_fma_f32 v0, v0, s80, 0.5
	v_cvt_u32_f32_e32 v0, v0
	v_add_f32_e32 v34, 1.0, v34
	v_div_scale_f32 v35, s[0:1], v34, v34, 1.0
	v_rcp_f32_e32 v36, v35
	v_lshl_or_b32 v133, v0, 8, v131
	v_mul_f32_e32 v0, 0xbfb8aa3b, v42
	v_exp_f32_e32 v0, v0
	v_fma_f32 v37, -v35, v36, 1.0
	v_fmac_f32_e32 v36, v37, v36
	v_div_scale_f32 v37, vcc, 1.0, v34, 1.0
	v_mul_f32_e32 v38, v37, v36
	v_fma_f32 v39, -v35, v38, v37
	v_fmac_f32_e32 v38, v39, v36
	v_fma_f32 v35, -v35, v38, v37
	v_div_fmas_f32 v35, v35, v36, v38
	v_div_fixup_f32 v34, v35, v34, 1.0
	v_mul_f32_e32 v35, 0xbfb8aa3b, v41
	v_exp_f32_e32 v35, v35
	v_fma_f32 v34, v34, s80, 0.5
	v_cvt_u32_f32_sdwa v34, v34 dst_sel:WORD_1 dst_unused:UNUSED_PAD src0_sel:DWORD
	v_add_f32_e32 v0, 1.0, v0
	v_add_f32_e32 v35, 1.0, v35
	v_div_scale_f32 v36, s[0:1], v35, v35, 1.0
	v_rcp_f32_e32 v37, v36
	s_nop 0
	v_fma_f32 v38, -v36, v37, 1.0
	v_fmac_f32_e32 v37, v38, v37
	v_div_scale_f32 v38, vcc, 1.0, v35, 1.0
	v_mul_f32_e32 v39, v38, v37
	v_fma_f32 v40, -v36, v39, v38
	v_fmac_f32_e32 v39, v40, v37
	v_fma_f32 v36, -v36, v39, v38
	v_div_fmas_f32 v36, v36, v37, v39
	v_div_fixup_f32 v35, v36, v35, 1.0
	v_fma_f32 v35, v35, s80, 0.5
	v_cvt_u32_f32_sdwa v35, v35 dst_sel:BYTE_3 dst_unused:UNUSED_PAD src0_sel:DWORD
	s_nop 0
	v_or3_b32 v132, v34, v35, v133
	v_div_scale_f32 v34, s[0:1], v0, v0, 1.0
	v_rcp_f32_e32 v35, v34
	s_nop 0
	v_fma_f32 v36, -v34, v35, 1.0
	v_fmac_f32_e32 v35, v36, v35
	v_div_scale_f32 v36, vcc, 1.0, v0, 1.0
	v_mul_f32_e32 v37, v36, v35
	v_fma_f32 v38, -v34, v37, v36
	v_fmac_f32_e32 v37, v38, v35
	v_fma_f32 v34, -v34, v37, v36
	v_div_fmas_f32 v34, v34, v35, v37
	v_div_fixup_f32 v0, v34, v0, 1.0
	v_fma_f32 v0, v0, s80, 0.5
	v_cvt_u32_f32_e32 v134, v0
	v_mul_f32_e32 v0, 0xbfb8aa3b, v43
	v_exp_f32_e32 v0, v0
	s_nop 0
	v_add_f32_e32 v0, 1.0, v0
	v_div_scale_f32 v34, s[0:1], v0, v0, 1.0
	v_rcp_f32_e32 v35, v34
	s_nop 0
	v_fma_f32 v36, -v34, v35, 1.0
	v_fmac_f32_e32 v35, v36, v35
	v_div_scale_f32 v36, vcc, 1.0, v0, 1.0
	v_mul_f32_e32 v37, v36, v35
	v_fma_f32 v38, -v34, v37, v36
	v_fmac_f32_e32 v37, v38, v35
	v_fma_f32 v34, -v34, v37, v36
	v_div_fmas_f32 v34, v34, v35, v37
	v_div_fixup_f32 v0, v34, v0, 1.0
	v_mul_f32_e32 v34, 0xbfb8aa3b, v44
	v_exp_f32_e32 v34, v34
	v_fma_f32 v0, v0, s80, 0.5
	v_cvt_u32_f32_e32 v0, v0
	v_add_f32_e32 v34, 1.0, v34
	v_div_scale_f32 v35, s[0:1], v34, v34, 1.0
	v_rcp_f32_e32 v36, v35
	v_lshl_or_b32 v136, v0, 8, v134
	v_mul_f32_e32 v0, 0xbfb8aa3b, v46
	v_exp_f32_e32 v0, v0
	v_fma_f32 v37, -v35, v36, 1.0
	v_fmac_f32_e32 v36, v37, v36
	v_div_scale_f32 v37, vcc, 1.0, v34, 1.0
	v_mul_f32_e32 v38, v37, v36
	v_fma_f32 v39, -v35, v38, v37
	v_fmac_f32_e32 v38, v39, v36
	v_fma_f32 v35, -v35, v38, v37
	v_div_fmas_f32 v35, v35, v36, v38
	v_div_fixup_f32 v34, v35, v34, 1.0
	v_mul_f32_e32 v35, 0xbfb8aa3b, v45
	v_exp_f32_e32 v35, v35
	v_fma_f32 v34, v34, s80, 0.5
	v_cvt_u32_f32_sdwa v34, v34 dst_sel:WORD_1 dst_unused:UNUSED_PAD src0_sel:DWORD
	v_add_f32_e32 v0, 1.0, v0
	v_add_f32_e32 v35, 1.0, v35
	v_div_scale_f32 v36, s[0:1], v35, v35, 1.0
	v_rcp_f32_e32 v37, v36
	s_nop 0
	v_fma_f32 v38, -v36, v37, 1.0
	v_fmac_f32_e32 v37, v38, v37
	v_div_scale_f32 v38, vcc, 1.0, v35, 1.0
	v_mul_f32_e32 v39, v38, v37
	v_fma_f32 v40, -v36, v39, v38
	v_fmac_f32_e32 v39, v40, v37
	v_fma_f32 v36, -v36, v39, v38
	v_div_fmas_f32 v36, v36, v37, v39
	v_div_fixup_f32 v35, v36, v35, 1.0
	v_fma_f32 v35, v35, s80, 0.5
	v_cvt_u32_f32_sdwa v35, v35 dst_sel:BYTE_3 dst_unused:UNUSED_PAD src0_sel:DWORD
	s_nop 0
	v_or3_b32 v135, v34, v35, v136
	v_div_scale_f32 v34, s[0:1], v0, v0, 1.0
	v_rcp_f32_e32 v35, v34
	s_nop 0
	v_fma_f32 v36, -v34, v35, 1.0
	v_fmac_f32_e32 v35, v36, v35
	v_div_scale_f32 v36, vcc, 1.0, v0, 1.0
	v_mul_f32_e32 v37, v36, v35
	v_fma_f32 v38, -v34, v37, v36
	v_fmac_f32_e32 v37, v38, v35
	v_fma_f32 v34, -v34, v37, v36
	v_div_fmas_f32 v34, v34, v35, v37
	v_div_fixup_f32 v0, v34, v0, 1.0
	v_fma_f32 v0, v0, s80, 0.5
	v_cvt_u32_f32_e32 v137, v0
	v_mul_f32_e32 v0, 0xbfb8aa3b, v47
	v_exp_f32_e32 v0, v0
	s_nop 0
	v_add_f32_e32 v0, 1.0, v0
	v_div_scale_f32 v34, s[0:1], v0, v0, 1.0
	v_rcp_f32_e32 v35, v34
	s_nop 0
	v_fma_f32 v36, -v34, v35, 1.0
	v_fmac_f32_e32 v35, v36, v35
	v_div_scale_f32 v36, vcc, 1.0, v0, 1.0
	v_mul_f32_e32 v37, v36, v35
	v_fma_f32 v38, -v34, v37, v36
	v_fmac_f32_e32 v37, v38, v35
	v_fma_f32 v34, -v34, v37, v36
	v_div_fmas_f32 v34, v34, v35, v37
	v_div_fixup_f32 v0, v34, v0, 1.0
	v_mul_f32_e32 v34, 0xbfb8aa3b, v48
	v_exp_f32_e32 v34, v34
	v_fma_f32 v0, v0, s80, 0.5
	v_cvt_u32_f32_e32 v0, v0
	v_add_f32_e32 v34, 1.0, v34
	v_div_scale_f32 v35, s[0:1], v34, v34, 1.0
	v_rcp_f32_e32 v36, v35
	v_lshl_or_b32 v139, v0, 8, v137
	v_mul_f32_e32 v0, 0xbfb8aa3b, v18
	v_exp_f32_e32 v0, v0
	v_fma_f32 v37, -v35, v36, 1.0
	v_fmac_f32_e32 v36, v37, v36
	v_div_scale_f32 v37, vcc, 1.0, v34, 1.0
	v_mul_f32_e32 v38, v37, v36
	v_fma_f32 v39, -v35, v38, v37
	v_fmac_f32_e32 v38, v39, v36
	v_fma_f32 v35, -v35, v38, v37
	v_div_fmas_f32 v35, v35, v36, v38
	v_div_fixup_f32 v34, v35, v34, 1.0
	v_mul_f32_e32 v35, 0xbfb8aa3b, v49
	v_exp_f32_e32 v35, v35
	v_fma_f32 v34, v34, s80, 0.5
	v_cvt_u32_f32_sdwa v34, v34 dst_sel:WORD_1 dst_unused:UNUSED_PAD src0_sel:DWORD
	v_add_f32_e32 v0, 1.0, v0
	v_add_f32_e32 v35, 1.0, v35
	v_div_scale_f32 v36, s[0:1], v35, v35, 1.0
	v_rcp_f32_e32 v37, v36
	v_div_scale_f32 v18, s[0:1], v0, v0, 1.0
	v_fma_f32 v38, -v36, v37, 1.0
	v_fmac_f32_e32 v37, v38, v37
	v_div_scale_f32 v38, vcc, 1.0, v35, 1.0
	v_mul_f32_e32 v39, v38, v37
	v_fma_f32 v40, -v36, v39, v38
	v_fmac_f32_e32 v39, v40, v37
	v_fma_f32 v36, -v36, v39, v38
	v_div_fmas_f32 v36, v36, v37, v39
	v_div_fixup_f32 v35, v36, v35, 1.0
	v_fma_f32 v35, v35, s80, 0.5
	v_cvt_u32_f32_sdwa v35, v35 dst_sel:BYTE_3 dst_unused:UNUSED_PAD src0_sel:DWORD
	s_nop 0
	v_or3_b32 v138, v34, v35, v139
	v_rcp_f32_e32 v34, v18
	s_nop 0
	v_fma_f32 v35, -v18, v34, 1.0
	v_fmac_f32_e32 v34, v35, v34
	v_div_scale_f32 v35, vcc, 1.0, v0, 1.0
	v_mul_f32_e32 v36, v35, v34
	v_fma_f32 v37, -v18, v36, v35
	v_fmac_f32_e32 v36, v37, v34
	v_fma_f32 v18, -v18, v36, v35
	v_div_fmas_f32 v18, v18, v34, v36
	v_div_fixup_f32 v0, v18, v0, 1.0
	v_fma_f32 v0, v0, s80, 0.5
	v_cvt_u32_f32_e32 v140, v0
	v_mul_f32_e32 v0, 0xbfb8aa3b, v19
	v_exp_f32_e32 v0, v0
	s_nop 0
	v_add_f32_e32 v0, 1.0, v0
	v_div_scale_f32 v18, s[0:1], v0, v0, 1.0
	v_rcp_f32_e32 v19, v18
	s_nop 0
	v_fma_f32 v34, -v18, v19, 1.0
	v_fmac_f32_e32 v19, v34, v19
	v_div_scale_f32 v34, vcc, 1.0, v0, 1.0
	v_mul_f32_e32 v35, v34, v19
	v_fma_f32 v36, -v18, v35, v34
	v_fmac_f32_e32 v35, v36, v19
	v_fma_f32 v18, -v18, v35, v34
	v_div_fmas_f32 v18, v18, v19, v35
	v_div_fixup_f32 v0, v18, v0, 1.0
	v_mul_f32_e32 v18, 0xbfb8aa3b, v20
	v_exp_f32_e32 v18, v18
	v_fma_f32 v0, v0, s80, 0.5
	v_cvt_u32_f32_e32 v0, v0
	v_add_f32_e32 v18, 1.0, v18
	v_div_scale_f32 v19, s[0:1], v18, v18, 1.0
	v_rcp_f32_e32 v20, v19
	v_lshl_or_b32 v142, v0, 8, v140
	v_mul_f32_e32 v0, 0xbfb8aa3b, v22
	v_exp_f32_e32 v0, v0
	v_fma_f32 v34, -v19, v20, 1.0
	v_fmac_f32_e32 v20, v34, v20
	v_div_scale_f32 v34, vcc, 1.0, v18, 1.0
	v_mul_f32_e32 v35, v34, v20
	v_fma_f32 v36, -v19, v35, v34
	v_fmac_f32_e32 v35, v36, v20
	v_fma_f32 v19, -v19, v35, v34
	v_div_fmas_f32 v19, v19, v20, v35
	v_div_fixup_f32 v18, v19, v18, 1.0
	v_mul_f32_e32 v19, 0xbfb8aa3b, v21
	v_exp_f32_e32 v19, v19
	v_fma_f32 v18, v18, s80, 0.5
	v_cvt_u32_f32_sdwa v18, v18 dst_sel:WORD_1 dst_unused:UNUSED_PAD src0_sel:DWORD
	v_add_f32_e32 v0, 1.0, v0
	v_add_f32_e32 v19, 1.0, v19
	v_div_scale_f32 v20, s[0:1], v19, v19, 1.0
	v_rcp_f32_e32 v21, v20
	s_nop 0
	v_fma_f32 v34, -v20, v21, 1.0
	v_fmac_f32_e32 v21, v34, v21
	v_div_scale_f32 v34, vcc, 1.0, v19, 1.0
	v_mul_f32_e32 v35, v34, v21
	v_fma_f32 v36, -v20, v35, v34
	v_fmac_f32_e32 v35, v36, v21
	v_fma_f32 v20, -v20, v35, v34
	v_div_fmas_f32 v20, v20, v21, v35
	v_div_fixup_f32 v19, v20, v19, 1.0
	v_fma_f32 v19, v19, s80, 0.5
	v_cvt_u32_f32_sdwa v19, v19 dst_sel:BYTE_3 dst_unused:UNUSED_PAD src0_sel:DWORD
	s_nop 0
	v_or3_b32 v141, v18, v19, v142
	v_div_scale_f32 v18, s[0:1], v0, v0, 1.0
	v_rcp_f32_e32 v19, v18
	s_nop 0
	v_fma_f32 v20, -v18, v19, 1.0
	v_fmac_f32_e32 v19, v20, v19
	v_div_scale_f32 v20, vcc, 1.0, v0, 1.0
	v_mul_f32_e32 v21, v20, v19
	v_fma_f32 v22, -v18, v21, v20
	v_fmac_f32_e32 v21, v22, v19
	v_fma_f32 v18, -v18, v21, v20
	v_div_fmas_f32 v18, v18, v19, v21
	v_div_fixup_f32 v0, v18, v0, 1.0
	v_fma_f32 v0, v0, s80, 0.5
	v_cvt_u32_f32_e32 v143, v0
	v_mul_f32_e32 v0, 0xbfb8aa3b, v23
	v_exp_f32_e32 v0, v0
	s_nop 0
	v_add_f32_e32 v0, 1.0, v0
	v_div_scale_f32 v18, s[0:1], v0, v0, 1.0
	v_rcp_f32_e32 v19, v18
	s_nop 0
	v_fma_f32 v20, -v18, v19, 1.0
	v_fmac_f32_e32 v19, v20, v19
	v_div_scale_f32 v20, vcc, 1.0, v0, 1.0
	v_mul_f32_e32 v21, v20, v19
	v_fma_f32 v22, -v18, v21, v20
	v_fmac_f32_e32 v21, v22, v19
	v_fma_f32 v18, -v18, v21, v20
	v_div_fmas_f32 v18, v18, v19, v21
	v_div_fixup_f32 v0, v18, v0, 1.0
	v_mul_f32_e32 v18, 0xbfb8aa3b, v24
	v_exp_f32_e32 v18, v18
	v_fma_f32 v0, v0, s80, 0.5
	v_cvt_u32_f32_e32 v0, v0
	v_add_f32_e32 v18, 1.0, v18
	v_div_scale_f32 v19, s[0:1], v18, v18, 1.0
	v_rcp_f32_e32 v20, v19
	v_lshl_or_b32 v145, v0, 8, v143
	v_mul_f32_e32 v0, 0xbfb8aa3b, v26
	v_exp_f32_e32 v0, v0
	v_fma_f32 v21, -v19, v20, 1.0
	v_fmac_f32_e32 v20, v21, v20
	v_div_scale_f32 v21, vcc, 1.0, v18, 1.0
	v_mul_f32_e32 v22, v21, v20
	v_fma_f32 v23, -v19, v22, v21
	v_fmac_f32_e32 v22, v23, v20
	v_fma_f32 v19, -v19, v22, v21
	v_div_fmas_f32 v19, v19, v20, v22
	v_div_fixup_f32 v18, v19, v18, 1.0
	v_mul_f32_e32 v19, 0xbfb8aa3b, v25
	v_exp_f32_e32 v19, v19
	v_fma_f32 v18, v18, s80, 0.5
	v_cvt_u32_f32_sdwa v18, v18 dst_sel:WORD_1 dst_unused:UNUSED_PAD src0_sel:DWORD
	v_add_f32_e32 v0, 1.0, v0
	v_add_f32_e32 v19, 1.0, v19
	v_div_scale_f32 v20, s[0:1], v19, v19, 1.0
	v_rcp_f32_e32 v21, v20
	s_nop 0
	v_fma_f32 v22, -v20, v21, 1.0
	v_fmac_f32_e32 v21, v22, v21
	v_div_scale_f32 v22, vcc, 1.0, v19, 1.0
	v_mul_f32_e32 v23, v22, v21
	v_fma_f32 v24, -v20, v23, v22
	v_fmac_f32_e32 v23, v24, v21
	v_fma_f32 v20, -v20, v23, v22
	v_div_fmas_f32 v20, v20, v21, v23
	v_div_fixup_f32 v19, v20, v19, 1.0
	v_fma_f32 v19, v19, s80, 0.5
	v_cvt_u32_f32_sdwa v19, v19 dst_sel:BYTE_3 dst_unused:UNUSED_PAD src0_sel:DWORD
	s_nop 0
	v_or3_b32 v144, v18, v19, v145
	v_div_scale_f32 v18, s[0:1], v0, v0, 1.0
	v_rcp_f32_e32 v19, v18
	s_nop 0
	v_fma_f32 v20, -v18, v19, 1.0
	v_fmac_f32_e32 v19, v20, v19
	v_div_scale_f32 v20, vcc, 1.0, v0, 1.0
	v_mul_f32_e32 v21, v20, v19
	v_fma_f32 v22, -v18, v21, v20
	v_fmac_f32_e32 v21, v22, v19
	v_fma_f32 v18, -v18, v21, v20
	v_div_fmas_f32 v18, v18, v19, v21
	v_div_fixup_f32 v0, v18, v0, 1.0
	v_fma_f32 v0, v0, s80, 0.5
	v_cvt_u32_f32_e32 v146, v0
	v_mul_f32_e32 v0, 0xbfb8aa3b, v27
	v_exp_f32_e32 v0, v0
	s_nop 0
	v_add_f32_e32 v0, 1.0, v0
	v_div_scale_f32 v18, s[0:1], v0, v0, 1.0
	v_rcp_f32_e32 v19, v18
	s_nop 0
	v_fma_f32 v20, -v18, v19, 1.0
	v_fmac_f32_e32 v19, v20, v19
	v_div_scale_f32 v20, vcc, 1.0, v0, 1.0
	v_mul_f32_e32 v21, v20, v19
	v_fma_f32 v22, -v18, v21, v20
	v_fmac_f32_e32 v21, v22, v19
	v_fma_f32 v18, -v18, v21, v20
	v_div_fmas_f32 v18, v18, v19, v21
	v_div_fixup_f32 v0, v18, v0, 1.0
	v_mul_f32_e32 v18, 0xbfb8aa3b, v28
	v_exp_f32_e32 v18, v18
	v_fma_f32 v0, v0, s80, 0.5
	v_cvt_u32_f32_e32 v0, v0
	v_add_f32_e32 v18, 1.0, v18
	v_div_scale_f32 v19, s[0:1], v18, v18, 1.0
	v_rcp_f32_e32 v20, v19
	v_lshl_or_b32 v148, v0, 8, v146
	v_mul_f32_e32 v0, 0xbfb8aa3b, v30
	v_exp_f32_e32 v0, v0
	v_fma_f32 v21, -v19, v20, 1.0
	v_fmac_f32_e32 v20, v21, v20
	v_div_scale_f32 v21, vcc, 1.0, v18, 1.0
	v_mul_f32_e32 v22, v21, v20
	v_fma_f32 v23, -v19, v22, v21
	v_fmac_f32_e32 v22, v23, v20
	v_fma_f32 v19, -v19, v22, v21
	v_div_fmas_f32 v19, v19, v20, v22
	v_div_fixup_f32 v18, v19, v18, 1.0
	v_mul_f32_e32 v19, 0xbfb8aa3b, v29
	v_exp_f32_e32 v19, v19
	v_fma_f32 v18, v18, s80, 0.5
	v_cvt_u32_f32_sdwa v18, v18 dst_sel:WORD_1 dst_unused:UNUSED_PAD src0_sel:DWORD
	v_add_f32_e32 v0, 1.0, v0
	v_add_f32_e32 v19, 1.0, v19
	v_div_scale_f32 v20, s[0:1], v19, v19, 1.0
	v_rcp_f32_e32 v21, v20
	s_nop 0
	v_fma_f32 v22, -v20, v21, 1.0
	v_fmac_f32_e32 v21, v22, v21
	v_div_scale_f32 v22, vcc, 1.0, v19, 1.0
	v_mul_f32_e32 v23, v22, v21
	v_fma_f32 v24, -v20, v23, v22
	v_fmac_f32_e32 v23, v24, v21
	v_fma_f32 v20, -v20, v23, v22
	v_div_fmas_f32 v20, v20, v21, v23
	v_div_fixup_f32 v19, v20, v19, 1.0
	v_fma_f32 v19, v19, s80, 0.5
	v_cvt_u32_f32_sdwa v19, v19 dst_sel:BYTE_3 dst_unused:UNUSED_PAD src0_sel:DWORD
	s_nop 0
	v_or3_b32 v147, v18, v19, v148
	v_div_scale_f32 v18, s[0:1], v0, v0, 1.0
	v_rcp_f32_e32 v19, v18
	s_nop 0
	v_fma_f32 v20, -v18, v19, 1.0
	v_fmac_f32_e32 v19, v20, v19
	v_div_scale_f32 v20, vcc, 1.0, v0, 1.0
	v_mul_f32_e32 v21, v20, v19
	v_fma_f32 v22, -v18, v21, v20
	v_fmac_f32_e32 v21, v22, v19
	v_fma_f32 v18, -v18, v21, v20
	v_div_fmas_f32 v18, v18, v19, v21
	v_div_fixup_f32 v0, v18, v0, 1.0
	v_fma_f32 v0, v0, s80, 0.5
	v_cvt_u32_f32_e32 v149, v0
	v_mul_f32_e32 v0, 0xbfb8aa3b, v31
	v_exp_f32_e32 v0, v0
	s_nop 0
	v_add_f32_e32 v0, 1.0, v0
	v_div_scale_f32 v18, s[0:1], v0, v0, 1.0
	v_rcp_f32_e32 v19, v18
	s_nop 0
	v_fma_f32 v20, -v18, v19, 1.0
	v_fmac_f32_e32 v19, v20, v19
	v_div_scale_f32 v20, vcc, 1.0, v0, 1.0
	v_mul_f32_e32 v21, v20, v19
	v_fma_f32 v22, -v18, v21, v20
	v_fmac_f32_e32 v21, v22, v19
	v_fma_f32 v18, -v18, v21, v20
	v_div_fmas_f32 v18, v18, v19, v21
	v_div_fixup_f32 v0, v18, v0, 1.0
	v_mul_f32_e32 v18, 0xbfb8aa3b, v32
	v_exp_f32_e32 v18, v18
	v_fma_f32 v0, v0, s80, 0.5
	v_cvt_u32_f32_e32 v0, v0
	v_add_f32_e32 v18, 1.0, v18
	v_div_scale_f32 v19, s[0:1], v18, v18, 1.0
	v_rcp_f32_e32 v20, v19
	v_lshl_or_b32 v151, v0, 8, v149
	v_mul_f32_e32 v0, 0xbfb8aa3b, v2
	v_exp_f32_e32 v0, v0
	v_fma_f32 v21, -v19, v20, 1.0
	v_fmac_f32_e32 v20, v21, v20
	v_div_scale_f32 v21, vcc, 1.0, v18, 1.0
	v_mul_f32_e32 v22, v21, v20
	v_fma_f32 v23, -v19, v22, v21
	v_fmac_f32_e32 v22, v23, v20
	v_fma_f32 v19, -v19, v22, v21
	v_div_fmas_f32 v19, v19, v20, v22
	v_div_fixup_f32 v18, v19, v18, 1.0
	v_mul_f32_e32 v19, 0xbfb8aa3b, v33
	v_exp_f32_e32 v19, v19
	v_fma_f32 v18, v18, s80, 0.5
	v_cvt_u32_f32_sdwa v18, v18 dst_sel:WORD_1 dst_unused:UNUSED_PAD src0_sel:DWORD
	v_add_f32_e32 v0, 1.0, v0
	v_add_f32_e32 v19, 1.0, v19
	v_div_scale_f32 v20, s[0:1], v19, v19, 1.0
	v_rcp_f32_e32 v21, v20
	v_div_scale_f32 v2, s[0:1], v0, v0, 1.0
	v_fma_f32 v22, -v20, v21, 1.0
	v_fmac_f32_e32 v21, v22, v21
	v_div_scale_f32 v22, vcc, 1.0, v19, 1.0
	v_mul_f32_e32 v23, v22, v21
	v_fma_f32 v24, -v20, v23, v22
	v_fmac_f32_e32 v23, v24, v21
	v_fma_f32 v20, -v20, v23, v22
	v_div_fmas_f32 v20, v20, v21, v23
	v_div_fixup_f32 v19, v20, v19, 1.0
	v_fma_f32 v19, v19, s80, 0.5
	v_cvt_u32_f32_sdwa v19, v19 dst_sel:BYTE_3 dst_unused:UNUSED_PAD src0_sel:DWORD
	s_nop 0
	v_or3_b32 v150, v18, v19, v151
	v_rcp_f32_e32 v18, v2
	s_nop 0
	v_fma_f32 v19, -v2, v18, 1.0
	v_fmac_f32_e32 v18, v19, v18
	v_div_scale_f32 v19, vcc, 1.0, v0, 1.0
	v_mul_f32_e32 v20, v19, v18
	v_fma_f32 v21, -v2, v20, v19
	v_fmac_f32_e32 v20, v21, v18
	v_fma_f32 v2, -v2, v20, v19
	v_div_fmas_f32 v2, v2, v18, v20
	v_div_fixup_f32 v0, v2, v0, 1.0
	v_fma_f32 v0, v0, s80, 0.5
	v_cvt_u32_f32_e32 v152, v0
	v_mul_f32_e32 v0, 0xbfb8aa3b, v3
	v_exp_f32_e32 v0, v0
	s_nop 0
	v_add_f32_e32 v0, 1.0, v0
	v_div_scale_f32 v2, s[0:1], v0, v0, 1.0
	v_rcp_f32_e32 v3, v2
	s_nop 0
	v_fma_f32 v18, -v2, v3, 1.0
	v_fmac_f32_e32 v3, v18, v3
	v_div_scale_f32 v18, vcc, 1.0, v0, 1.0
	v_mul_f32_e32 v19, v18, v3
	v_fma_f32 v20, -v2, v19, v18
	v_fmac_f32_e32 v19, v20, v3
	v_fma_f32 v2, -v2, v19, v18
	v_div_fmas_f32 v2, v2, v3, v19
	v_div_fixup_f32 v0, v2, v0, 1.0
	v_mul_f32_e32 v2, 0xbfb8aa3b, v4
	v_exp_f32_e32 v2, v2
	v_fma_f32 v0, v0, s80, 0.5
	v_cvt_u32_f32_e32 v0, v0
	v_add_f32_e32 v2, 1.0, v2
	v_div_scale_f32 v3, s[0:1], v2, v2, 1.0
	v_rcp_f32_e32 v4, v3
	v_lshl_or_b32 v154, v0, 8, v152
	v_mul_f32_e32 v0, 0xbfb8aa3b, v6
	v_exp_f32_e32 v0, v0
	v_fma_f32 v18, -v3, v4, 1.0
	v_fmac_f32_e32 v4, v18, v4
	v_div_scale_f32 v18, vcc, 1.0, v2, 1.0
	v_mul_f32_e32 v19, v18, v4
	v_fma_f32 v20, -v3, v19, v18
	v_fmac_f32_e32 v19, v20, v4
	v_fma_f32 v3, -v3, v19, v18
	v_div_fmas_f32 v3, v3, v4, v19
	v_div_fixup_f32 v2, v3, v2, 1.0
	v_mul_f32_e32 v3, 0xbfb8aa3b, v5
	v_exp_f32_e32 v3, v3
	v_fma_f32 v2, v2, s80, 0.5
	v_cvt_u32_f32_sdwa v2, v2 dst_sel:WORD_1 dst_unused:UNUSED_PAD src0_sel:DWORD
	v_add_f32_e32 v0, 1.0, v0
	v_add_f32_e32 v3, 1.0, v3
	v_div_scale_f32 v4, s[0:1], v3, v3, 1.0
	v_rcp_f32_e32 v5, v4
	s_nop 0
	v_fma_f32 v18, -v4, v5, 1.0
	v_fmac_f32_e32 v5, v18, v5
	v_div_scale_f32 v18, vcc, 1.0, v3, 1.0
	v_mul_f32_e32 v19, v18, v5
	v_fma_f32 v20, -v4, v19, v18
	v_fmac_f32_e32 v19, v20, v5
	v_fma_f32 v4, -v4, v19, v18
	v_div_fmas_f32 v4, v4, v5, v19
	v_div_fixup_f32 v3, v4, v3, 1.0
	v_fma_f32 v3, v3, s80, 0.5
	v_cvt_u32_f32_sdwa v3, v3 dst_sel:BYTE_3 dst_unused:UNUSED_PAD src0_sel:DWORD
	s_nop 0
	v_or3_b32 v153, v2, v3, v154
	v_div_scale_f32 v2, s[0:1], v0, v0, 1.0
	v_rcp_f32_e32 v3, v2
	s_nop 0
	v_fma_f32 v4, -v2, v3, 1.0
	v_fmac_f32_e32 v3, v4, v3
	v_div_scale_f32 v4, vcc, 1.0, v0, 1.0
	v_mul_f32_e32 v5, v4, v3
	v_fma_f32 v6, -v2, v5, v4
	v_fmac_f32_e32 v5, v6, v3
	v_fma_f32 v2, -v2, v5, v4
	v_div_fmas_f32 v2, v2, v3, v5
	v_div_fixup_f32 v0, v2, v0, 1.0
	v_fma_f32 v0, v0, s80, 0.5
	v_cvt_u32_f32_e32 v155, v0
	v_mul_f32_e32 v0, 0xbfb8aa3b, v7
	v_exp_f32_e32 v0, v0
	s_nop 0
	v_add_f32_e32 v0, 1.0, v0
	v_div_scale_f32 v2, s[0:1], v0, v0, 1.0
	v_rcp_f32_e32 v3, v2
	s_nop 0
	v_fma_f32 v4, -v2, v3, 1.0
	v_fmac_f32_e32 v3, v4, v3
	v_div_scale_f32 v4, vcc, 1.0, v0, 1.0
	v_mul_f32_e32 v5, v4, v3
	v_fma_f32 v6, -v2, v5, v4
	v_fmac_f32_e32 v5, v6, v3
	v_fma_f32 v2, -v2, v5, v4
	v_div_fmas_f32 v2, v2, v3, v5
	v_div_fixup_f32 v0, v2, v0, 1.0
	v_mul_f32_e32 v2, 0xbfb8aa3b, v8
	v_exp_f32_e32 v2, v2
	v_fma_f32 v0, v0, s80, 0.5
	v_cvt_u32_f32_e32 v0, v0
	v_add_f32_e32 v2, 1.0, v2
	v_div_scale_f32 v3, s[0:1], v2, v2, 1.0
	v_rcp_f32_e32 v4, v3
	v_lshl_or_b32 v157, v0, 8, v155
	v_mul_f32_e32 v0, 0xbfb8aa3b, v10
	v_exp_f32_e32 v0, v0
	v_fma_f32 v5, -v3, v4, 1.0
	v_fmac_f32_e32 v4, v5, v4
	v_div_scale_f32 v5, vcc, 1.0, v2, 1.0
	v_mul_f32_e32 v6, v5, v4
	v_fma_f32 v7, -v3, v6, v5
	v_fmac_f32_e32 v6, v7, v4
	v_fma_f32 v3, -v3, v6, v5
	v_div_fmas_f32 v3, v3, v4, v6
	v_div_fixup_f32 v2, v3, v2, 1.0
	v_mul_f32_e32 v3, 0xbfb8aa3b, v9
	v_exp_f32_e32 v3, v3
	v_fma_f32 v2, v2, s80, 0.5
	v_cvt_u32_f32_sdwa v2, v2 dst_sel:WORD_1 dst_unused:UNUSED_PAD src0_sel:DWORD
	v_add_f32_e32 v0, 1.0, v0
	v_add_f32_e32 v3, 1.0, v3
	v_div_scale_f32 v4, s[0:1], v3, v3, 1.0
	v_rcp_f32_e32 v5, v4
	s_nop 0
	v_fma_f32 v6, -v4, v5, 1.0
	v_fmac_f32_e32 v5, v6, v5
	v_div_scale_f32 v6, vcc, 1.0, v3, 1.0
	v_mul_f32_e32 v7, v6, v5
	v_fma_f32 v8, -v4, v7, v6
	v_fmac_f32_e32 v7, v8, v5
	v_fma_f32 v4, -v4, v7, v6
	v_div_fmas_f32 v4, v4, v5, v7
	v_div_fixup_f32 v3, v4, v3, 1.0
	v_fma_f32 v3, v3, s80, 0.5
	v_cvt_u32_f32_sdwa v3, v3 dst_sel:BYTE_3 dst_unused:UNUSED_PAD src0_sel:DWORD
	s_nop 0
	v_or3_b32 v156, v2, v3, v157
	v_div_scale_f32 v2, s[0:1], v0, v0, 1.0
	v_rcp_f32_e32 v3, v2
	s_nop 0
	v_fma_f32 v4, -v2, v3, 1.0
	v_fmac_f32_e32 v3, v4, v3
	v_div_scale_f32 v4, vcc, 1.0, v0, 1.0
	v_mul_f32_e32 v5, v4, v3
	v_fma_f32 v6, -v2, v5, v4
	v_fmac_f32_e32 v5, v6, v3
	v_fma_f32 v2, -v2, v5, v4
	v_div_fmas_f32 v2, v2, v3, v5
	v_div_fixup_f32 v0, v2, v0, 1.0
	v_fma_f32 v0, v0, s80, 0.5
	v_cvt_u32_f32_e32 v158, v0
	v_mul_f32_e32 v0, 0xbfb8aa3b, v11
	v_exp_f32_e32 v0, v0
	s_nop 0
	v_add_f32_e32 v0, 1.0, v0
	v_div_scale_f32 v2, s[0:1], v0, v0, 1.0
	v_rcp_f32_e32 v3, v2
	s_nop 0
	v_fma_f32 v4, -v2, v3, 1.0
	v_fmac_f32_e32 v3, v4, v3
	v_div_scale_f32 v4, vcc, 1.0, v0, 1.0
	v_mul_f32_e32 v5, v4, v3
	v_fma_f32 v6, -v2, v5, v4
	v_fmac_f32_e32 v5, v6, v3
	v_fma_f32 v2, -v2, v5, v4
	v_div_fmas_f32 v2, v2, v3, v5
	v_div_fixup_f32 v0, v2, v0, 1.0
	v_mul_f32_e32 v2, 0xbfb8aa3b, v12
	v_exp_f32_e32 v2, v2
	v_fma_f32 v0, v0, s80, 0.5
	v_cvt_u32_f32_e32 v0, v0
	v_add_f32_e32 v2, 1.0, v2
	v_div_scale_f32 v3, s[0:1], v2, v2, 1.0
	v_rcp_f32_e32 v4, v3
	v_lshl_or_b32 v160, v0, 8, v158
	v_mul_f32_e32 v0, 0xbfb8aa3b, v14
	v_exp_f32_e32 v0, v0
	v_fma_f32 v5, -v3, v4, 1.0
	v_fmac_f32_e32 v4, v5, v4
	v_div_scale_f32 v5, vcc, 1.0, v2, 1.0
	v_mul_f32_e32 v6, v5, v4
	v_fma_f32 v7, -v3, v6, v5
	v_fmac_f32_e32 v6, v7, v4
	v_fma_f32 v3, -v3, v6, v5
	v_div_fmas_f32 v3, v3, v4, v6
	v_div_fixup_f32 v2, v3, v2, 1.0
	v_mul_f32_e32 v3, 0xbfb8aa3b, v13
	v_exp_f32_e32 v3, v3
	v_fma_f32 v2, v2, s80, 0.5
	v_cvt_u32_f32_sdwa v2, v2 dst_sel:WORD_1 dst_unused:UNUSED_PAD src0_sel:DWORD
	v_add_f32_e32 v0, 1.0, v0
	v_add_f32_e32 v3, 1.0, v3
	v_div_scale_f32 v4, s[0:1], v3, v3, 1.0
	v_rcp_f32_e32 v5, v4
	s_nop 0
	v_fma_f32 v6, -v4, v5, 1.0
	v_fmac_f32_e32 v5, v6, v5
	v_div_scale_f32 v6, vcc, 1.0, v3, 1.0
	v_mul_f32_e32 v7, v6, v5
	v_fma_f32 v8, -v4, v7, v6
	v_fmac_f32_e32 v7, v8, v5
	v_fma_f32 v4, -v4, v7, v6
	v_div_fmas_f32 v4, v4, v5, v7
	v_div_fixup_f32 v3, v4, v3, 1.0
	v_fma_f32 v3, v3, s80, 0.5
	v_cvt_u32_f32_sdwa v3, v3 dst_sel:BYTE_3 dst_unused:UNUSED_PAD src0_sel:DWORD
	s_nop 0
	v_or3_b32 v159, v2, v3, v160
	v_div_scale_f32 v2, s[0:1], v0, v0, 1.0
	v_rcp_f32_e32 v3, v2
	s_nop 0
	v_fma_f32 v4, -v2, v3, 1.0
	v_fmac_f32_e32 v3, v4, v3
	v_div_scale_f32 v4, vcc, 1.0, v0, 1.0
	v_mul_f32_e32 v5, v4, v3
	v_fma_f32 v6, -v2, v5, v4
	v_fmac_f32_e32 v5, v6, v3
	v_fma_f32 v2, -v2, v5, v4
	v_div_fmas_f32 v2, v2, v3, v5
	v_div_fixup_f32 v0, v2, v0, 1.0
	v_fma_f32 v0, v0, s80, 0.5
	v_cvt_u32_f32_e32 v161, v0
	v_mul_f32_e32 v0, 0xbfb8aa3b, v15
	v_exp_f32_e32 v0, v0
	s_nop 0
	v_add_f32_e32 v0, 1.0, v0
	v_div_scale_f32 v2, s[0:1], v0, v0, 1.0
	v_rcp_f32_e32 v3, v2
	s_nop 0
	v_fma_f32 v4, -v2, v3, 1.0
	v_fmac_f32_e32 v3, v4, v3
	v_div_scale_f32 v4, vcc, 1.0, v0, 1.0
	v_mul_f32_e32 v5, v4, v3
	v_fma_f32 v6, -v2, v5, v4
	v_fmac_f32_e32 v5, v6, v3
	v_fma_f32 v2, -v2, v5, v4
	v_div_fmas_f32 v2, v2, v3, v5
	v_div_fixup_f32 v0, v2, v0, 1.0
	v_mul_f32_e32 v2, 0xbfb8aa3b, v16
	v_exp_f32_e32 v2, v2
	v_fma_f32 v0, v0, s80, 0.5
	v_cvt_u32_f32_e32 v0, v0
	v_add_f32_e32 v2, 1.0, v2
	v_div_scale_f32 v3, s[0:1], v2, v2, 1.0
	v_rcp_f32_e32 v4, v3
	v_lshl_or_b32 v163, v0, 8, v161
	v_fma_f32 v5, -v3, v4, 1.0
	v_fmac_f32_e32 v4, v5, v4
	v_div_scale_f32 v5, vcc, 1.0, v2, 1.0
	v_mul_f32_e32 v6, v5, v4
	v_fma_f32 v7, -v3, v6, v5
	v_fmac_f32_e32 v6, v7, v4
	v_fma_f32 v3, -v3, v6, v5
	v_div_fmas_f32 v3, v3, v4, v6
	v_div_fixup_f32 v2, v3, v2, 1.0
	v_mul_f32_e32 v3, 0xbfb8aa3b, v17
	v_exp_f32_e32 v3, v3
	v_fma_f32 v2, v2, s80, 0.5
	v_cvt_u32_f32_sdwa v2, v2 dst_sel:WORD_1 dst_unused:UNUSED_PAD src0_sel:DWORD
	v_add_f32_e32 v3, 1.0, v3
	v_div_scale_f32 v4, s[0:1], v3, v3, 1.0
	v_rcp_f32_e32 v5, v4
	s_movk_i32 s0, 0xaa0
	s_cselect_b32 s12, s0, 0x12a0
	s_mov_b32 s0, 0x12f0000
	v_fma_f32 v6, -v4, v5, 1.0
	v_fmac_f32_e32 v5, v6, v5
	v_div_scale_f32 v6, vcc, 1.0, v3, 1.0
	v_mul_f32_e32 v7, v6, v5
	v_fma_f32 v8, -v4, v7, v6
	v_fmac_f32_e32 v7, v8, v5
	v_fma_f32 v4, -v4, v7, v6
	v_div_fmas_f32 v4, v4, v5, v7
	s_cselect_b32 s13, s0, 0x13f0000
	s_cmp_eq_u32 s45, 0
	v_div_fixup_f32 v3, v4, v3, 1.0
	s_cselect_b64 vcc, -1, 0
	v_fma_f32 v3, v3, s80, 0.5
	s_and_b64 s[0:1], vcc, exec
	v_cvt_u32_f32_sdwa v3, v3 dst_sel:BYTE_3 dst_unused:UNUSED_PAD src0_sel:DWORD
	s_cselect_b32 s0, 0x2a0, s12
	s_cselect_b32 s13, 0x11f0000, s13
	s_lshl_b32 s0, s0, 1
	s_add_u32 s0, s43, s0
	v_mov_b32_e32 v6, v178
	s_addc_u32 s1, s44, 0
	v_or3_b32 v162, v2, v3, v163
	v_lshlrev_b32_e32 v0, 3, v6
	v_ashrrev_i32_e32 v2, 3, v6
	v_and_b32_e32 v36, 56, v0
	v_mov_b64_e32 v[4:5], s[0:1]
	s_add_u32 s12, s25, s13
	v_ashrrev_i32_e32 v3, 31, v2
	v_mad_i64_i32 v[4:5], s[0:1], v2, s77, v[4:5]
	v_lshlrev_b32_e32 v0, 1, v36
	s_addc_u32 s13, s42, 0
	v_lshl_add_u64 v[102:103], v[4:5], 0, v[0:1]
	v_lshlrev_b64 v[4:5], 10, v[2:3]
	v_lshl_add_u64 v[4:5], s[12:13], 0, v[4:5]
	v_and_b32_e32 v7, 31, v6
	v_lshl_add_u64 v[100:101], v[4:5], 0, v[0:1]
	v_lshrrev_b32_e32 v0, 1, v6
	v_and_or_b32 v3, v0, s35, v7
	v_and_b32_e32 v0, 16, v0
	v_mad_u64_u32 v[98:99], s[0:1], v3, s72, v[0:1]
	v_add_co_u32_e64 v104, s[0:1], s97, v102
	v_and_b32_e32 v3, 0x5f, v6
	s_nop 0
	v_addc_co_u32_e64 v105, s[0:1], 0, v103, s[0:1]
	v_add_co_u32_e64 v106, s[0:1], s31, v100
	global_load_dwordx4 v[4:7], v[102:103], off
	global_load_dwordx4 v[8:11], v[100:101], off
	v_addc_co_u32_e64 v107, s[0:1], 0, v101, s[0:1]
	v_add_co_u32_e64 v108, s[0:1], s26, v102
	global_load_dwordx4 v[12:15], v[104:105], off
	global_load_dwordx4 v[16:19], v[106:107], off
	v_addc_co_u32_e64 v109, s[0:1], 0, v103, s[0:1]
	v_add_co_u32_e64 v110, s[0:1], s73, v100
	global_load_dwordx4 v[20:23], v[108:109], off
	s_nop 0
	v_addc_co_u32_e64 v111, s[0:1], 0, v101, s[0:1]
	v_add_co_u32_e64 v112, s[0:1], s96, v102
	global_load_dwordx4 v[24:27], v[110:111], off
	s_nop 0
	v_addc_co_u32_e64 v113, s[0:1], 0, v103, s[0:1]
	s_mov_b32 s0, 0x18000
	s_nop 0
	v_add_co_u32_e64 v114, s[0:1], s0, v100
	global_load_dwordx4 v[28:31], v[112:113], off
	s_nop 0
	v_addc_co_u32_e64 v115, s[0:1], 0, v101, s[0:1]
	global_load_dwordx4 v[32:35], v[114:115], off
	v_mul_lo_u32 v2, v2, s82
	v_add_lshl_u32 v99, v2, v36, 1
	s_waitcnt vmcnt(7)
	ds_write_b128 v99, v[4:7]
	s_waitcnt vmcnt(6)
	ds_write_b128 v99, v[8:11] offset:36864
	s_waitcnt vmcnt(5)
	ds_write_b128 v99, v[12:15] offset:4608
	s_waitcnt vmcnt(4)
	ds_write_b128 v99, v[16:19] offset:41472
	s_waitcnt vmcnt(3)
	ds_write_b128 v99, v[20:23] offset:9216
	s_waitcnt vmcnt(2)
	ds_write_b128 v99, v[24:27] offset:46080
	s_waitcnt vmcnt(1)
	ds_write_b128 v99, v[28:31] offset:13824
	s_waitcnt vmcnt(0)
	ds_write_b128 v99, v[32:35] offset:50688
	s_waitcnt lgkmcnt(0)
	s_barrier
	global_load_dwordx4 v[94:97], v[102:103], off offset:128
	global_load_dwordx4 v[78:81], v[100:101], off offset:128
	global_load_dwordx4 v[82:85], v[104:105], off offset:128
	global_load_dwordx4 v[86:89], v[106:107], off offset:128
	global_load_dwordx4 v[90:93], v[108:109], off offset:128
	global_load_dwordx4 v[66:69], v[110:111], off offset:128
	global_load_dwordx4 v[70:73], v[112:113], off offset:128
	global_load_dwordx4 v[74:77], v[114:115], off offset:128
	v_mad_u32_u24 v0, v3, s72, v0
	ds_read_b128 v[18:21], v98 offset:4608
	ds_read_b128 v[22:25], v0 offset:41472
	ds_read_b128 v[26:29], v98
	ds_read_b128 v[222:225], v98 offset:32
	ds_read_b128 v[30:33], v0 offset:36864
	ds_read_b128 v[226:229], v0 offset:36896
	s_waitcnt lgkmcnt(1)
	v_mfma_f32_32x32x16_bf16 v[2:17], v[26:29], v[30:33], 0
	ds_read_b128 v[230:233], v98 offset:4640
	ds_read_b128 v[234:237], v0 offset:41504
	s_cmp_eq_u32 s45, 2
	s_mov_b64 s[0:1], -1
	v_mfma_f32_32x32x16_bf16 v[50:65], v[26:29], v[22:25], 0
	v_mfma_f32_32x32x16_bf16 v[34:49], v[18:21], v[30:33], 0
	v_mfma_f32_32x32x16_bf16 v[18:33], v[18:21], v[22:25], 0
	s_waitcnt lgkmcnt(2)
	v_mfma_f32_32x32x16_bf16 v[2:17], v[222:225], v[226:229], v[2:17]
	s_waitcnt lgkmcnt(0)
	v_mfma_f32_32x32x16_bf16 v[50:65], v[222:225], v[234:237], v[50:65]
	v_mfma_f32_32x32x16_bf16 v[34:49], v[230:233], v[226:229], v[34:49]
	v_mfma_f32_32x32x16_bf16 v[18:33], v[230:233], v[234:237], v[18:33]
	ds_read_b128 v[222:225], v98 offset:64
	ds_read_b128 v[226:229], v98 offset:4672
	ds_read_b128 v[230:233], v0 offset:36928
	ds_read_b128 v[234:237], v0 offset:41536
	s_waitcnt lgkmcnt(1)
	v_mfma_f32_32x32x16_bf16 v[2:17], v[222:225], v[230:233], v[2:17]
	s_waitcnt lgkmcnt(0)
	v_mfma_f32_32x32x16_bf16 v[50:65], v[222:225], v[234:237], v[50:65]
	v_mfma_f32_32x32x16_bf16 v[34:49], v[226:229], v[230:233], v[34:49]
	v_mfma_f32_32x32x16_bf16 v[18:33], v[226:229], v[234:237], v[18:33]
	ds_read_b128 v[222:225], v98 offset:96
	ds_read_b128 v[226:229], v98 offset:4704
	ds_read_b128 v[230:233], v0 offset:36960
	ds_read_b128 v[234:237], v0 offset:41568
	s_waitcnt vmcnt(7)
	ds_write_b128 v99, v[94:97] offset:18432
	s_waitcnt lgkmcnt(2)
	v_mfma_f32_32x32x16_bf16 v[2:17], v[222:225], v[230:233], v[2:17]
	s_waitcnt lgkmcnt(1)
	v_mfma_f32_32x32x16_bf16 v[50:65], v[222:225], v[234:237], v[50:65]
	v_add_u32_e32 v222, 0xd800, v99
	s_waitcnt vmcnt(6)
	ds_write_b128 v99, v[78:81] offset:55296
	s_waitcnt vmcnt(5)
	ds_write_b128 v99, v[82:85] offset:23040
	s_waitcnt vmcnt(4)
	ds_write_b128 v99, v[86:89] offset:59904
	s_waitcnt vmcnt(3)
	ds_write_b128 v99, v[90:93] offset:27648
	s_waitcnt vmcnt(2)
	ds_write_b128 v99, v[66:69] offset:64512
	s_waitcnt vmcnt(1)
	ds_write_b128 v99, v[70:73] offset:32256
	s_waitcnt vmcnt(0)
	ds_write_b128 v222, v[74:77] offset:13824
	s_waitcnt lgkmcnt(0)
	s_barrier
	global_load_dwordx4 v[94:97], v[102:103], off offset:256
	global_load_dwordx4 v[78:81], v[100:101], off offset:256
	global_load_dwordx4 v[82:85], v[104:105], off offset:256
	global_load_dwordx4 v[86:89], v[106:107], off offset:256
	global_load_dwordx4 v[90:93], v[108:109], off offset:256
	global_load_dwordx4 v[66:69], v[110:111], off offset:256
	global_load_dwordx4 v[70:73], v[112:113], off offset:256
	global_load_dwordx4 v[74:77], v[114:115], off offset:256
	v_mfma_f32_32x32x16_bf16 v[34:49], v[226:229], v[230:233], v[34:49]
	v_mfma_f32_32x32x16_bf16 v[18:33], v[226:229], v[234:237], v[18:33]
	ds_read_b128 v[224:227], v98 offset:23040
	ds_read_b128 v[228:231], v0 offset:59904
	ds_read_b128 v[232:235], v98 offset:18432
	ds_read_b128 v[236:239], v98 offset:18464
	ds_read_b128 v[240:243], v0 offset:55296
	ds_read_b128 v[244:247], v0 offset:55328
	s_waitcnt lgkmcnt(1)
	v_mfma_f32_32x32x16_bf16 v[2:17], v[232:235], v[240:243], v[2:17]
	v_mfma_f32_32x32x16_bf16 v[50:65], v[232:235], v[228:231], v[50:65]
	v_mfma_f32_32x32x16_bf16 v[34:49], v[224:227], v[240:243], v[34:49]
	v_mfma_f32_32x32x16_bf16 v[18:33], v[224:227], v[228:231], v[18:33]
	ds_read_b128 v[224:227], v98 offset:23072
	ds_read_b128 v[228:231], v0 offset:59936
	s_waitcnt lgkmcnt(2)
	v_mfma_f32_32x32x16_bf16 v[2:17], v[236:239], v[244:247], v[2:17]
	s_waitcnt lgkmcnt(0)
	v_mfma_f32_32x32x16_bf16 v[50:65], v[236:239], v[228:231], v[50:65]
	v_mfma_f32_32x32x16_bf16 v[34:49], v[224:227], v[244:247], v[34:49]
	v_mfma_f32_32x32x16_bf16 v[18:33], v[224:227], v[228:231], v[18:33]
	ds_read_b128 v[224:227], v98 offset:18496
	ds_read_b128 v[228:231], v98 offset:23104
	ds_read_b128 v[232:235], v0 offset:55360
	ds_read_b128 v[236:239], v0 offset:59968
	s_waitcnt lgkmcnt(1)
	v_mfma_f32_32x32x16_bf16 v[2:17], v[224:227], v[232:235], v[2:17]
	s_waitcnt lgkmcnt(0)
	v_mfma_f32_32x32x16_bf16 v[50:65], v[224:227], v[236:239], v[50:65]
	v_mfma_f32_32x32x16_bf16 v[34:49], v[228:231], v[232:235], v[34:49]
	v_mfma_f32_32x32x16_bf16 v[18:33], v[228:231], v[236:239], v[18:33]
	ds_read_b128 v[224:227], v98 offset:18528
	ds_read_b128 v[228:231], v98 offset:23136
	ds_read_b128 v[232:235], v0 offset:55392
	ds_read_b128 v[236:239], v0 offset:60000
	s_waitcnt vmcnt(7)
	ds_write_b128 v99, v[94:97]
	s_waitcnt vmcnt(6)
	ds_write_b128 v99, v[78:81] offset:36864
	s_waitcnt vmcnt(5)
	ds_write_b128 v99, v[82:85] offset:4608
	s_waitcnt vmcnt(4)
	ds_write_b128 v99, v[86:89] offset:41472
	s_waitcnt vmcnt(3)
	ds_write_b128 v99, v[90:93] offset:9216
	s_waitcnt vmcnt(2)
	ds_write_b128 v99, v[66:69] offset:46080
	s_waitcnt vmcnt(1)
	ds_write_b128 v99, v[70:73] offset:13824
	s_waitcnt vmcnt(0)
	ds_write_b128 v99, v[74:77] offset:50688
	s_waitcnt lgkmcnt(0)
	s_barrier
	global_load_dwordx4 v[78:81], v[102:103], off offset:384
	global_load_dwordx4 v[82:85], v[100:101], off offset:384
	global_load_dwordx4 v[86:89], v[104:105], off offset:384
	global_load_dwordx4 v[90:93], v[106:107], off offset:384
	global_load_dwordx4 v[94:97], v[108:109], off offset:384
	global_load_dwordx4 v[66:69], v[110:111], off offset:384
	global_load_dwordx4 v[70:73], v[112:113], off offset:384
	global_load_dwordx4 v[74:77], v[114:115], off offset:384
	v_mfma_f32_32x32x16_bf16 v[2:17], v[224:227], v[232:235], v[2:17]
	v_mfma_f32_32x32x16_bf16 v[50:65], v[224:227], v[236:239], v[50:65]
	v_mfma_f32_32x32x16_bf16 v[34:49], v[228:231], v[232:235], v[34:49]
	v_mfma_f32_32x32x16_bf16 v[18:33], v[228:231], v[236:239], v[18:33]
	ds_read_b128 v[224:227], v98 offset:4608
	ds_read_b128 v[228:231], v0 offset:41472
	ds_read_b128 v[232:235], v98
	ds_read_b128 v[236:239], v98 offset:32
	ds_read_b128 v[240:243], v0 offset:36864
	ds_read_b128 v[244:247], v0 offset:36896
	s_waitcnt lgkmcnt(1)
	v_mfma_f32_32x32x16_bf16 v[2:17], v[232:235], v[240:243], v[2:17]
	v_mfma_f32_32x32x16_bf16 v[50:65], v[232:235], v[228:231], v[50:65]
	v_mfma_f32_32x32x16_bf16 v[34:49], v[224:227], v[240:243], v[34:49]
	v_mfma_f32_32x32x16_bf16 v[18:33], v[224:227], v[228:231], v[18:33]
	ds_read_b128 v[224:227], v98 offset:4640
	ds_read_b128 v[228:231], v0 offset:41504
	s_waitcnt lgkmcnt(2)
	v_mfma_f32_32x32x16_bf16 v[2:17], v[236:239], v[244:247], v[2:17]
	s_waitcnt lgkmcnt(0)
	v_mfma_f32_32x32x16_bf16 v[50:65], v[236:239], v[228:231], v[50:65]
	v_mfma_f32_32x32x16_bf16 v[34:49], v[224:227], v[244:247], v[34:49]
	v_mfma_f32_32x32x16_bf16 v[18:33], v[224:227], v[228:231], v[18:33]
	ds_read_b128 v[224:227], v98 offset:64
	ds_read_b128 v[228:231], v98 offset:4672
	ds_read_b128 v[232:235], v0 offset:36928
	ds_read_b128 v[236:239], v0 offset:41536
	s_waitcnt lgkmcnt(1)
	v_mfma_f32_32x32x16_bf16 v[2:17], v[224:227], v[232:235], v[2:17]
	s_waitcnt lgkmcnt(0)
	v_mfma_f32_32x32x16_bf16 v[50:65], v[224:227], v[236:239], v[50:65]
	v_mfma_f32_32x32x16_bf16 v[34:49], v[228:231], v[232:235], v[34:49]
	v_mfma_f32_32x32x16_bf16 v[18:33], v[228:231], v[236:239], v[18:33]
	ds_read_b128 v[224:227], v98 offset:96
	ds_read_b128 v[228:231], v98 offset:4704
	ds_read_b128 v[232:235], v0 offset:36960
	ds_read_b128 v[236:239], v0 offset:41568
	s_waitcnt vmcnt(7)
	ds_write_b128 v99, v[78:81] offset:18432
	s_waitcnt vmcnt(6)
	ds_write_b128 v99, v[82:85] offset:55296
	s_waitcnt vmcnt(5)
	ds_write_b128 v99, v[86:89] offset:23040
	s_waitcnt vmcnt(4)
	ds_write_b128 v99, v[90:93] offset:59904
	s_waitcnt vmcnt(3)
	ds_write_b128 v99, v[94:97] offset:27648
	s_waitcnt vmcnt(2)
	ds_write_b128 v99, v[66:69] offset:64512
	s_waitcnt vmcnt(1)
	ds_write_b128 v99, v[70:73] offset:32256
	s_waitcnt vmcnt(0)
	ds_write_b128 v222, v[74:77] offset:13824
	s_waitcnt lgkmcnt(0)
	s_barrier
	global_load_dwordx4 v[78:81], v[102:103], off offset:512
	global_load_dwordx4 v[82:85], v[100:101], off offset:512
	global_load_dwordx4 v[86:89], v[104:105], off offset:512
	global_load_dwordx4 v[90:93], v[106:107], off offset:512
	global_load_dwordx4 v[94:97], v[108:109], off offset:512
	global_load_dwordx4 v[66:69], v[110:111], off offset:512
	global_load_dwordx4 v[70:73], v[112:113], off offset:512
	global_load_dwordx4 v[74:77], v[114:115], off offset:512
	v_mfma_f32_32x32x16_bf16 v[2:17], v[224:227], v[232:235], v[2:17]
	v_mfma_f32_32x32x16_bf16 v[50:65], v[224:227], v[236:239], v[50:65]
	v_mfma_f32_32x32x16_bf16 v[34:49], v[228:231], v[232:235], v[34:49]
	v_mfma_f32_32x32x16_bf16 v[18:33], v[228:231], v[236:239], v[18:33]
	ds_read_b128 v[224:227], v98 offset:23040
	ds_read_b128 v[228:231], v0 offset:59904
	ds_read_b128 v[232:235], v98 offset:18432
	ds_read_b128 v[236:239], v98 offset:18464
	ds_read_b128 v[240:243], v0 offset:55296
	ds_read_b128 v[244:247], v0 offset:55328
	s_waitcnt lgkmcnt(1)
	v_mfma_f32_32x32x16_bf16 v[2:17], v[232:235], v[240:243], v[2:17]
	v_mfma_f32_32x32x16_bf16 v[50:65], v[232:235], v[228:231], v[50:65]
	v_mfma_f32_32x32x16_bf16 v[34:49], v[224:227], v[240:243], v[34:49]
	v_mfma_f32_32x32x16_bf16 v[18:33], v[224:227], v[228:231], v[18:33]
	ds_read_b128 v[224:227], v98 offset:23072
	ds_read_b128 v[228:231], v0 offset:59936
	s_waitcnt lgkmcnt(2)
	v_mfma_f32_32x32x16_bf16 v[2:17], v[236:239], v[244:247], v[2:17]
	s_waitcnt lgkmcnt(0)
	v_mfma_f32_32x32x16_bf16 v[50:65], v[236:239], v[228:231], v[50:65]
	v_mfma_f32_32x32x16_bf16 v[34:49], v[224:227], v[244:247], v[34:49]
	v_mfma_f32_32x32x16_bf16 v[18:33], v[224:227], v[228:231], v[18:33]
	ds_read_b128 v[224:227], v98 offset:18496
	ds_read_b128 v[228:231], v98 offset:23104
	ds_read_b128 v[232:235], v0 offset:55360
	ds_read_b128 v[236:239], v0 offset:59968
	s_waitcnt lgkmcnt(1)
	v_mfma_f32_32x32x16_bf16 v[2:17], v[224:227], v[232:235], v[2:17]
	s_waitcnt lgkmcnt(0)
	v_mfma_f32_32x32x16_bf16 v[50:65], v[224:227], v[236:239], v[50:65]
	v_mfma_f32_32x32x16_bf16 v[34:49], v[228:231], v[232:235], v[34:49]
	v_mfma_f32_32x32x16_bf16 v[18:33], v[228:231], v[236:239], v[18:33]
	ds_read_b128 v[224:227], v98 offset:18528
	ds_read_b128 v[228:231], v98 offset:23136
	ds_read_b128 v[232:235], v0 offset:55392
	ds_read_b128 v[236:239], v0 offset:60000
	s_waitcnt vmcnt(7)
	ds_write_b128 v99, v[78:81]
	s_waitcnt vmcnt(6)
	ds_write_b128 v99, v[82:85] offset:36864
	s_waitcnt vmcnt(5)
	ds_write_b128 v99, v[86:89] offset:4608
	s_waitcnt vmcnt(4)
	ds_write_b128 v99, v[90:93] offset:41472
	s_waitcnt vmcnt(3)
	ds_write_b128 v99, v[94:97] offset:9216
	s_waitcnt vmcnt(2)
	ds_write_b128 v99, v[66:69] offset:46080
	s_waitcnt vmcnt(1)
	ds_write_b128 v99, v[70:73] offset:13824
	s_waitcnt vmcnt(0)
	ds_write_b128 v99, v[74:77] offset:50688
	s_waitcnt lgkmcnt(0)
	s_barrier
	global_load_dwordx4 v[78:81], v[102:103], off offset:640
	global_load_dwordx4 v[82:85], v[100:101], off offset:640
	global_load_dwordx4 v[86:89], v[104:105], off offset:640
	global_load_dwordx4 v[90:93], v[106:107], off offset:640
	global_load_dwordx4 v[94:97], v[108:109], off offset:640
	global_load_dwordx4 v[66:69], v[110:111], off offset:640
	global_load_dwordx4 v[70:73], v[112:113], off offset:640
	global_load_dwordx4 v[74:77], v[114:115], off offset:640
	v_mfma_f32_32x32x16_bf16 v[2:17], v[224:227], v[232:235], v[2:17]
	v_mfma_f32_32x32x16_bf16 v[50:65], v[224:227], v[236:239], v[50:65]
	v_mfma_f32_32x32x16_bf16 v[34:49], v[228:231], v[232:235], v[34:49]
	v_mfma_f32_32x32x16_bf16 v[18:33], v[228:231], v[236:239], v[18:33]
	ds_read_b128 v[224:227], v98 offset:4608
	ds_read_b128 v[228:231], v0 offset:41472
	ds_read_b128 v[232:235], v98
	ds_read_b128 v[236:239], v98 offset:32
	ds_read_b128 v[240:243], v0 offset:36864
	ds_read_b128 v[244:247], v0 offset:36896
	s_waitcnt lgkmcnt(1)
	v_mfma_f32_32x32x16_bf16 v[2:17], v[232:235], v[240:243], v[2:17]
	v_mfma_f32_32x32x16_bf16 v[50:65], v[232:235], v[228:231], v[50:65]
	v_mfma_f32_32x32x16_bf16 v[34:49], v[224:227], v[240:243], v[34:49]
	v_mfma_f32_32x32x16_bf16 v[18:33], v[224:227], v[228:231], v[18:33]
	ds_read_b128 v[224:227], v98 offset:4640
	ds_read_b128 v[228:231], v0 offset:41504
	s_waitcnt lgkmcnt(2)
	v_mfma_f32_32x32x16_bf16 v[2:17], v[236:239], v[244:247], v[2:17]
	s_waitcnt lgkmcnt(0)
	v_mfma_f32_32x32x16_bf16 v[50:65], v[236:239], v[228:231], v[50:65]
	v_mfma_f32_32x32x16_bf16 v[34:49], v[224:227], v[244:247], v[34:49]
	v_mfma_f32_32x32x16_bf16 v[18:33], v[224:227], v[228:231], v[18:33]
	ds_read_b128 v[224:227], v98 offset:64
	ds_read_b128 v[228:231], v98 offset:4672
	ds_read_b128 v[232:235], v0 offset:36928
	ds_read_b128 v[236:239], v0 offset:41536
	s_waitcnt lgkmcnt(1)
	v_mfma_f32_32x32x16_bf16 v[2:17], v[224:227], v[232:235], v[2:17]
	s_waitcnt lgkmcnt(0)
	v_mfma_f32_32x32x16_bf16 v[50:65], v[224:227], v[236:239], v[50:65]
	v_mfma_f32_32x32x16_bf16 v[34:49], v[228:231], v[232:235], v[34:49]
	v_mfma_f32_32x32x16_bf16 v[18:33], v[228:231], v[236:239], v[18:33]
	ds_read_b128 v[224:227], v98 offset:96
	ds_read_b128 v[228:231], v98 offset:4704
	ds_read_b128 v[232:235], v0 offset:36960
	ds_read_b128 v[236:239], v0 offset:41568
	s_waitcnt vmcnt(7)
	ds_write_b128 v99, v[78:81] offset:18432
	s_waitcnt vmcnt(6)
	ds_write_b128 v99, v[82:85] offset:55296
	s_waitcnt vmcnt(5)
	ds_write_b128 v99, v[86:89] offset:23040
	s_waitcnt vmcnt(4)
	ds_write_b128 v99, v[90:93] offset:59904
	s_waitcnt vmcnt(3)
	ds_write_b128 v99, v[94:97] offset:27648
	s_waitcnt vmcnt(2)
	ds_write_b128 v99, v[66:69] offset:64512
	s_waitcnt vmcnt(1)
	ds_write_b128 v99, v[70:73] offset:32256
	s_waitcnt vmcnt(0)
	ds_write_b128 v222, v[74:77] offset:13824
	s_waitcnt lgkmcnt(0)
	s_barrier
	global_load_dwordx4 v[94:97], v[102:103], off offset:768
	global_load_dwordx4 v[90:93], v[100:101], off offset:768
	global_load_dwordx4 v[70:73], v[104:105], off offset:768
	global_load_dwordx4 v[74:77], v[106:107], off offset:768
	global_load_dwordx4 v[78:81], v[108:109], off offset:768
	global_load_dwordx4 v[82:85], v[110:111], off offset:768
	global_load_dwordx4 v[86:89], v[112:113], off offset:768
	global_load_dwordx4 v[66:69], v[114:115], off offset:768
	v_mfma_f32_32x32x16_bf16 v[2:17], v[224:227], v[232:235], v[2:17]
	v_mfma_f32_32x32x16_bf16 v[50:65], v[224:227], v[236:239], v[50:65]
	v_mfma_f32_32x32x16_bf16 v[34:49], v[228:231], v[232:235], v[34:49]
	v_mfma_f32_32x32x16_bf16 v[18:33], v[228:231], v[236:239], v[18:33]
	ds_read_b128 v[224:227], v98 offset:23040
	ds_read_b128 v[228:231], v0 offset:59904
	ds_read_b128 v[232:235], v98 offset:18432
	ds_read_b128 v[236:239], v98 offset:18464
	ds_read_b128 v[240:243], v0 offset:55296
	ds_read_b128 v[244:247], v0 offset:55328
	s_waitcnt lgkmcnt(1)
	v_mfma_f32_32x32x16_bf16 v[2:17], v[232:235], v[240:243], v[2:17]
	v_mfma_f32_32x32x16_bf16 v[50:65], v[232:235], v[228:231], v[50:65]
	v_mfma_f32_32x32x16_bf16 v[34:49], v[224:227], v[240:243], v[34:49]
	v_mfma_f32_32x32x16_bf16 v[18:33], v[224:227], v[228:231], v[18:33]
	ds_read_b128 v[224:227], v98 offset:23072
	ds_read_b128 v[228:231], v0 offset:59936
	s_waitcnt lgkmcnt(2)
	v_mfma_f32_32x32x16_bf16 v[2:17], v[236:239], v[244:247], v[2:17]
	s_waitcnt lgkmcnt(0)
	v_mfma_f32_32x32x16_bf16 v[50:65], v[236:239], v[228:231], v[50:65]
	v_mfma_f32_32x32x16_bf16 v[34:49], v[224:227], v[244:247], v[34:49]
	v_mfma_f32_32x32x16_bf16 v[18:33], v[224:227], v[228:231], v[18:33]
	ds_read_b128 v[224:227], v98 offset:18496
	ds_read_b128 v[228:231], v98 offset:23104
	ds_read_b128 v[232:235], v0 offset:55360
	ds_read_b128 v[236:239], v0 offset:59968
	s_waitcnt lgkmcnt(1)
	v_mfma_f32_32x32x16_bf16 v[2:17], v[224:227], v[232:235], v[2:17]
	s_waitcnt lgkmcnt(0)
	v_mfma_f32_32x32x16_bf16 v[50:65], v[224:227], v[236:239], v[50:65]
	v_mfma_f32_32x32x16_bf16 v[34:49], v[228:231], v[232:235], v[34:49]
	v_mfma_f32_32x32x16_bf16 v[18:33], v[228:231], v[236:239], v[18:33]
	ds_read_b128 v[224:227], v98 offset:18528
	ds_read_b128 v[228:231], v98 offset:23136
	ds_read_b128 v[232:235], v0 offset:55392
	ds_read_b128 v[236:239], v0 offset:60000
	s_waitcnt vmcnt(7)
	ds_write_b128 v99, v[94:97]
	s_waitcnt vmcnt(6)
	ds_write_b128 v99, v[90:93] offset:36864
	s_waitcnt vmcnt(5)
	ds_write_b128 v99, v[70:73] offset:4608
	s_waitcnt vmcnt(4)
	ds_write_b128 v99, v[74:77] offset:41472
	s_waitcnt vmcnt(3)
	ds_write_b128 v99, v[78:81] offset:9216
	s_waitcnt vmcnt(2)
	ds_write_b128 v99, v[82:85] offset:46080
	s_waitcnt vmcnt(1)
	ds_write_b128 v99, v[86:89] offset:13824
	s_waitcnt vmcnt(0)
	ds_write_b128 v99, v[66:69] offset:50688
	s_waitcnt lgkmcnt(0)
	s_barrier
	global_load_dwordx4 v[94:97], v[102:103], off offset:896
	global_load_dwordx4 v[90:93], v[100:101], off offset:896
	global_load_dwordx4 v[78:81], v[104:105], off offset:896
	global_load_dwordx4 v[82:85], v[106:107], off offset:896
	global_load_dwordx4 v[86:89], v[108:109], off offset:896
	global_load_dwordx4 v[66:69], v[110:111], off offset:896
	global_load_dwordx4 v[70:73], v[112:113], off offset:896
	global_load_dwordx4 v[74:77], v[114:115], off offset:896
	v_mfma_f32_32x32x16_bf16 v[2:17], v[224:227], v[232:235], v[2:17]
	v_mfma_f32_32x32x16_bf16 v[50:65], v[224:227], v[236:239], v[50:65]
	v_mfma_f32_32x32x16_bf16 v[34:49], v[228:231], v[232:235], v[34:49]
	v_mfma_f32_32x32x16_bf16 v[18:33], v[228:231], v[236:239], v[18:33]
	ds_read_b128 v[100:103], v98 offset:4608
	ds_read_b128 v[104:107], v0 offset:41472
	ds_read_b128 v[108:111], v98
	ds_read_b128 v[112:115], v98 offset:32
	ds_read_b128 v[224:227], v0 offset:36864
	ds_read_b128 v[228:231], v0 offset:36896
	s_waitcnt lgkmcnt(1)
	v_mfma_f32_32x32x16_bf16 v[2:17], v[108:111], v[224:227], v[2:17]
	v_mfma_f32_32x32x16_bf16 v[50:65], v[108:111], v[104:107], v[50:65]
	v_mfma_f32_32x32x16_bf16 v[34:49], v[100:103], v[224:227], v[34:49]
	v_mfma_f32_32x32x16_bf16 v[18:33], v[100:103], v[104:107], v[18:33]
	ds_read_b128 v[100:103], v98 offset:4640
	ds_read_b128 v[104:107], v0 offset:41504
	s_waitcnt lgkmcnt(2)
	v_mfma_f32_32x32x16_bf16 v[2:17], v[112:115], v[228:231], v[2:17]
	s_waitcnt lgkmcnt(0)
	v_mfma_f32_32x32x16_bf16 v[50:65], v[112:115], v[104:107], v[50:65]
	v_mfma_f32_32x32x16_bf16 v[34:49], v[100:103], v[228:231], v[34:49]
	v_mfma_f32_32x32x16_bf16 v[18:33], v[100:103], v[104:107], v[18:33]
	ds_read_b128 v[100:103], v98 offset:64
	ds_read_b128 v[104:107], v98 offset:4672
	ds_read_b128 v[108:111], v0 offset:36928
	ds_read_b128 v[112:115], v0 offset:41536
	s_waitcnt lgkmcnt(1)
	v_mfma_f32_32x32x16_bf16 v[2:17], v[100:103], v[108:111], v[2:17]
	s_waitcnt lgkmcnt(0)
	v_mfma_f32_32x32x16_bf16 v[50:65], v[100:103], v[112:115], v[50:65]
	v_mfma_f32_32x32x16_bf16 v[34:49], v[104:107], v[108:111], v[34:49]
	v_mfma_f32_32x32x16_bf16 v[18:33], v[104:107], v[112:115], v[18:33]
	ds_read_b128 v[100:103], v98 offset:96
	ds_read_b128 v[104:107], v98 offset:4704
	ds_read_b128 v[108:111], v0 offset:36960
	ds_read_b128 v[112:115], v0 offset:41568
	s_waitcnt vmcnt(7)
	ds_write_b128 v99, v[94:97] offset:18432
	s_waitcnt vmcnt(6)
	ds_write_b128 v99, v[90:93] offset:55296
	s_waitcnt vmcnt(5)
	ds_write_b128 v99, v[78:81] offset:23040
	s_waitcnt vmcnt(4)
	ds_write_b128 v99, v[82:85] offset:59904
	s_waitcnt vmcnt(3)
	ds_write_b128 v99, v[86:89] offset:27648
	s_waitcnt vmcnt(2)
	ds_write_b128 v99, v[66:69] offset:64512
	s_waitcnt vmcnt(1)
	ds_write_b128 v99, v[70:73] offset:32256
	s_waitcnt vmcnt(0)
	ds_write_b128 v222, v[74:77] offset:13824
	s_waitcnt lgkmcnt(0)
	s_barrier
	ds_read_b128 v[66:69], v98 offset:23040
	ds_read_b128 v[70:73], v0 offset:59904
	ds_read_b128 v[74:77], v98 offset:18432
	ds_read_b128 v[78:81], v98 offset:18464
	ds_read_b128 v[82:85], v0 offset:55296
	ds_read_b128 v[86:89], v0 offset:55328
	v_and_b32_e32 v92, 0xffff0000, v169
	v_mfma_f32_32x32x16_bf16 v[2:17], v[100:103], v[108:111], v[2:17]
	v_lshlrev_b32_e32 v96, 16, v206
	v_and_b32_e32 v99, 0xffff0000, v206
	v_mfma_f32_32x32x16_bf16 v[50:65], v[100:103], v[112:115], v[50:65]
	v_lshlrev_b32_e32 v100, 16, v207
	v_mfma_f32_32x32x16_bf16 v[34:49], v[104:107], v[108:111], v[34:49]
	v_and_b32_e32 v108, 0xffff0000, v209
	v_lshlrev_b32_e32 v110, 16, v210
	v_and_b32_e32 v111, 0xffff0000, v210
	v_mfma_f32_32x32x16_bf16 v[18:33], v[104:107], v[112:115], v[18:33]
	v_and_b32_e32 v104, 0xffff0000, v207
	v_lshlrev_b32_e32 v105, 16, v208
	v_and_b32_e32 v106, 0xffff0000, v208
	v_lshlrev_b32_e32 v107, 16, v209
	v_lshlrev_b32_e32 v112, 16, v211
	v_and_b32_e32 v114, 0xffff0000, v211
	s_waitcnt lgkmcnt(1)
	v_mfma_f32_32x32x16_bf16 v[2:17], v[74:77], v[82:85], v[2:17]
	v_mfma_f32_32x32x16_bf16 v[50:65], v[74:77], v[70:73], v[50:65]
	v_mfma_f32_32x32x16_bf16 v[34:49], v[66:69], v[82:85], v[34:49]
	v_and_b32_e32 v82, 0xffff0000, v171
	v_lshlrev_b32_e32 v83, 16, v170
	v_mfma_f32_32x32x16_bf16 v[18:33], v[66:69], v[70:73], v[18:33]
	ds_read_b128 v[66:69], v98 offset:23072
	ds_read_b128 v[70:73], v0 offset:59936
	s_waitcnt lgkmcnt(2)
	v_mfma_f32_32x32x16_bf16 v[2:17], v[78:81], v[86:89], v[2:17]
	s_waitcnt lgkmcnt(0)
	v_mfma_f32_32x32x16_bf16 v[50:65], v[78:81], v[70:73], v[50:65]
	v_mfma_f32_32x32x16_bf16 v[34:49], v[66:69], v[86:89], v[34:49]
	v_and_b32_e32 v86, 0xffff0000, v170
	v_lshlrev_b32_e32 v89, 16, v169
	v_mfma_f32_32x32x16_bf16 v[18:33], v[66:69], v[70:73], v[18:33]
	ds_read_b128 v[66:69], v98 offset:18496
	ds_read_b128 v[70:73], v98 offset:23104
	ds_read_b128 v[74:77], v0 offset:55360
	ds_read_b128 v[78:81], v0 offset:59968
	s_waitcnt lgkmcnt(1)
	v_mfma_f32_32x32x16_bf16 v[2:17], v[66:69], v[74:77], v[2:17]
	s_waitcnt lgkmcnt(0)
	v_mfma_f32_32x32x16_bf16 v[50:65], v[66:69], v[78:81], v[50:65]
	v_mfma_f32_32x32x16_bf16 v[34:49], v[70:73], v[74:77], v[34:49]
	v_mfma_f32_32x32x16_bf16 v[18:33], v[70:73], v[78:81], v[18:33]
	ds_read_b128 v[66:69], v98 offset:18528
	ds_read_b128 v[70:73], v98 offset:23136
	ds_read_b128 v[74:77], v0 offset:55392
	ds_read_b128 v[78:81], v0 offset:60000
	v_cvt_f32_ubyte0_e32 v0, v116
	v_mul_f32_e32 v0, 0x3b808081, v0
	v_lshlrev_b32_e32 v116, 16, v212
	s_waitcnt lgkmcnt(0)
	s_barrier
	v_mfma_f32_32x32x16_bf16 v[2:17], v[66:69], v[74:77], v[2:17]
	v_mfma_f32_32x32x16_bf16 v[50:65], v[66:69], v[78:81], v[50:65]
	v_cvt_f32_ubyte2_e32 v67, v117
	v_mul_f32_e32 v67, 0x3b808081, v67
	s_nop 8
	v_mul_f32_e32 v4, v67, v4
	v_cvt_f32_ubyte3_e32 v67, v117
	v_mul_f32_e32 v67, 0x3b808081, v67
	v_mul_f32_e32 v5, v67, v5
	v_cvt_f32_ubyte0_e32 v67, v119
	v_mul_f32_e32 v67, 0x3b808081, v67
	v_mul_f32_e32 v6, v67, v6
	v_cvt_f32_ubyte1_e32 v67, v121
	v_mul_f32_e32 v67, 0x3b808081, v67
	v_mul_f32_e32 v7, v67, v7
	v_cvt_f32_ubyte2_e32 v67, v120
	v_mul_f32_e32 v67, 0x3b808081, v67
	v_mul_f32_e32 v8, v67, v8
	v_cvt_f32_ubyte3_e32 v67, v120
	v_mul_f32_e32 v67, 0x3b808081, v67
	v_mul_f32_e32 v9, v67, v9
	v_cvt_f32_ubyte0_e32 v67, v122
	v_mul_f32_e32 v67, 0x3b808081, v67
	v_mul_f32_e32 v10, v67, v10
	v_cvt_f32_ubyte1_e32 v67, v124
	v_mul_f32_e32 v67, 0x3b808081, v67
	v_mul_f32_e32 v11, v67, v11
	v_cvt_f32_ubyte2_e32 v67, v123
	v_mul_f32_e32 v67, 0x3b808081, v67
	v_mul_f32_e32 v12, v67, v12
	v_cvt_f32_ubyte3_e32 v67, v123
	v_mul_f32_e32 v67, 0x3b808081, v67
	v_mul_f32_e32 v13, v67, v13
	v_cvt_f32_ubyte0_e32 v67, v125
	v_mul_f32_e32 v67, 0x3b808081, v67
	v_mul_f32_e32 v14, v67, v14
	v_cvt_f32_ubyte1_e32 v67, v127
	v_mul_f32_e32 v67, 0x3b808081, v67
	v_mul_f32_e32 v15, v67, v15
	v_cvt_f32_ubyte2_e32 v67, v126
	v_mul_f32_e32 v67, 0x3b808081, v67
	v_mul_f32_e32 v67, v67, v16
	v_cvt_f32_ubyte3_e32 v16, v126
	v_mul_f32_e32 v16, 0x3b808081, v16
	v_mul_f32_e32 v68, v16, v17
	v_cvt_f32_ubyte0_e32 v16, v128
	v_mul_f32_e32 v16, 0x3b808081, v16
	v_mul_f32_e32 v50, v16, v50
	v_cvt_f32_ubyte1_e32 v16, v130
	v_mul_f32_e32 v16, 0x3b808081, v16
	v_mul_f32_e32 v51, v16, v51
	v_cvt_f32_ubyte2_e32 v16, v129
	v_mul_f32_e32 v16, 0x3b808081, v16
	v_mul_f32_e32 v52, v16, v52
	v_cvt_f32_ubyte3_e32 v16, v129
	v_mul_f32_e32 v16, 0x3b808081, v16
	v_mul_f32_e32 v53, v16, v53
	v_cvt_f32_ubyte0_e32 v16, v131
	v_mul_f32_e32 v16, 0x3b808081, v16
	v_mul_f32_e32 v54, v16, v54
	v_cvt_f32_ubyte1_e32 v16, v133
	v_mul_f32_e32 v16, 0x3b808081, v16
	v_mul_f32_e32 v55, v16, v55
	v_cvt_f32_ubyte2_e32 v16, v132
	v_mul_f32_e32 v16, 0x3b808081, v16
	v_mul_f32_e32 v56, v16, v56
	v_cvt_f32_ubyte3_e32 v16, v132
	v_mul_f32_e32 v16, 0x3b808081, v16
	v_mul_f32_e32 v57, v16, v57
	v_cvt_f32_ubyte0_e32 v16, v134
	v_mul_f32_e32 v16, 0x3b808081, v16
	v_mul_f32_e32 v58, v16, v58
	v_cvt_f32_ubyte1_e32 v16, v136
	v_mul_f32_e32 v16, 0x3b808081, v16
	v_mul_f32_e32 v59, v16, v59
	v_cvt_f32_ubyte2_e32 v16, v135
	v_mul_f32_e32 v16, 0x3b808081, v16
	v_mul_f32_e32 v60, v16, v60
	v_cvt_f32_ubyte3_e32 v16, v135
	v_mul_f32_e32 v16, 0x3b808081, v16
	v_mul_f32_e32 v61, v16, v61
	v_cvt_f32_ubyte0_e32 v16, v137
	v_mul_f32_e32 v16, 0x3b808081, v16
	v_mfma_f32_32x32x16_bf16 v[34:49], v[70:73], v[74:77], v[34:49]
	v_mul_f32_e32 v62, v16, v62
	v_cvt_f32_ubyte1_e32 v16, v139
	v_mul_f32_e32 v16, 0x3b808081, v16
	v_mul_f32_e32 v63, v16, v63
	v_cvt_f32_ubyte2_e32 v16, v138
	v_mul_f32_e32 v16, 0x3b808081, v16
	v_mul_f32_e32 v64, v16, v64
	v_cvt_f32_ubyte3_e32 v16, v138
	v_mul_f32_e32 v16, 0x3b808081, v16
	v_mul_f32_e32 v65, v16, v65
	v_cvt_f32_ubyte0_e32 v16, v140
	v_mul_f32_e32 v16, 0x3b808081, v16
	v_mul_f32_e32 v34, v16, v34
	v_cvt_f32_ubyte1_e32 v16, v142
	v_mul_f32_e32 v16, 0x3b808081, v16
	v_mul_f32_e32 v35, v16, v35
	v_cvt_f32_ubyte2_e32 v16, v141
	v_mul_f32_e32 v16, 0x3b808081, v16
	v_mul_f32_e32 v36, v16, v36
	v_cvt_f32_ubyte3_e32 v16, v141
	v_mul_f32_e32 v16, 0x3b808081, v16
	v_mul_f32_e32 v37, v16, v37
	v_cvt_f32_ubyte0_e32 v16, v143
	v_mul_f32_e32 v16, 0x3b808081, v16
	v_mul_f32_e32 v38, v16, v38
	v_cvt_f32_ubyte1_e32 v16, v145
	v_mul_f32_e32 v16, 0x3b808081, v16
	v_mul_f32_e32 v39, v16, v39
	v_cvt_f32_ubyte2_e32 v16, v144
	v_mul_f32_e32 v16, 0x3b808081, v16
	v_mul_f32_e32 v40, v16, v40
	v_cvt_f32_ubyte3_e32 v16, v144
	v_mul_f32_e32 v16, 0x3b808081, v16
	v_mul_f32_e32 v69, v16, v41
	v_cvt_f32_ubyte0_e32 v16, v146
	v_mul_f32_e32 v16, 0x3b808081, v16
	v_mfma_f32_32x32x16_bf16 v[18:33], v[70:73], v[78:81], v[18:33]
	v_mul_f32_e32 v70, v16, v42
	v_cvt_f32_ubyte1_e32 v16, v148
	v_mul_f32_e32 v16, 0x3b808081, v16
	v_mul_f32_e32 v76, v16, v43
	v_cvt_f32_ubyte2_e32 v16, v147
	v_mul_f32_e32 v16, 0x3b808081, v16
	v_mul_f32_e32 v78, v16, v44
	v_cvt_f32_ubyte3_e32 v16, v147
	v_mul_f32_e32 v16, 0x3b808081, v16
	v_mul_f32_e32 v81, v16, v45
	v_cvt_f32_ubyte0_e32 v16, v149
	v_mul_f32_e32 v16, 0x3b808081, v16
	v_mul_f32_e32 v93, v16, v46
	v_cvt_f32_ubyte1_e32 v16, v151
	v_mul_f32_e32 v16, 0x3b808081, v16
	v_mul_f32_e32 v101, v16, v47
	v_cvt_f32_ubyte2_e32 v16, v150
	v_mul_f32_e32 v16, 0x3b808081, v16
	v_mul_f32_e32 v109, v16, v48
	v_cvt_f32_ubyte3_e32 v16, v150
	v_mul_f32_e32 v16, 0x3b808081, v16
	v_mul_f32_e32 v113, v16, v49
	v_cvt_f32_ubyte0_e32 v16, v152
	v_mul_f32_e32 v16, 0x3b808081, v16
	v_mul_f32_e32 v115, v16, v18
	v_cvt_f32_ubyte1_e32 v16, v154
	v_mul_f32_e32 v16, 0x3b808081, v16
	v_mul_f32_e32 v117, v16, v19
	v_cvt_f32_ubyte2_e32 v16, v153
	v_mul_f32_e32 v16, 0x3b808081, v16
	v_cvt_f32_ubyte1_e32 v66, v118
	v_mul_f32_e32 v118, v16, v20
	v_cvt_f32_ubyte3_e32 v16, v153
	v_mul_f32_e32 v16, 0x3b808081, v16
	v_mul_f32_e32 v119, v16, v21
	v_cvt_f32_ubyte0_e32 v16, v155
	v_mul_f32_e32 v16, 0x3b808081, v16
	v_mul_f32_e32 v120, v16, v22
	v_cvt_f32_ubyte1_e32 v16, v157
	v_mul_f32_e32 v16, 0x3b808081, v16
	v_mul_f32_e32 v122, v16, v23
	v_cvt_f32_ubyte2_e32 v16, v156
	v_mul_f32_e32 v16, 0x3b808081, v16
	v_mul_f32_e32 v123, v16, v24
	v_cvt_f32_ubyte3_e32 v16, v156
	v_mul_f32_e32 v16, 0x3b808081, v16
	v_mul_f32_e32 v124, v16, v25
	v_cvt_f32_ubyte0_e32 v16, v158
	v_mul_f32_e32 v16, 0x3b808081, v16
	v_mul_f32_e32 v125, v16, v26
	v_cvt_f32_ubyte1_e32 v16, v160
	v_mul_f32_e32 v16, 0x3b808081, v16
	v_mul_f32_e32 v127, v16, v27
	v_cvt_f32_ubyte2_e32 v16, v159
	v_mul_f32_e32 v16, 0x3b808081, v16
	v_mul_f32_e32 v128, v16, v28
	v_cvt_f32_ubyte3_e32 v16, v159
	v_mul_f32_e32 v16, 0x3b808081, v16
	v_mul_f32_e32 v129, v16, v29
	v_cvt_f32_ubyte0_e32 v16, v161
	v_mul_f32_e32 v16, 0x3b808081, v16
	v_mul_f32_e32 v130, v16, v30
	v_cvt_f32_ubyte1_e32 v16, v163
	v_mul_f32_e32 v16, 0x3b808081, v16
	v_mul_f32_e32 v132, v16, v31
	v_cvt_f32_ubyte2_e32 v16, v162
	v_mul_f32_e32 v16, 0x3b808081, v16
	v_mul_f32_e32 v133, v16, v32
	v_cvt_f32_ubyte3_e32 v16, v162
	v_mul_f32_e32 v16, 0x3b808081, v16
	v_mul_f32_e32 v66, 0x3b808081, v66
	v_mul_f32_e32 v134, v16, v33
	v_lshlrev_b32_e32 v16, 16, v205
	v_and_b32_e32 v17, 0xffff0000, v205
	v_lshlrev_b32_e32 v18, 16, v204
	v_and_b32_e32 v19, 0xffff0000, v204
	v_lshlrev_b32_e32 v20, 16, v203
	v_and_b32_e32 v21, 0xffff0000, v203
	v_lshlrev_b32_e32 v22, 16, v202
	v_and_b32_e32 v23, 0xffff0000, v202
	v_lshlrev_b32_e32 v24, 16, v201
	v_and_b32_e32 v25, 0xffff0000, v201
	v_lshlrev_b32_e32 v28, 16, v200
	v_and_b32_e32 v31, 0xffff0000, v200
	v_lshlrev_b32_e32 v41, 16, v199
	v_and_b32_e32 v44, 0xffff0000, v199
	v_lshlrev_b32_e32 v45, 16, v177
	v_and_b32_e32 v46, 0xffff0000, v177
	v_lshlrev_b32_e32 v47, 16, v176
	v_and_b32_e32 v48, 0xffff0000, v176
	v_lshlrev_b32_e32 v49, 16, v175
	v_and_b32_e32 v71, 0xffff0000, v175
	v_lshlrev_b32_e32 v72, 16, v174
	v_and_b32_e32 v73, 0xffff0000, v174
	v_lshlrev_b32_e32 v74, 16, v173
	v_and_b32_e32 v75, 0xffff0000, v173
	v_lshlrev_b32_e32 v77, 16, v172
	v_and_b32_e32 v79, 0xffff0000, v172
	v_lshlrev_b32_e32 v80, 16, v171
	v_and_b32_e32 v121, 0xffff0000, v212
	v_lshlrev_b32_e32 v126, 16, v213
	v_and_b32_e32 v131, 0xffff0000, v213
	v_lshlrev_b32_e32 v135, 16, v214
	v_and_b32_e32 v136, 0xffff0000, v214
	v_lshlrev_b32_e32 v137, 16, v215
	v_and_b32_e32 v138, 0xffff0000, v215
	v_lshlrev_b32_e32 v139, 16, v216
	v_and_b32_e32 v140, 0xffff0000, v216
	v_lshlrev_b32_e32 v141, 16, v217
	v_and_b32_e32 v142, 0xffff0000, v217
	v_lshlrev_b32_e32 v143, 16, v218
	v_and_b32_e32 v144, 0xffff0000, v218
	v_lshlrev_b32_e32 v145, 16, v219
	v_and_b32_e32 v146, 0xffff0000, v219
	v_lshlrev_b32_e32 v147, 16, v220
	v_and_b32_e32 v148, 0xffff0000, v220
	v_lshlrev_b32_e32 v149, 16, v221
	v_and_b32_e32 v150, 0xffff0000, v221
	v_fmac_f32_e32 v16, v0, v2
	v_fmac_f32_e32 v17, v66, v3
	v_add_f32_e32 v42, v4, v18
	v_add_f32_e32 v43, v5, v19
	v_add_f32_e32 v32, v6, v20
	v_add_f32_e32 v33, v7, v21
	v_add_f32_e32 v29, v8, v22
	v_add_f32_e32 v30, v9, v23
	v_add_f32_e32 v26, v10, v24
	v_add_f32_e32 v27, v11, v25
	v_add_f32_e32 v23, v12, v28
	v_add_f32_e32 v24, v13, v31
	v_add_f32_e32 v21, v14, v41
	v_add_f32_e32 v20, v15, v44
	v_add_f32_e32 v19, v67, v45
	v_add_f32_e32 v18, v68, v46
	v_add_f32_e32 v102, v50, v47
	v_add_f32_e32 v103, v51, v48
	v_add_f32_e32 v97, v52, v49
	v_add_f32_e32 v98, v53, v71
	v_add_f32_e32 v94, v54, v72
	v_add_f32_e32 v95, v55, v73
	v_add_f32_e32 v90, v56, v74
	v_add_f32_e32 v91, v57, v75
	v_add_f32_e32 v87, v58, v77
	v_add_f32_e32 v88, v59, v79
	v_add_f32_e32 v84, v60, v80
	v_add_f32_e32 v85, v61, v82
	v_add_f32_e32 v82, v62, v83
	v_add_f32_e32 v80, v63, v86
	v_add_f32_e32 v79, v64, v89
	v_add_f32_e32 v77, v65, v92
	v_add_f32_e32 v75, v34, v96
	v_add_f32_e32 v73, v35, v99
	v_add_f32_e32 v74, v36, v100
	v_add_f32_e32 v72, v37, v104
	v_add_f32_e32 v71, v38, v105
	v_add_f32_e32 v48, v39, v106
	v_add_f32_e32 v49, v40, v107
	v_add_f32_e32 v47, v69, v108
	v_add_f32_e32 v46, v70, v110
	v_add_f32_e32 v44, v76, v111
	v_add_f32_e32 v45, v78, v112
	v_add_f32_e32 v41, v81, v114
	v_add_f32_e32 v31, v93, v116
	v_add_f32_e32 v28, v101, v121
	v_add_f32_e32 v25, v109, v126
	v_add_f32_e32 v22, v113, v131
	v_add_f32_e32 v114, v115, v135
	v_add_f32_e32 v111, v117, v136
	v_add_f32_e32 v112, v118, v137
	v_add_f32_e32 v110, v119, v138
	v_add_f32_e32 v108, v120, v139
	v_add_f32_e32 v106, v122, v140
	v_add_f32_e32 v107, v123, v141
	v_add_f32_e32 v105, v124, v142
	v_add_f32_e32 v104, v125, v143
	v_add_f32_e32 v99, v127, v144
	v_add_f32_e32 v100, v128, v145
	v_add_f32_e32 v96, v129, v146
	v_add_f32_e32 v92, v130, v147
	v_add_f32_e32 v89, v132, v148
	v_add_f32_e32 v86, v133, v149
	v_add_f32_e32 v83, v134, v150
	s_cbranch_scc1 .LBB0_857
	v_mul_f32_e32 v0, v0, v2
	v_mul_f32_e32 v2, v66, v3
	v_cndmask_b32_e32 v0, v16, v0, vcc
	v_cndmask_b32_e32 v2, v17, v2, vcc
	v_cvt_pk_bf16_f32 v116, v0, v2
	v_cndmask_b32_e32 v0, v42, v4, vcc
	v_cndmask_b32_e32 v2, v43, v5, vcc
	v_cvt_pk_bf16_f32 v121, v0, v2
	v_cndmask_b32_e32 v0, v32, v6, vcc
	v_cndmask_b32_e32 v2, v33, v7, vcc
	v_cvt_pk_bf16_f32 v126, v0, v2
	v_cndmask_b32_e32 v0, v29, v8, vcc
	v_cndmask_b32_e32 v2, v30, v9, vcc
	v_cvt_pk_bf16_f32 v131, v0, v2
	v_cndmask_b32_e32 v0, v26, v10, vcc
	v_cndmask_b32_e32 v2, v27, v11, vcc
	v_cvt_pk_bf16_f32 v135, v0, v2
	v_cndmask_b32_e32 v0, v23, v12, vcc
	v_cndmask_b32_e32 v2, v24, v13, vcc
	v_cvt_pk_bf16_f32 v136, v0, v2
	v_cndmask_b32_e32 v0, v21, v14, vcc
	v_cndmask_b32_e32 v2, v20, v15, vcc
	v_cvt_pk_bf16_f32 v137, v0, v2
	v_cndmask_b32_e32 v0, v19, v67, vcc
	v_cndmask_b32_e32 v2, v18, v68, vcc
	v_cvt_pk_bf16_f32 v138, v0, v2
	v_cndmask_b32_e32 v0, v102, v50, vcc
	v_cndmask_b32_e32 v2, v103, v51, vcc
	v_cvt_pk_bf16_f32 v155, v0, v2
	v_cndmask_b32_e32 v0, v97, v52, vcc
	v_cndmask_b32_e32 v2, v98, v53, vcc
	v_cvt_pk_bf16_f32 v156, v0, v2
	v_cndmask_b32_e32 v0, v94, v54, vcc
	v_cndmask_b32_e32 v2, v95, v55, vcc
	v_cvt_pk_bf16_f32 v157, v0, v2
	v_cndmask_b32_e32 v0, v90, v56, vcc
	v_cndmask_b32_e32 v2, v91, v57, vcc
	v_cvt_pk_bf16_f32 v158, v0, v2
	v_cndmask_b32_e32 v0, v87, v58, vcc
	v_cndmask_b32_e32 v2, v88, v59, vcc
	v_cvt_pk_bf16_f32 v159, v0, v2
	v_cndmask_b32_e32 v0, v84, v60, vcc
	v_cndmask_b32_e32 v2, v85, v61, vcc
	v_cvt_pk_bf16_f32 v160, v0, v2
	v_cndmask_b32_e32 v0, v82, v62, vcc
	v_cndmask_b32_e32 v2, v80, v63, vcc
	v_cvt_pk_bf16_f32 v161, v0, v2
	v_cndmask_b32_e32 v0, v79, v64, vcc
	v_cndmask_b32_e32 v2, v77, v65, vcc
	v_cvt_pk_bf16_f32 v162, v0, v2
	v_cndmask_b32_e32 v0, v75, v34, vcc
	v_cndmask_b32_e32 v2, v73, v35, vcc
	v_cvt_pk_bf16_f32 v154, v0, v2
	v_cndmask_b32_e32 v0, v74, v36, vcc
	v_cndmask_b32_e32 v2, v72, v37, vcc
	v_cvt_pk_bf16_f32 v153, v0, v2
	v_cndmask_b32_e32 v0, v71, v38, vcc
	v_cndmask_b32_e32 v2, v48, v39, vcc
	v_cvt_pk_bf16_f32 v152, v0, v2
	v_cndmask_b32_e32 v0, v49, v40, vcc
	v_cndmask_b32_e32 v2, v47, v69, vcc
	v_cvt_pk_bf16_f32 v151, v0, v2
	v_cndmask_b32_e32 v0, v46, v70, vcc
	v_cndmask_b32_e32 v2, v44, v76, vcc
	v_cvt_pk_bf16_f32 v150, v0, v2
	v_cndmask_b32_e32 v0, v45, v78, vcc
	v_cndmask_b32_e32 v2, v41, v81, vcc
	v_cvt_pk_bf16_f32 v149, v0, v2
	v_cndmask_b32_e32 v0, v31, v93, vcc
	v_cndmask_b32_e32 v2, v28, v101, vcc
	v_cvt_pk_bf16_f32 v148, v0, v2
	v_cndmask_b32_e32 v0, v25, v109, vcc
	v_cndmask_b32_e32 v2, v22, v113, vcc
	v_cvt_pk_bf16_f32 v147, v0, v2
	v_cndmask_b32_e32 v0, v114, v115, vcc
	v_cndmask_b32_e32 v2, v111, v117, vcc
	v_cvt_pk_bf16_f32 v146, v0, v2
	v_cndmask_b32_e32 v0, v112, v118, vcc
	v_cndmask_b32_e32 v2, v110, v119, vcc
	v_cvt_pk_bf16_f32 v145, v0, v2
	v_cndmask_b32_e32 v0, v108, v120, vcc
	v_cndmask_b32_e32 v2, v106, v122, vcc
	v_cvt_pk_bf16_f32 v144, v0, v2
	v_cndmask_b32_e32 v0, v107, v123, vcc
	v_cndmask_b32_e32 v2, v105, v124, vcc
	v_cvt_pk_bf16_f32 v143, v0, v2
	v_cndmask_b32_e32 v0, v104, v125, vcc
	v_cndmask_b32_e32 v2, v99, v127, vcc
	v_cvt_pk_bf16_f32 v142, v0, v2
	v_cndmask_b32_e32 v0, v100, v128, vcc
	v_cndmask_b32_e32 v2, v96, v129, vcc
	v_cvt_pk_bf16_f32 v141, v0, v2
	v_cndmask_b32_e32 v0, v92, v130, vcc
	v_cndmask_b32_e32 v2, v89, v132, vcc
	v_cvt_pk_bf16_f32 v140, v0, v2
	v_cndmask_b32_e32 v0, v86, v133, vcc
	v_cndmask_b32_e32 v2, v83, v134, vcc
	v_cvt_pk_bf16_f32 v139, v0, v2
	s_mov_b64 s[0:1], 0

.LBB0_909:
	s_lshl_b32 s0, s13, 3
	s_and_b32 s0, s0, 56
	s_bfe_u32 s1, s13, 0x30003
	s_or_b32 s20, s0, s1
	s_lshl_b32 s0, s13, 1
	s_and_b32 s0, s0, 0xffffff80
	s_lshl_b32 s1, s20, 18
	v_readlane_b32 s22, v251, 37
	s_waitcnt vmcnt(12)
	v_mov_b32_e32 v36, v178
	v_readlane_b32 s23, v251, 38
	s_add_u32 s22, s22, s1
	s_addc_u32 s23, s23, 0
	v_ashrrev_i32_e32 v34, 3, v36
	s_ashr_i32 s1, s0, 31
	v_lshlrev_b32_e32 v0, 3, v36
	v_ashrrev_i32_e32 v35, 31, v34
	s_lshl_b64 s[24:25], s[0:1], 11
	v_and_b32_e32 v37, 56, v0
	s_waitcnt vmcnt(5)
	v_lshlrev_b64 v[2:3], 11, v[34:35]
	s_add_u32 s24, s68, s24
	v_lshl_add_u64 v[4:5], s[22:23], 0, v[2:3]
	v_lshlrev_b32_e32 v0, 1, v37
	s_addc_u32 s25, s69, s25
	v_lshl_add_u64 v[68:69], v[4:5], 0, v[0:1]
	v_lshl_add_u64 v[2:3], s[24:25], 0, v[2:3]
	v_lshl_add_u64 v[70:71], v[2:3], 0, v[0:1]
	v_and_b32_e32 v0, 7, v36
	v_bfe_u32 v66, v36, 4, 3
	v_xor_b32_e32 v66, v66, v0
	v_sub_u32_e32 v66, v66, v0
	v_lshlrev_b32_e32 v66, 4, v66
	v_ashrrev_i32_e32 v67, 31, v66
	v_lshl_add_u64 v[68:69], v[68:69], 0, v[66:67]
	v_lshl_add_u64 v[70:71], v[70:71], 0, v[66:67]
	v_add_co_u32_e32 v72, vcc, s73, v68
	s_nop 1
	v_addc_co_u32_e32 v73, vcc, 0, v69, vcc
	v_add_co_u32_e32 v74, vcc, s73, v70
	s_nop 1
	v_addc_co_u32_e32 v75, vcc, 0, v71, vcc
	v_add_co_u32_e32 v76, vcc, s52, v68
	s_nop 1
	v_addc_co_u32_e32 v77, vcc, 0, v69, vcc
	v_add_co_u32_e32 v78, vcc, s52, v70
	s_nop 1
	v_addc_co_u32_e32 v79, vcc, 0, v71, vcc
	v_add_co_u32_e32 v80, vcc, s53, v68
	s_nop 1
	v_addc_co_u32_e32 v81, vcc, 0, v69, vcc
	v_add_co_u32_e32 v82, vcc, s53, v70
	s_nop 1
	v_addc_co_u32_e32 v83, vcc, 0, v71, vcc
	v_and_b32_e32 v0, 31, v36
	v_bfe_u32 v66, v36, 5, 1
	v_bfe_u32 v67, v36, 1, 3
	v_xor_b32_e32 v66, v66, v67
	v_lshlrev_b32_e32 v66, 4, v66
	v_lshl_add_u32 v66, v0, 7, v66
	v_bfe_u32 v67, v36, 7, 1
	v_lshl_add_u32 v86, v67, 13, v66
	v_bfe_u32 v67, v36, 6, 1
	v_lshl_add_u32 v90, v67, 13, v66
	v_add_u32_e32 v90, 0x4000, v90
	v_xor_b32_e32 v87, 32, v86
	v_xor_b32_e32 v91, 32, v90
	v_xor_b32_e32 v88, 64, v86
	v_xor_b32_e32 v92, 64, v90
	v_xor_b32_e32 v89, 96, v86
	v_xor_b32_e32 v93, 96, v90
	v_lshrrev_b32_e32 v66, 6, v36
	v_lshlrev_b32_e32 v66, 10, v66
	s_nop 1
	v_readfirstlane_b32 s14, v66
	s_mov_b32 s21, 0
	s_lshl_b32 s20, s20, 7
	v_readlane_b32 s15, v251, 0
	s_cmpk_lt_u32 s15, 0x100
	s_cbranch_scc1 .Lgp_g2
	s_setprio 1
.Lgp_g2:
	s_add_u32 m0, s14, 0x800
	s_nop 0
	global_load_lds_dwordx4 v[68:69], off
	s_add_u32 m0, s14, 0x1800
	s_nop 0
	global_load_lds_dwordx4 v[72:73], off
	s_add_u32 m0, s14, 0x2800
	s_nop 0
	global_load_lds_dwordx4 v[76:77], off
	s_add_u32 m0, s14, 0x3800
	s_nop 0
	global_load_lds_dwordx4 v[80:81], off
	s_add_u32 m0, s14, 0x4800
	s_nop 0
	global_load_lds_dwordx4 v[70:71], off
	s_add_u32 m0, s14, 0x5800
	s_nop 0
	global_load_lds_dwordx4 v[74:75], off
	s_add_u32 m0, s14, 0x6800
	s_nop 0
	global_load_lds_dwordx4 v[78:79], off
	s_add_u32 m0, s14, 0x7800
	s_nop 0
	global_load_lds_dwordx4 v[82:83], off
	s_add_u32 m0, s14, 0x8780
	s_nop 0
	global_load_lds_dwordx4 v[68:69], off offset:128
	s_add_u32 m0, s14, 0x9780
	s_nop 0
	global_load_lds_dwordx4 v[72:73], off offset:128
	s_add_u32 m0, s14, 0xa780
	s_nop 0
	global_load_lds_dwordx4 v[76:77], off offset:128
	s_add_u32 m0, s14, 0xb780
	s_nop 0
	global_load_lds_dwordx4 v[80:81], off offset:128
	s_add_u32 m0, s14, 0xc780
	s_nop 0
	global_load_lds_dwordx4 v[70:71], off offset:128
	s_add_u32 m0, s14, 0xd780
	s_nop 0
	global_load_lds_dwordx4 v[74:75], off offset:128
	s_add_u32 m0, s14, 0xe780
	s_nop 0
	global_load_lds_dwordx4 v[78:79], off offset:128
	s_add_u32 m0, s14, 0xf780
	s_nop 0
	global_load_lds_dwordx4 v[82:83], off offset:128
	s_waitcnt vmcnt(8)
	s_barrier
	ds_read_b128 v[94:97], v86 offset:2048
	ds_read_b128 v[98:101], v86 offset:6144
	ds_read_b128 v[102:105], v90 offset:2048
	ds_read_b128 v[106:109], v90 offset:6144
	ds_read_b128 v[110:113], v87 offset:2048
	ds_read_b128 v[114:117], v87 offset:6144
	ds_read_b128 v[118:121], v91 offset:2048
	ds_read_b128 v[122:125], v91 offset:6144
	ds_read_b128 v[126:129], v88 offset:2048
	ds_read_b128 v[130:133], v88 offset:6144
	ds_read_b128 v[134:137], v92 offset:2048
	ds_read_b128 v[138:141], v92 offset:6144
	ds_read_b128 v[142:145], v89 offset:2048
	ds_read_b128 v[146:149], v89 offset:6144
	ds_read_b128 v[150:153], v93 offset:2048
	ds_read_b128 v[154:157], v93 offset:6144
	s_waitcnt lgkmcnt(0)
	s_barrier
	s_add_u32 m0, s14, 0x700
	s_nop 0
	global_load_lds_dwordx4 v[68:69], off offset:256
	s_add_u32 m0, s14, 0x1700
	s_nop 0
	global_load_lds_dwordx4 v[72:73], off offset:256
	s_add_u32 m0, s14, 0x2700
	s_nop 0
	global_load_lds_dwordx4 v[76:77], off offset:256
	s_add_u32 m0, s14, 0x3700
	s_nop 0
	global_load_lds_dwordx4 v[80:81], off offset:256
	s_add_u32 m0, s14, 0x4700
	s_nop 0
	global_load_lds_dwordx4 v[70:71], off offset:256
	s_add_u32 m0, s14, 0x5700
	s_nop 0
	global_load_lds_dwordx4 v[74:75], off offset:256
	s_add_u32 m0, s14, 0x6700
	s_nop 0
	global_load_lds_dwordx4 v[78:79], off offset:256
	s_add_u32 m0, s14, 0x7700
	s_nop 0
	global_load_lds_dwordx4 v[82:83], off offset:256
	v_mfma_f32_32x32x16_bf16 v[34:49], v[94:97], v[102:105], 0
	v_mfma_f32_32x32x16_bf16 v[50:65], v[94:97], v[106:109], 0
	v_mfma_f32_32x32x16_bf16 v[2:17], v[98:101], v[102:105], 0
	v_mfma_f32_32x32x16_bf16 v[18:33], v[98:101], v[106:109], 0
	s_waitcnt vmcnt(8)
	s_barrier
	ds_read_b128 v[94:97], v86 offset:34816
	ds_read_b128 v[98:101], v86 offset:38912
	ds_read_b128 v[102:105], v90 offset:34816
	ds_read_b128 v[106:109], v90 offset:38912
	v_mfma_f32_32x32x16_bf16 v[34:49], v[110:113], v[118:121], v[34:49]
	v_mfma_f32_32x32x16_bf16 v[50:65], v[110:113], v[122:125], v[50:65]
	v_mfma_f32_32x32x16_bf16 v[2:17], v[114:117], v[118:121], v[2:17]
	v_mfma_f32_32x32x16_bf16 v[18:33], v[114:117], v[122:125], v[18:33]
	ds_read_b128 v[110:113], v87 offset:34816
	ds_read_b128 v[114:117], v87 offset:38912
	ds_read_b128 v[118:121], v91 offset:34816
	ds_read_b128 v[122:125], v91 offset:38912
	v_mfma_f32_32x32x16_bf16 v[34:49], v[126:129], v[134:137], v[34:49]
	v_mfma_f32_32x32x16_bf16 v[50:65], v[126:129], v[138:141], v[50:65]
	v_mfma_f32_32x32x16_bf16 v[2:17], v[130:133], v[134:137], v[2:17]
	v_mfma_f32_32x32x16_bf16 v[18:33], v[130:133], v[138:141], v[18:33]
	ds_read_b128 v[126:129], v88 offset:34816
	ds_read_b128 v[130:133], v88 offset:38912
	ds_read_b128 v[134:137], v92 offset:34816
	ds_read_b128 v[138:141], v92 offset:38912
	v_mfma_f32_32x32x16_bf16 v[34:49], v[142:145], v[150:153], v[34:49]
	v_mfma_f32_32x32x16_bf16 v[50:65], v[142:145], v[154:157], v[50:65]
	v_mfma_f32_32x32x16_bf16 v[2:17], v[146:149], v[150:153], v[2:17]
	v_mfma_f32_32x32x16_bf16 v[18:33], v[146:149], v[154:157], v[18:33]
	ds_read_b128 v[142:145], v89 offset:34816
	ds_read_b128 v[146:149], v89 offset:38912
	ds_read_b128 v[150:153], v93 offset:34816
	ds_read_b128 v[154:157], v93 offset:38912
	s_waitcnt lgkmcnt(0)
	s_barrier
	v_mfma_f32_32x32x16_bf16 v[34:49], v[94:97], v[102:105], v[34:49]
	s_add_u32 m0, s14, 0x8680
	s_nop 0
	global_load_lds_dwordx4 v[68:69], off offset:384
	s_add_u32 m0, s14, 0x9680
	s_nop 0
	global_load_lds_dwordx4 v[72:73], off offset:384
	v_mfma_f32_32x32x16_bf16 v[50:65], v[94:97], v[106:109], v[50:65]
	s_add_u32 m0, s14, 0xa680
	s_nop 0
	global_load_lds_dwordx4 v[76:77], off offset:384
	s_add_u32 m0, s14, 0xb680
	s_nop 0
	global_load_lds_dwordx4 v[80:81], off offset:384
	v_mfma_f32_32x32x16_bf16 v[2:17], v[98:101], v[102:105], v[2:17]
	s_add_u32 m0, s14, 0xc680
	s_nop 0
	global_load_lds_dwordx4 v[70:71], off offset:384
	s_add_u32 m0, s14, 0xd680
	s_nop 0
	global_load_lds_dwordx4 v[74:75], off offset:384
	v_mfma_f32_32x32x16_bf16 v[18:33], v[98:101], v[106:109], v[18:33]
	s_add_u32 m0, s14, 0xe680
	s_nop 0
	global_load_lds_dwordx4 v[78:79], off offset:384
	s_add_u32 m0, s14, 0xf680
	s_nop 0
	global_load_lds_dwordx4 v[82:83], off offset:384
	s_waitcnt vmcnt(8)
	s_barrier
	ds_read_b128 v[94:97], v86 offset:2048
	ds_read_b128 v[98:101], v86 offset:6144
	ds_read_b128 v[102:105], v90 offset:2048
	ds_read_b128 v[106:109], v90 offset:6144
	v_mfma_f32_32x32x16_bf16 v[34:49], v[110:113], v[118:121], v[34:49]
	v_mfma_f32_32x32x16_bf16 v[50:65], v[110:113], v[122:125], v[50:65]
	v_mfma_f32_32x32x16_bf16 v[2:17], v[114:117], v[118:121], v[2:17]
	v_mfma_f32_32x32x16_bf16 v[18:33], v[114:117], v[122:125], v[18:33]
	ds_read_b128 v[110:113], v87 offset:2048
	ds_read_b128 v[114:117], v87 offset:6144
	ds_read_b128 v[118:121], v91 offset:2048
	ds_read_b128 v[122:125], v91 offset:6144
	v_mfma_f32_32x32x16_bf16 v[34:49], v[126:129], v[134:137], v[34:49]
	v_mfma_f32_32x32x16_bf16 v[50:65], v[126:129], v[138:141], v[50:65]
	v_mfma_f32_32x32x16_bf16 v[2:17], v[130:133], v[134:137], v[2:17]
	v_mfma_f32_32x32x16_bf16 v[18:33], v[130:133], v[138:141], v[18:33]
	ds_read_b128 v[126:129], v88 offset:2048
	ds_read_b128 v[130:133], v88 offset:6144
	ds_read_b128 v[134:137], v92 offset:2048
	ds_read_b128 v[138:141], v92 offset:6144
	v_mfma_f32_32x32x16_bf16 v[34:49], v[142:145], v[150:153], v[34:49]
	v_mfma_f32_32x32x16_bf16 v[50:65], v[142:145], v[154:157], v[50:65]
	v_mfma_f32_32x32x16_bf16 v[2:17], v[146:149], v[150:153], v[2:17]
	v_mfma_f32_32x32x16_bf16 v[18:33], v[146:149], v[154:157], v[18:33]
	ds_read_b128 v[142:145], v89 offset:2048
	ds_read_b128 v[146:149], v89 offset:6144
	ds_read_b128 v[150:153], v93 offset:2048
	ds_read_b128 v[154:157], v93 offset:6144
	s_waitcnt lgkmcnt(0)
	s_barrier
	v_mfma_f32_32x32x16_bf16 v[34:49], v[94:97], v[102:105], v[34:49]
	s_add_u32 m0, s14, 0x600
	s_nop 0
	global_load_lds_dwordx4 v[68:69], off offset:512
	s_add_u32 m0, s14, 0x1600
	s_nop 0
	global_load_lds_dwordx4 v[72:73], off offset:512
	v_mfma_f32_32x32x16_bf16 v[50:65], v[94:97], v[106:109], v[50:65]
	s_add_u32 m0, s14, 0x2600
	s_nop 0
	global_load_lds_dwordx4 v[76:77], off offset:512
	s_add_u32 m0, s14, 0x3600
	s_nop 0
	global_load_lds_dwordx4 v[80:81], off offset:512
	v_mfma_f32_32x32x16_bf16 v[2:17], v[98:101], v[102:105], v[2:17]
	s_add_u32 m0, s14, 0x4600
	s_nop 0
	global_load_lds_dwordx4 v[70:71], off offset:512
	s_add_u32 m0, s14, 0x5600
	s_nop 0
	global_load_lds_dwordx4 v[74:75], off offset:512
	v_mfma_f32_32x32x16_bf16 v[18:33], v[98:101], v[106:109], v[18:33]
	s_add_u32 m0, s14, 0x6600
	s_nop 0
	global_load_lds_dwordx4 v[78:79], off offset:512
	s_add_u32 m0, s14, 0x7600
	s_nop 0
	global_load_lds_dwordx4 v[82:83], off offset:512
	s_waitcnt vmcnt(8)
	s_barrier
	ds_read_b128 v[94:97], v86 offset:34816
	ds_read_b128 v[98:101], v86 offset:38912
	ds_read_b128 v[102:105], v90 offset:34816
	ds_read_b128 v[106:109], v90 offset:38912
	v_mfma_f32_32x32x16_bf16 v[34:49], v[110:113], v[118:121], v[34:49]
	v_mfma_f32_32x32x16_bf16 v[50:65], v[110:113], v[122:125], v[50:65]
	v_mfma_f32_32x32x16_bf16 v[2:17], v[114:117], v[118:121], v[2:17]
	v_mfma_f32_32x32x16_bf16 v[18:33], v[114:117], v[122:125], v[18:33]
	ds_read_b128 v[110:113], v87 offset:34816
	ds_read_b128 v[114:117], v87 offset:38912
	ds_read_b128 v[118:121], v91 offset:34816
	ds_read_b128 v[122:125], v91 offset:38912
	v_mfma_f32_32x32x16_bf16 v[34:49], v[126:129], v[134:137], v[34:49]
	v_mfma_f32_32x32x16_bf16 v[50:65], v[126:129], v[138:141], v[50:65]
	v_mfma_f32_32x32x16_bf16 v[2:17], v[130:133], v[134:137], v[2:17]
	v_mfma_f32_32x32x16_bf16 v[18:33], v[130:133], v[138:141], v[18:33]
	ds_read_b128 v[126:129], v88 offset:34816
	ds_read_b128 v[130:133], v88 offset:38912
	ds_read_b128 v[134:137], v92 offset:34816
	ds_read_b128 v[138:141], v92 offset:38912
	v_mfma_f32_32x32x16_bf16 v[34:49], v[142:145], v[150:153], v[34:49]
	v_mfma_f32_32x32x16_bf16 v[50:65], v[142:145], v[154:157], v[50:65]
	v_mfma_f32_32x32x16_bf16 v[2:17], v[146:149], v[150:153], v[2:17]
	v_mfma_f32_32x32x16_bf16 v[18:33], v[146:149], v[154:157], v[18:33]
	ds_read_b128 v[142:145], v89 offset:34816
	ds_read_b128 v[146:149], v89 offset:38912
	ds_read_b128 v[150:153], v93 offset:34816
	ds_read_b128 v[154:157], v93 offset:38912
	s_waitcnt lgkmcnt(0)
	s_barrier
	v_mfma_f32_32x32x16_bf16 v[34:49], v[94:97], v[102:105], v[34:49]
	s_add_u32 m0, s14, 0x8580
	s_nop 0
	global_load_lds_dwordx4 v[68:69], off offset:640
	s_add_u32 m0, s14, 0x9580
	s_nop 0
	global_load_lds_dwordx4 v[72:73], off offset:640
	v_mfma_f32_32x32x16_bf16 v[50:65], v[94:97], v[106:109], v[50:65]
	s_add_u32 m0, s14, 0xa580
	s_nop 0
	global_load_lds_dwordx4 v[76:77], off offset:640
	s_add_u32 m0, s14, 0xb580
	s_nop 0
	global_load_lds_dwordx4 v[80:81], off offset:640
	v_mfma_f32_32x32x16_bf16 v[2:17], v[98:101], v[102:105], v[2:17]
	s_add_u32 m0, s14, 0xc580
	s_nop 0
	global_load_lds_dwordx4 v[70:71], off offset:640
	s_add_u32 m0, s14, 0xd580
	s_nop 0
	global_load_lds_dwordx4 v[74:75], off offset:640
	v_mfma_f32_32x32x16_bf16 v[18:33], v[98:101], v[106:109], v[18:33]
	s_add_u32 m0, s14, 0xe580
	s_nop 0
	global_load_lds_dwordx4 v[78:79], off offset:640
	s_add_u32 m0, s14, 0xf580
	s_nop 0
	global_load_lds_dwordx4 v[82:83], off offset:640
	s_waitcnt vmcnt(8)
	s_barrier
	ds_read_b128 v[94:97], v86 offset:2048
	ds_read_b128 v[98:101], v86 offset:6144
	ds_read_b128 v[102:105], v90 offset:2048
	ds_read_b128 v[106:109], v90 offset:6144
	v_mfma_f32_32x32x16_bf16 v[34:49], v[110:113], v[118:121], v[34:49]
	v_mfma_f32_32x32x16_bf16 v[50:65], v[110:113], v[122:125], v[50:65]
	v_mfma_f32_32x32x16_bf16 v[2:17], v[114:117], v[118:121], v[2:17]
	v_mfma_f32_32x32x16_bf16 v[18:33], v[114:117], v[122:125], v[18:33]
	ds_read_b128 v[110:113], v87 offset:2048
	ds_read_b128 v[114:117], v87 offset:6144
	ds_read_b128 v[118:121], v91 offset:2048
	ds_read_b128 v[122:125], v91 offset:6144
	v_mfma_f32_32x32x16_bf16 v[34:49], v[126:129], v[134:137], v[34:49]
	v_mfma_f32_32x32x16_bf16 v[50:65], v[126:129], v[138:141], v[50:65]
	v_mfma_f32_32x32x16_bf16 v[2:17], v[130:133], v[134:137], v[2:17]
	v_mfma_f32_32x32x16_bf16 v[18:33], v[130:133], v[138:141], v[18:33]
	ds_read_b128 v[126:129], v88 offset:2048
	ds_read_b128 v[130:133], v88 offset:6144
	ds_read_b128 v[134:137], v92 offset:2048
	ds_read_b128 v[138:141], v92 offset:6144
	v_mfma_f32_32x32x16_bf16 v[34:49], v[142:145], v[150:153], v[34:49]
	v_mfma_f32_32x32x16_bf16 v[50:65], v[142:145], v[154:157], v[50:65]
	v_mfma_f32_32x32x16_bf16 v[2:17], v[146:149], v[150:153], v[2:17]
	v_mfma_f32_32x32x16_bf16 v[18:33], v[146:149], v[154:157], v[18:33]
	ds_read_b128 v[142:145], v89 offset:2048
	ds_read_b128 v[146:149], v89 offset:6144
	ds_read_b128 v[150:153], v93 offset:2048
	ds_read_b128 v[154:157], v93 offset:6144
	s_waitcnt lgkmcnt(0)
	s_barrier
	v_mfma_f32_32x32x16_bf16 v[34:49], v[94:97], v[102:105], v[34:49]
	s_add_u32 m0, s14, 0x500
	s_nop 0
	global_load_lds_dwordx4 v[68:69], off offset:768
	s_add_u32 m0, s14, 0x1500
	s_nop 0
	global_load_lds_dwordx4 v[72:73], off offset:768
	v_mfma_f32_32x32x16_bf16 v[50:65], v[94:97], v[106:109], v[50:65]
	s_add_u32 m0, s14, 0x2500
	s_nop 0
	global_load_lds_dwordx4 v[76:77], off offset:768
	s_add_u32 m0, s14, 0x3500
	s_nop 0
	global_load_lds_dwordx4 v[80:81], off offset:768
	v_mfma_f32_32x32x16_bf16 v[2:17], v[98:101], v[102:105], v[2:17]
	s_add_u32 m0, s14, 0x4500
	s_nop 0
	global_load_lds_dwordx4 v[70:71], off offset:768
	s_add_u32 m0, s14, 0x5500
	s_nop 0
	global_load_lds_dwordx4 v[74:75], off offset:768
	v_mfma_f32_32x32x16_bf16 v[18:33], v[98:101], v[106:109], v[18:33]
	s_add_u32 m0, s14, 0x6500
	s_nop 0
	global_load_lds_dwordx4 v[78:79], off offset:768
	s_add_u32 m0, s14, 0x7500
	s_nop 0
	global_load_lds_dwordx4 v[82:83], off offset:768
	s_waitcnt vmcnt(8)
	s_barrier
	ds_read_b128 v[94:97], v86 offset:34816
	ds_read_b128 v[98:101], v86 offset:38912
	ds_read_b128 v[102:105], v90 offset:34816
	ds_read_b128 v[106:109], v90 offset:38912
	v_mfma_f32_32x32x16_bf16 v[34:49], v[110:113], v[118:121], v[34:49]
	v_mfma_f32_32x32x16_bf16 v[50:65], v[110:113], v[122:125], v[50:65]
	v_mfma_f32_32x32x16_bf16 v[2:17], v[114:117], v[118:121], v[2:17]
	v_mfma_f32_32x32x16_bf16 v[18:33], v[114:117], v[122:125], v[18:33]
	ds_read_b128 v[110:113], v87 offset:34816
	ds_read_b128 v[114:117], v87 offset:38912
	ds_read_b128 v[118:121], v91 offset:34816
	ds_read_b128 v[122:125], v91 offset:38912
	v_mfma_f32_32x32x16_bf16 v[34:49], v[126:129], v[134:137], v[34:49]
	v_mfma_f32_32x32x16_bf16 v[50:65], v[126:129], v[138:141], v[50:65]
	v_mfma_f32_32x32x16_bf16 v[2:17], v[130:133], v[134:137], v[2:17]
	v_mfma_f32_32x32x16_bf16 v[18:33], v[130:133], v[138:141], v[18:33]
	ds_read_b128 v[126:129], v88 offset:34816
	ds_read_b128 v[130:133], v88 offset:38912
	ds_read_b128 v[134:137], v92 offset:34816
	ds_read_b128 v[138:141], v92 offset:38912
	v_mfma_f32_32x32x16_bf16 v[34:49], v[142:145], v[150:153], v[34:49]
	v_mfma_f32_32x32x16_bf16 v[50:65], v[142:145], v[154:157], v[50:65]
	v_mfma_f32_32x32x16_bf16 v[2:17], v[146:149], v[150:153], v[2:17]
	v_mfma_f32_32x32x16_bf16 v[18:33], v[146:149], v[154:157], v[18:33]
	ds_read_b128 v[142:145], v89 offset:34816
	ds_read_b128 v[146:149], v89 offset:38912
	ds_read_b128 v[150:153], v93 offset:34816
	ds_read_b128 v[154:157], v93 offset:38912
	s_waitcnt lgkmcnt(0)
	s_barrier
	v_mfma_f32_32x32x16_bf16 v[34:49], v[94:97], v[102:105], v[34:49]
	s_add_u32 m0, s14, 0x8480
	s_nop 0
	global_load_lds_dwordx4 v[68:69], off offset:896
	s_add_u32 m0, s14, 0x9480
	s_nop 0
	global_load_lds_dwordx4 v[72:73], off offset:896
	v_mfma_f32_32x32x16_bf16 v[50:65], v[94:97], v[106:109], v[50:65]
	s_add_u32 m0, s14, 0xa480
	s_nop 0
	global_load_lds_dwordx4 v[76:77], off offset:896
	s_add_u32 m0, s14, 0xb480
	s_nop 0
	global_load_lds_dwordx4 v[80:81], off offset:896
	v_mfma_f32_32x32x16_bf16 v[2:17], v[98:101], v[102:105], v[2:17]
	s_add_u32 m0, s14, 0xc480
	s_nop 0
	global_load_lds_dwordx4 v[70:71], off offset:896
	s_add_u32 m0, s14, 0xd480
	s_nop 0
	global_load_lds_dwordx4 v[74:75], off offset:896
	v_mfma_f32_32x32x16_bf16 v[18:33], v[98:101], v[106:109], v[18:33]
	s_add_u32 m0, s14, 0xe480
	s_nop 0
	global_load_lds_dwordx4 v[78:79], off offset:896
	s_add_u32 m0, s14, 0xf480
	s_nop 0
	global_load_lds_dwordx4 v[82:83], off offset:896
	s_waitcnt vmcnt(8)
	s_barrier
	ds_read_b128 v[94:97], v86 offset:2048
	ds_read_b128 v[98:101], v86 offset:6144
	ds_read_b128 v[102:105], v90 offset:2048
	ds_read_b128 v[106:109], v90 offset:6144
	v_mfma_f32_32x32x16_bf16 v[34:49], v[110:113], v[118:121], v[34:49]
	v_mfma_f32_32x32x16_bf16 v[50:65], v[110:113], v[122:125], v[50:65]
	v_mfma_f32_32x32x16_bf16 v[2:17], v[114:117], v[118:121], v[2:17]
	v_mfma_f32_32x32x16_bf16 v[18:33], v[114:117], v[122:125], v[18:33]
	ds_read_b128 v[110:113], v87 offset:2048
	ds_read_b128 v[114:117], v87 offset:6144
	ds_read_b128 v[118:121], v91 offset:2048
	ds_read_b128 v[122:125], v91 offset:6144
	v_mfma_f32_32x32x16_bf16 v[34:49], v[126:129], v[134:137], v[34:49]
	v_mfma_f32_32x32x16_bf16 v[50:65], v[126:129], v[138:141], v[50:65]
	v_mfma_f32_32x32x16_bf16 v[2:17], v[130:133], v[134:137], v[2:17]
	v_mfma_f32_32x32x16_bf16 v[18:33], v[130:133], v[138:141], v[18:33]
	ds_read_b128 v[126:129], v88 offset:2048
	ds_read_b128 v[130:133], v88 offset:6144
	ds_read_b128 v[134:137], v92 offset:2048
	ds_read_b128 v[138:141], v92 offset:6144
	v_mfma_f32_32x32x16_bf16 v[34:49], v[142:145], v[150:153], v[34:49]
	v_mfma_f32_32x32x16_bf16 v[50:65], v[142:145], v[154:157], v[50:65]
	v_mfma_f32_32x32x16_bf16 v[2:17], v[146:149], v[150:153], v[2:17]
	v_mfma_f32_32x32x16_bf16 v[18:33], v[146:149], v[154:157], v[18:33]
	ds_read_b128 v[142:145], v89 offset:2048
	ds_read_b128 v[146:149], v89 offset:6144
	ds_read_b128 v[150:153], v93 offset:2048
	ds_read_b128 v[154:157], v93 offset:6144
	s_waitcnt lgkmcnt(0)
	s_barrier
	v_mfma_f32_32x32x16_bf16 v[34:49], v[94:97], v[102:105], v[34:49]
	s_add_u32 m0, s14, 0x400
	s_nop 0
	global_load_lds_dwordx4 v[68:69], off offset:1024
	s_add_u32 m0, s14, 0x1400
	s_nop 0
	global_load_lds_dwordx4 v[72:73], off offset:1024
	v_mfma_f32_32x32x16_bf16 v[50:65], v[94:97], v[106:109], v[50:65]
	s_add_u32 m0, s14, 0x2400
	s_nop 0
	global_load_lds_dwordx4 v[76:77], off offset:1024
	s_add_u32 m0, s14, 0x3400
	s_nop 0
	global_load_lds_dwordx4 v[80:81], off offset:1024
	v_mfma_f32_32x32x16_bf16 v[2:17], v[98:101], v[102:105], v[2:17]
	s_add_u32 m0, s14, 0x4400
	s_nop 0
	global_load_lds_dwordx4 v[70:71], off offset:1024
	s_add_u32 m0, s14, 0x5400
	s_nop 0
	global_load_lds_dwordx4 v[74:75], off offset:1024
	v_mfma_f32_32x32x16_bf16 v[18:33], v[98:101], v[106:109], v[18:33]
	s_add_u32 m0, s14, 0x6400
	s_nop 0
	global_load_lds_dwordx4 v[78:79], off offset:1024
	s_add_u32 m0, s14, 0x7400
	s_nop 0
	global_load_lds_dwordx4 v[82:83], off offset:1024
	s_waitcnt vmcnt(8)
	s_barrier
	ds_read_b128 v[94:97], v86 offset:34816
	ds_read_b128 v[98:101], v86 offset:38912
	ds_read_b128 v[102:105], v90 offset:34816
	ds_read_b128 v[106:109], v90 offset:38912
	v_mfma_f32_32x32x16_bf16 v[34:49], v[110:113], v[118:121], v[34:49]
	v_mfma_f32_32x32x16_bf16 v[50:65], v[110:113], v[122:125], v[50:65]
	v_mfma_f32_32x32x16_bf16 v[2:17], v[114:117], v[118:121], v[2:17]
	v_mfma_f32_32x32x16_bf16 v[18:33], v[114:117], v[122:125], v[18:33]
	ds_read_b128 v[110:113], v87 offset:34816
	ds_read_b128 v[114:117], v87 offset:38912
	ds_read_b128 v[118:121], v91 offset:34816
	ds_read_b128 v[122:125], v91 offset:38912
	v_mfma_f32_32x32x16_bf16 v[34:49], v[126:129], v[134:137], v[34:49]
	v_mfma_f32_32x32x16_bf16 v[50:65], v[126:129], v[138:141], v[50:65]
	v_mfma_f32_32x32x16_bf16 v[2:17], v[130:133], v[134:137], v[2:17]
	v_mfma_f32_32x32x16_bf16 v[18:33], v[130:133], v[138:141], v[18:33]
	ds_read_b128 v[126:129], v88 offset:34816
	ds_read_b128 v[130:133], v88 offset:38912
	ds_read_b128 v[134:137], v92 offset:34816
	ds_read_b128 v[138:141], v92 offset:38912
	v_mfma_f32_32x32x16_bf16 v[34:49], v[142:145], v[150:153], v[34:49]
	v_mfma_f32_32x32x16_bf16 v[50:65], v[142:145], v[154:157], v[50:65]
	v_mfma_f32_32x32x16_bf16 v[2:17], v[146:149], v[150:153], v[2:17]
	v_mfma_f32_32x32x16_bf16 v[18:33], v[146:149], v[154:157], v[18:33]
	ds_read_b128 v[142:145], v89 offset:34816
	ds_read_b128 v[146:149], v89 offset:38912
	ds_read_b128 v[150:153], v93 offset:34816
	ds_read_b128 v[154:157], v93 offset:38912
	s_waitcnt lgkmcnt(0)
	s_barrier
	v_mfma_f32_32x32x16_bf16 v[34:49], v[94:97], v[102:105], v[34:49]
	s_add_u32 m0, s14, 0x8380
	s_nop 0
	global_load_lds_dwordx4 v[68:69], off offset:1152
	s_add_u32 m0, s14, 0x9380
	s_nop 0
	global_load_lds_dwordx4 v[72:73], off offset:1152
	v_mfma_f32_32x32x16_bf16 v[50:65], v[94:97], v[106:109], v[50:65]
	s_add_u32 m0, s14, 0xa380
	s_nop 0
	global_load_lds_dwordx4 v[76:77], off offset:1152
	s_add_u32 m0, s14, 0xb380
	s_nop 0
	global_load_lds_dwordx4 v[80:81], off offset:1152
	v_mfma_f32_32x32x16_bf16 v[2:17], v[98:101], v[102:105], v[2:17]
	s_add_u32 m0, s14, 0xc380
	s_nop 0
	global_load_lds_dwordx4 v[70:71], off offset:1152
	s_add_u32 m0, s14, 0xd380
	s_nop 0
	global_load_lds_dwordx4 v[74:75], off offset:1152
	v_mfma_f32_32x32x16_bf16 v[18:33], v[98:101], v[106:109], v[18:33]
	s_add_u32 m0, s14, 0xe380
	s_nop 0
	global_load_lds_dwordx4 v[78:79], off offset:1152
	s_add_u32 m0, s14, 0xf380
	s_nop 0
	global_load_lds_dwordx4 v[82:83], off offset:1152
	s_waitcnt vmcnt(8)
	s_barrier
	ds_read_b128 v[94:97], v86 offset:2048
	ds_read_b128 v[98:101], v86 offset:6144
	ds_read_b128 v[102:105], v90 offset:2048
	ds_read_b128 v[106:109], v90 offset:6144
	v_mfma_f32_32x32x16_bf16 v[34:49], v[110:113], v[118:121], v[34:49]
	v_mfma_f32_32x32x16_bf16 v[50:65], v[110:113], v[122:125], v[50:65]
	v_mfma_f32_32x32x16_bf16 v[2:17], v[114:117], v[118:121], v[2:17]
	v_mfma_f32_32x32x16_bf16 v[18:33], v[114:117], v[122:125], v[18:33]
	ds_read_b128 v[110:113], v87 offset:2048
	ds_read_b128 v[114:117], v87 offset:6144
	ds_read_b128 v[118:121], v91 offset:2048
	ds_read_b128 v[122:125], v91 offset:6144
	v_mfma_f32_32x32x16_bf16 v[34:49], v[126:129], v[134:137], v[34:49]
	v_mfma_f32_32x32x16_bf16 v[50:65], v[126:129], v[138:141], v[50:65]
	v_mfma_f32_32x32x16_bf16 v[2:17], v[130:133], v[134:137], v[2:17]
	v_mfma_f32_32x32x16_bf16 v[18:33], v[130:133], v[138:141], v[18:33]
	ds_read_b128 v[126:129], v88 offset:2048
	ds_read_b128 v[130:133], v88 offset:6144
	ds_read_b128 v[134:137], v92 offset:2048
	ds_read_b128 v[138:141], v92 offset:6144
	v_mfma_f32_32x32x16_bf16 v[34:49], v[142:145], v[150:153], v[34:49]
	v_mfma_f32_32x32x16_bf16 v[50:65], v[142:145], v[154:157], v[50:65]
	v_mfma_f32_32x32x16_bf16 v[2:17], v[146:149], v[150:153], v[2:17]
	v_mfma_f32_32x32x16_bf16 v[18:33], v[146:149], v[154:157], v[18:33]
	ds_read_b128 v[142:145], v89 offset:2048
	ds_read_b128 v[146:149], v89 offset:6144
	ds_read_b128 v[150:153], v93 offset:2048
	ds_read_b128 v[154:157], v93 offset:6144
	s_waitcnt lgkmcnt(0)
	s_barrier
	v_mfma_f32_32x32x16_bf16 v[34:49], v[94:97], v[102:105], v[34:49]
	s_add_u32 m0, s14, 0x300
	s_nop 0
	global_load_lds_dwordx4 v[68:69], off offset:1280
	s_add_u32 m0, s14, 0x1300
	s_nop 0
	global_load_lds_dwordx4 v[72:73], off offset:1280
	v_mfma_f32_32x32x16_bf16 v[50:65], v[94:97], v[106:109], v[50:65]
	s_add_u32 m0, s14, 0x2300
	s_nop 0
	global_load_lds_dwordx4 v[76:77], off offset:1280
	s_add_u32 m0, s14, 0x3300
	s_nop 0
	global_load_lds_dwordx4 v[80:81], off offset:1280
	v_mfma_f32_32x32x16_bf16 v[2:17], v[98:101], v[102:105], v[2:17]
	s_add_u32 m0, s14, 0x4300
	s_nop 0
	global_load_lds_dwordx4 v[70:71], off offset:1280
	s_add_u32 m0, s14, 0x5300
	s_nop 0
	global_load_lds_dwordx4 v[74:75], off offset:1280
	v_mfma_f32_32x32x16_bf16 v[18:33], v[98:101], v[106:109], v[18:33]
	s_add_u32 m0, s14, 0x6300
	s_nop 0
	global_load_lds_dwordx4 v[78:79], off offset:1280
	s_add_u32 m0, s14, 0x7300
	s_nop 0
	global_load_lds_dwordx4 v[82:83], off offset:1280
	s_waitcnt vmcnt(8)
	s_barrier
	ds_read_b128 v[94:97], v86 offset:34816
	ds_read_b128 v[98:101], v86 offset:38912
	ds_read_b128 v[102:105], v90 offset:34816
	ds_read_b128 v[106:109], v90 offset:38912
	v_mfma_f32_32x32x16_bf16 v[34:49], v[110:113], v[118:121], v[34:49]
	v_mfma_f32_32x32x16_bf16 v[50:65], v[110:113], v[122:125], v[50:65]
	v_mfma_f32_32x32x16_bf16 v[2:17], v[114:117], v[118:121], v[2:17]
	v_mfma_f32_32x32x16_bf16 v[18:33], v[114:117], v[122:125], v[18:33]
	ds_read_b128 v[110:113], v87 offset:34816
	ds_read_b128 v[114:117], v87 offset:38912
	ds_read_b128 v[118:121], v91 offset:34816
	ds_read_b128 v[122:125], v91 offset:38912
	v_mfma_f32_32x32x16_bf16 v[34:49], v[126:129], v[134:137], v[34:49]
	v_mfma_f32_32x32x16_bf16 v[50:65], v[126:129], v[138:141], v[50:65]
	v_mfma_f32_32x32x16_bf16 v[2:17], v[130:133], v[134:137], v[2:17]
	v_mfma_f32_32x32x16_bf16 v[18:33], v[130:133], v[138:141], v[18:33]
	ds_read_b128 v[126:129], v88 offset:34816
	ds_read_b128 v[130:133], v88 offset:38912
	ds_read_b128 v[134:137], v92 offset:34816
	ds_read_b128 v[138:141], v92 offset:38912
	v_mfma_f32_32x32x16_bf16 v[34:49], v[142:145], v[150:153], v[34:49]
	v_mfma_f32_32x32x16_bf16 v[50:65], v[142:145], v[154:157], v[50:65]
	v_mfma_f32_32x32x16_bf16 v[2:17], v[146:149], v[150:153], v[2:17]
	v_mfma_f32_32x32x16_bf16 v[18:33], v[146:149], v[154:157], v[18:33]
	ds_read_b128 v[142:145], v89 offset:34816
	ds_read_b128 v[146:149], v89 offset:38912
	ds_read_b128 v[150:153], v93 offset:34816
	ds_read_b128 v[154:157], v93 offset:38912
	s_waitcnt lgkmcnt(0)
	s_barrier
	v_mfma_f32_32x32x16_bf16 v[34:49], v[94:97], v[102:105], v[34:49]
	s_add_u32 m0, s14, 0x8280
	s_nop 0
	global_load_lds_dwordx4 v[68:69], off offset:1408
	s_add_u32 m0, s14, 0x9280
	s_nop 0
	global_load_lds_dwordx4 v[72:73], off offset:1408
	v_mfma_f32_32x32x16_bf16 v[50:65], v[94:97], v[106:109], v[50:65]
	s_add_u32 m0, s14, 0xa280
	s_nop 0
	global_load_lds_dwordx4 v[76:77], off offset:1408
	s_add_u32 m0, s14, 0xb280
	s_nop 0
	global_load_lds_dwordx4 v[80:81], off offset:1408
	v_mfma_f32_32x32x16_bf16 v[2:17], v[98:101], v[102:105], v[2:17]
	s_add_u32 m0, s14, 0xc280
	s_nop 0
	global_load_lds_dwordx4 v[70:71], off offset:1408
	s_add_u32 m0, s14, 0xd280
	s_nop 0
	global_load_lds_dwordx4 v[74:75], off offset:1408
	v_mfma_f32_32x32x16_bf16 v[18:33], v[98:101], v[106:109], v[18:33]
	s_add_u32 m0, s14, 0xe280
	s_nop 0
	global_load_lds_dwordx4 v[78:79], off offset:1408
	s_add_u32 m0, s14, 0xf280
	s_nop 0
	global_load_lds_dwordx4 v[82:83], off offset:1408
	s_waitcnt vmcnt(8)
	s_barrier
	ds_read_b128 v[94:97], v86 offset:2048
	ds_read_b128 v[98:101], v86 offset:6144
	ds_read_b128 v[102:105], v90 offset:2048
	ds_read_b128 v[106:109], v90 offset:6144
	v_mfma_f32_32x32x16_bf16 v[34:49], v[110:113], v[118:121], v[34:49]
	v_mfma_f32_32x32x16_bf16 v[50:65], v[110:113], v[122:125], v[50:65]
	v_mfma_f32_32x32x16_bf16 v[2:17], v[114:117], v[118:121], v[2:17]
	v_mfma_f32_32x32x16_bf16 v[18:33], v[114:117], v[122:125], v[18:33]
	ds_read_b128 v[110:113], v87 offset:2048
	ds_read_b128 v[114:117], v87 offset:6144
	ds_read_b128 v[118:121], v91 offset:2048
	ds_read_b128 v[122:125], v91 offset:6144
	v_mfma_f32_32x32x16_bf16 v[34:49], v[126:129], v[134:137], v[34:49]
	v_mfma_f32_32x32x16_bf16 v[50:65], v[126:129], v[138:141], v[50:65]
	v_mfma_f32_32x32x16_bf16 v[2:17], v[130:133], v[134:137], v[2:17]
	v_mfma_f32_32x32x16_bf16 v[18:33], v[130:133], v[138:141], v[18:33]
	ds_read_b128 v[126:129], v88 offset:2048
	ds_read_b128 v[130:133], v88 offset:6144
	ds_read_b128 v[134:137], v92 offset:2048
	ds_read_b128 v[138:141], v92 offset:6144
	v_mfma_f32_32x32x16_bf16 v[34:49], v[142:145], v[150:153], v[34:49]
	v_mfma_f32_32x32x16_bf16 v[50:65], v[142:145], v[154:157], v[50:65]
	v_mfma_f32_32x32x16_bf16 v[2:17], v[146:149], v[150:153], v[2:17]
	v_mfma_f32_32x32x16_bf16 v[18:33], v[146:149], v[154:157], v[18:33]
	ds_read_b128 v[142:145], v89 offset:2048
	ds_read_b128 v[146:149], v89 offset:6144
	ds_read_b128 v[150:153], v93 offset:2048
	ds_read_b128 v[154:157], v93 offset:6144
	s_waitcnt lgkmcnt(0)
	s_barrier
	v_mfma_f32_32x32x16_bf16 v[34:49], v[94:97], v[102:105], v[34:49]
	s_add_u32 m0, s14, 0x200
	s_nop 0
	global_load_lds_dwordx4 v[68:69], off offset:1536
	s_add_u32 m0, s14, 0x1200
	s_nop 0
	global_load_lds_dwordx4 v[72:73], off offset:1536
	v_mfma_f32_32x32x16_bf16 v[50:65], v[94:97], v[106:109], v[50:65]
	s_add_u32 m0, s14, 0x2200
	s_nop 0
	global_load_lds_dwordx4 v[76:77], off offset:1536
	s_add_u32 m0, s14, 0x3200
	s_nop 0
	global_load_lds_dwordx4 v[80:81], off offset:1536
	v_mfma_f32_32x32x16_bf16 v[2:17], v[98:101], v[102:105], v[2:17]
	s_add_u32 m0, s14, 0x4200
	s_nop 0
	global_load_lds_dwordx4 v[70:71], off offset:1536
	s_add_u32 m0, s14, 0x5200
	s_nop 0
	global_load_lds_dwordx4 v[74:75], off offset:1536
	v_mfma_f32_32x32x16_bf16 v[18:33], v[98:101], v[106:109], v[18:33]
	s_add_u32 m0, s14, 0x6200
	s_nop 0
	global_load_lds_dwordx4 v[78:79], off offset:1536
	s_add_u32 m0, s14, 0x7200
	s_nop 0
	global_load_lds_dwordx4 v[82:83], off offset:1536
	s_waitcnt vmcnt(8)
	s_barrier
	ds_read_b128 v[94:97], v86 offset:34816
	ds_read_b128 v[98:101], v86 offset:38912
	ds_read_b128 v[102:105], v90 offset:34816
	ds_read_b128 v[106:109], v90 offset:38912
	v_mfma_f32_32x32x16_bf16 v[34:49], v[110:113], v[118:121], v[34:49]
	v_mfma_f32_32x32x16_bf16 v[50:65], v[110:113], v[122:125], v[50:65]
	v_mfma_f32_32x32x16_bf16 v[2:17], v[114:117], v[118:121], v[2:17]
	v_mfma_f32_32x32x16_bf16 v[18:33], v[114:117], v[122:125], v[18:33]
	ds_read_b128 v[110:113], v87 offset:34816
	ds_read_b128 v[114:117], v87 offset:38912
	ds_read_b128 v[118:121], v91 offset:34816
	ds_read_b128 v[122:125], v91 offset:38912
	v_mfma_f32_32x32x16_bf16 v[34:49], v[126:129], v[134:137], v[34:49]
	v_mfma_f32_32x32x16_bf16 v[50:65], v[126:129], v[138:141], v[50:65]
	v_mfma_f32_32x32x16_bf16 v[2:17], v[130:133], v[134:137], v[2:17]
	v_mfma_f32_32x32x16_bf16 v[18:33], v[130:133], v[138:141], v[18:33]
	ds_read_b128 v[126:129], v88 offset:34816
	ds_read_b128 v[130:133], v88 offset:38912
	ds_read_b128 v[134:137], v92 offset:34816
	ds_read_b128 v[138:141], v92 offset:38912
	v_mfma_f32_32x32x16_bf16 v[34:49], v[142:145], v[150:153], v[34:49]
	v_mfma_f32_32x32x16_bf16 v[50:65], v[142:145], v[154:157], v[50:65]
	v_mfma_f32_32x32x16_bf16 v[2:17], v[146:149], v[150:153], v[2:17]
	v_mfma_f32_32x32x16_bf16 v[18:33], v[146:149], v[154:157], v[18:33]
	ds_read_b128 v[142:145], v89 offset:34816
	ds_read_b128 v[146:149], v89 offset:38912
	ds_read_b128 v[150:153], v93 offset:34816
	ds_read_b128 v[154:157], v93 offset:38912
	s_waitcnt lgkmcnt(0)
	s_barrier
	v_mfma_f32_32x32x16_bf16 v[34:49], v[94:97], v[102:105], v[34:49]
	s_add_u32 m0, s14, 0x8180
	s_nop 0
	global_load_lds_dwordx4 v[68:69], off offset:1664
	s_add_u32 m0, s14, 0x9180
	s_nop 0
	global_load_lds_dwordx4 v[72:73], off offset:1664
	v_mfma_f32_32x32x16_bf16 v[50:65], v[94:97], v[106:109], v[50:65]
	s_add_u32 m0, s14, 0xa180
	s_nop 0
	global_load_lds_dwordx4 v[76:77], off offset:1664
	s_add_u32 m0, s14, 0xb180
	s_nop 0
	global_load_lds_dwordx4 v[80:81], off offset:1664
	v_mfma_f32_32x32x16_bf16 v[2:17], v[98:101], v[102:105], v[2:17]
	s_add_u32 m0, s14, 0xc180
	s_nop 0
	global_load_lds_dwordx4 v[70:71], off offset:1664
	s_add_u32 m0, s14, 0xd180
	s_nop 0
	global_load_lds_dwordx4 v[74:75], off offset:1664
	v_mfma_f32_32x32x16_bf16 v[18:33], v[98:101], v[106:109], v[18:33]
	s_add_u32 m0, s14, 0xe180
	s_nop 0
	global_load_lds_dwordx4 v[78:79], off offset:1664
	s_add_u32 m0, s14, 0xf180
	s_nop 0
	global_load_lds_dwordx4 v[82:83], off offset:1664
	s_waitcnt vmcnt(8)
	s_barrier
	ds_read_b128 v[94:97], v86 offset:2048
	ds_read_b128 v[98:101], v86 offset:6144
	ds_read_b128 v[102:105], v90 offset:2048
	ds_read_b128 v[106:109], v90 offset:6144
	v_mfma_f32_32x32x16_bf16 v[34:49], v[110:113], v[118:121], v[34:49]
	v_mfma_f32_32x32x16_bf16 v[50:65], v[110:113], v[122:125], v[50:65]
	v_mfma_f32_32x32x16_bf16 v[2:17], v[114:117], v[118:121], v[2:17]
	v_mfma_f32_32x32x16_bf16 v[18:33], v[114:117], v[122:125], v[18:33]
	ds_read_b128 v[110:113], v87 offset:2048
	ds_read_b128 v[114:117], v87 offset:6144
	ds_read_b128 v[118:121], v91 offset:2048
	ds_read_b128 v[122:125], v91 offset:6144
	v_mfma_f32_32x32x16_bf16 v[34:49], v[126:129], v[134:137], v[34:49]
	v_mfma_f32_32x32x16_bf16 v[50:65], v[126:129], v[138:141], v[50:65]
	v_mfma_f32_32x32x16_bf16 v[2:17], v[130:133], v[134:137], v[2:17]
	v_mfma_f32_32x32x16_bf16 v[18:33], v[130:133], v[138:141], v[18:33]
	ds_read_b128 v[126:129], v88 offset:2048
	ds_read_b128 v[130:133], v88 offset:6144
	ds_read_b128 v[134:137], v92 offset:2048
	ds_read_b128 v[138:141], v92 offset:6144
	v_mfma_f32_32x32x16_bf16 v[34:49], v[142:145], v[150:153], v[34:49]
	v_mfma_f32_32x32x16_bf16 v[50:65], v[142:145], v[154:157], v[50:65]
	v_mfma_f32_32x32x16_bf16 v[2:17], v[146:149], v[150:153], v[2:17]
	v_mfma_f32_32x32x16_bf16 v[18:33], v[146:149], v[154:157], v[18:33]
	ds_read_b128 v[142:145], v89 offset:2048
	ds_read_b128 v[146:149], v89 offset:6144
	ds_read_b128 v[150:153], v93 offset:2048
	ds_read_b128 v[154:157], v93 offset:6144
	s_waitcnt lgkmcnt(0)
	s_barrier
	v_mfma_f32_32x32x16_bf16 v[34:49], v[94:97], v[102:105], v[34:49]
	s_add_u32 m0, s14, 0x100
	s_nop 0
	global_load_lds_dwordx4 v[68:69], off offset:1792
	s_add_u32 m0, s14, 0x1100
	s_nop 0
	global_load_lds_dwordx4 v[72:73], off offset:1792
	v_mfma_f32_32x32x16_bf16 v[50:65], v[94:97], v[106:109], v[50:65]
	s_add_u32 m0, s14, 0x2100
	s_nop 0
	global_load_lds_dwordx4 v[76:77], off offset:1792
	s_add_u32 m0, s14, 0x3100
	s_nop 0
	global_load_lds_dwordx4 v[80:81], off offset:1792
	v_mfma_f32_32x32x16_bf16 v[2:17], v[98:101], v[102:105], v[2:17]
	s_add_u32 m0, s14, 0x4100
	s_nop 0
	global_load_lds_dwordx4 v[70:71], off offset:1792
	s_add_u32 m0, s14, 0x5100
	s_nop 0
	global_load_lds_dwordx4 v[74:75], off offset:1792
	v_mfma_f32_32x32x16_bf16 v[18:33], v[98:101], v[106:109], v[18:33]
	s_add_u32 m0, s14, 0x6100
	s_nop 0
	global_load_lds_dwordx4 v[78:79], off offset:1792
	s_add_u32 m0, s14, 0x7100
	s_nop 0
	global_load_lds_dwordx4 v[82:83], off offset:1792
	s_waitcnt vmcnt(8)
	s_barrier
	ds_read_b128 v[94:97], v86 offset:34816
	ds_read_b128 v[98:101], v86 offset:38912
	ds_read_b128 v[102:105], v90 offset:34816
	ds_read_b128 v[106:109], v90 offset:38912
	v_mfma_f32_32x32x16_bf16 v[34:49], v[110:113], v[118:121], v[34:49]
	v_mfma_f32_32x32x16_bf16 v[50:65], v[110:113], v[122:125], v[50:65]
	v_mfma_f32_32x32x16_bf16 v[2:17], v[114:117], v[118:121], v[2:17]
	v_mfma_f32_32x32x16_bf16 v[18:33], v[114:117], v[122:125], v[18:33]
	ds_read_b128 v[110:113], v87 offset:34816
	ds_read_b128 v[114:117], v87 offset:38912
	ds_read_b128 v[118:121], v91 offset:34816
	ds_read_b128 v[122:125], v91 offset:38912
	v_mfma_f32_32x32x16_bf16 v[34:49], v[126:129], v[134:137], v[34:49]
	v_mfma_f32_32x32x16_bf16 v[50:65], v[126:129], v[138:141], v[50:65]
	v_mfma_f32_32x32x16_bf16 v[2:17], v[130:133], v[134:137], v[2:17]
	v_mfma_f32_32x32x16_bf16 v[18:33], v[130:133], v[138:141], v[18:33]
	ds_read_b128 v[126:129], v88 offset:34816
	ds_read_b128 v[130:133], v88 offset:38912
	ds_read_b128 v[134:137], v92 offset:34816
	ds_read_b128 v[138:141], v92 offset:38912
	v_mfma_f32_32x32x16_bf16 v[34:49], v[142:145], v[150:153], v[34:49]
	v_mfma_f32_32x32x16_bf16 v[50:65], v[142:145], v[154:157], v[50:65]
	v_mfma_f32_32x32x16_bf16 v[2:17], v[146:149], v[150:153], v[2:17]
	v_mfma_f32_32x32x16_bf16 v[18:33], v[146:149], v[154:157], v[18:33]
	ds_read_b128 v[142:145], v89 offset:34816
	ds_read_b128 v[146:149], v89 offset:38912
	ds_read_b128 v[150:153], v93 offset:34816
	ds_read_b128 v[154:157], v93 offset:38912
	s_waitcnt lgkmcnt(0)
	s_barrier
	v_mfma_f32_32x32x16_bf16 v[34:49], v[94:97], v[102:105], v[34:49]
	s_add_u32 m0, s14, 0x8080
	s_nop 0
	global_load_lds_dwordx4 v[68:69], off offset:1920
	s_add_u32 m0, s14, 0x9080
	s_nop 0
	global_load_lds_dwordx4 v[72:73], off offset:1920
	v_mfma_f32_32x32x16_bf16 v[50:65], v[94:97], v[106:109], v[50:65]
	s_add_u32 m0, s14, 0xa080
	s_nop 0
	global_load_lds_dwordx4 v[76:77], off offset:1920
	s_add_u32 m0, s14, 0xb080
	s_nop 0
	global_load_lds_dwordx4 v[80:81], off offset:1920
	v_mfma_f32_32x32x16_bf16 v[2:17], v[98:101], v[102:105], v[2:17]
	s_add_u32 m0, s14, 0xc080
	s_nop 0
	global_load_lds_dwordx4 v[70:71], off offset:1920
	s_add_u32 m0, s14, 0xd080
	s_nop 0
	global_load_lds_dwordx4 v[74:75], off offset:1920
	v_mfma_f32_32x32x16_bf16 v[18:33], v[98:101], v[106:109], v[18:33]
	s_add_u32 m0, s14, 0xe080
	s_nop 0
	global_load_lds_dwordx4 v[78:79], off offset:1920
	s_add_u32 m0, s14, 0xf080
	s_nop 0
	global_load_lds_dwordx4 v[82:83], off offset:1920
	s_waitcnt vmcnt(8)
	s_barrier
	ds_read_b128 v[94:97], v86 offset:2048
	ds_read_b128 v[98:101], v86 offset:6144
	ds_read_b128 v[102:105], v90 offset:2048
	ds_read_b128 v[106:109], v90 offset:6144
	v_mfma_f32_32x32x16_bf16 v[34:49], v[110:113], v[118:121], v[34:49]
	v_mfma_f32_32x32x16_bf16 v[50:65], v[110:113], v[122:125], v[50:65]
	v_mfma_f32_32x32x16_bf16 v[2:17], v[114:117], v[118:121], v[2:17]
	v_mfma_f32_32x32x16_bf16 v[18:33], v[114:117], v[122:125], v[18:33]
	ds_read_b128 v[110:113], v87 offset:2048
	ds_read_b128 v[114:117], v87 offset:6144
	ds_read_b128 v[118:121], v91 offset:2048
	ds_read_b128 v[122:125], v91 offset:6144
	v_mfma_f32_32x32x16_bf16 v[34:49], v[126:129], v[134:137], v[34:49]
	v_mfma_f32_32x32x16_bf16 v[50:65], v[126:129], v[138:141], v[50:65]
	v_mfma_f32_32x32x16_bf16 v[2:17], v[130:133], v[134:137], v[2:17]
	v_mfma_f32_32x32x16_bf16 v[18:33], v[130:133], v[138:141], v[18:33]
	ds_read_b128 v[126:129], v88 offset:2048
	ds_read_b128 v[130:133], v88 offset:6144
	ds_read_b128 v[134:137], v92 offset:2048
	ds_read_b128 v[138:141], v92 offset:6144
	v_mfma_f32_32x32x16_bf16 v[34:49], v[142:145], v[150:153], v[34:49]
	v_mfma_f32_32x32x16_bf16 v[50:65], v[142:145], v[154:157], v[50:65]
	v_mfma_f32_32x32x16_bf16 v[2:17], v[146:149], v[150:153], v[2:17]
	v_mfma_f32_32x32x16_bf16 v[18:33], v[146:149], v[154:157], v[18:33]
	ds_read_b128 v[142:145], v89 offset:2048
	ds_read_b128 v[146:149], v89 offset:6144
	ds_read_b128 v[150:153], v93 offset:2048
	ds_read_b128 v[154:157], v93 offset:6144
	s_waitcnt lgkmcnt(0)
	v_mfma_f32_32x32x16_bf16 v[34:49], v[94:97], v[102:105], v[34:49]
	v_mfma_f32_32x32x16_bf16 v[50:65], v[94:97], v[106:109], v[50:65]
	v_mfma_f32_32x32x16_bf16 v[2:17], v[98:101], v[102:105], v[2:17]
	v_mfma_f32_32x32x16_bf16 v[18:33], v[98:101], v[106:109], v[18:33]
	s_waitcnt vmcnt(0)
	s_barrier
	ds_read_b128 v[94:97], v86 offset:34816
	ds_read_b128 v[98:101], v86 offset:38912
	ds_read_b128 v[102:105], v90 offset:34816
	ds_read_b128 v[106:109], v90 offset:38912
	v_mfma_f32_32x32x16_bf16 v[34:49], v[110:113], v[118:121], v[34:49]
	v_mfma_f32_32x32x16_bf16 v[50:65], v[110:113], v[122:125], v[50:65]
	v_mfma_f32_32x32x16_bf16 v[2:17], v[114:117], v[118:121], v[2:17]
	v_mfma_f32_32x32x16_bf16 v[18:33], v[114:117], v[122:125], v[18:33]
	ds_read_b128 v[110:113], v87 offset:34816
	ds_read_b128 v[114:117], v87 offset:38912
	ds_read_b128 v[118:121], v91 offset:34816
	ds_read_b128 v[122:125], v91 offset:38912
	v_mfma_f32_32x32x16_bf16 v[34:49], v[126:129], v[134:137], v[34:49]
	v_mfma_f32_32x32x16_bf16 v[50:65], v[126:129], v[138:141], v[50:65]
	v_mfma_f32_32x32x16_bf16 v[2:17], v[130:133], v[134:137], v[2:17]
	v_mfma_f32_32x32x16_bf16 v[18:33], v[130:133], v[138:141], v[18:33]
	ds_read_b128 v[126:129], v88 offset:34816
	ds_read_b128 v[130:133], v88 offset:38912
	ds_read_b128 v[134:137], v92 offset:34816
	ds_read_b128 v[138:141], v92 offset:38912
	v_mfma_f32_32x32x16_bf16 v[34:49], v[142:145], v[150:153], v[34:49]
	v_mfma_f32_32x32x16_bf16 v[50:65], v[142:145], v[154:157], v[50:65]
	v_mfma_f32_32x32x16_bf16 v[2:17], v[146:149], v[150:153], v[2:17]
	v_mfma_f32_32x32x16_bf16 v[18:33], v[146:149], v[154:157], v[18:33]
	ds_read_b128 v[142:145], v89 offset:34816
	ds_read_b128 v[146:149], v89 offset:38912
	ds_read_b128 v[150:153], v93 offset:34816
	ds_read_b128 v[154:157], v93 offset:38912
	s_waitcnt lgkmcnt(0)
	v_mfma_f32_32x32x16_bf16 v[34:49], v[94:97], v[102:105], v[34:49]
	v_mfma_f32_32x32x16_bf16 v[50:65], v[94:97], v[106:109], v[50:65]
	v_mfma_f32_32x32x16_bf16 v[2:17], v[98:101], v[102:105], v[2:17]
	v_mfma_f32_32x32x16_bf16 v[18:33], v[98:101], v[106:109], v[18:33]
	v_mfma_f32_32x32x16_bf16 v[34:49], v[110:113], v[118:121], v[34:49]
	v_mfma_f32_32x32x16_bf16 v[50:65], v[110:113], v[122:125], v[50:65]
	v_mfma_f32_32x32x16_bf16 v[2:17], v[114:117], v[118:121], v[2:17]
	v_mfma_f32_32x32x16_bf16 v[18:33], v[114:117], v[122:125], v[18:33]
	v_mfma_f32_32x32x16_bf16 v[34:49], v[126:129], v[134:137], v[34:49]
	v_mfma_f32_32x32x16_bf16 v[50:65], v[126:129], v[138:141], v[50:65]
	v_mfma_f32_32x32x16_bf16 v[2:17], v[130:133], v[134:137], v[2:17]
	v_mfma_f32_32x32x16_bf16 v[18:33], v[130:133], v[138:141], v[18:33]
	v_mfma_f32_32x32x16_bf16 v[34:49], v[142:145], v[150:153], v[34:49]
	v_mfma_f32_32x32x16_bf16 v[50:65], v[142:145], v[154:157], v[50:65]
	v_mfma_f32_32x32x16_bf16 v[2:17], v[146:149], v[150:153], v[2:17]
	v_mfma_f32_32x32x16_bf16 v[18:33], v[146:149], v[154:157], v[18:33]
	s_setprio 0
	v_mov_b32_e32 v66, v178
	s_waitcnt lgkmcnt(0)
	s_barrier
	s_nop 0
	v_lshrrev_b32_e32 v0, 1, v66
	v_and_b32_e32 v0, 0xfffffc0, v0
	v_lshrrev_b32_e32 v67, 3, v66
	v_and_or_b32 v0, v67, 4, v0
	v_and_b32_e32 v67, 0x5f, v66
	v_mul_lo_u32 v0, v0, s83
	v_lshl_add_u32 v0, v67, 2, v0
	s_nop 0
	s_nop 11
	ds_write2_b32 v0, v34, v50 offset1:32
	ds_write2_b32 v0, v35, v51 offset0:132 offset1:164
	s_nop 0
	v_add_u32_e32 v34, 0x400, v0
	ds_write2_b32 v34, v36, v52 offset0:8 offset1:40
	ds_write2_b32 v34, v37, v53 offset0:140 offset1:172
	v_add_u32_e32 v34, 0x1000, v0
	ds_write2_b32 v34, v38, v54 offset0:32 offset1:64
	ds_write2_b32 v34, v39, v55 offset0:164 offset1:196
	v_add_u32_e32 v34, 0x1400, v0
	ds_write2_b32 v34, v40, v56 offset0:40 offset1:72
	ds_write2_b32 v34, v41, v57 offset0:172 offset1:204
	v_add_u32_e32 v34, 0x2000, v0
	s_nop 0
	ds_write2_b32 v34, v42, v58 offset0:64 offset1:96
	ds_write2_b32 v34, v43, v59 offset0:196 offset1:228
	v_add_u32_e32 v34, 0x2400, v0
	ds_write2_b32 v34, v44, v60 offset0:72 offset1:104
	ds_write2_b32 v34, v45, v61 offset0:204 offset1:236
	v_add_u32_e32 v34, 0x3000, v0
	ds_write2_b32 v34, v46, v62 offset0:96 offset1:128
	v_add_u32_e32 v34, 0x3200, v0
	ds_write2_b32 v34, v47, v63 offset0:100 offset1:132
	s_nop 0
	v_add_u32_e32 v34, 0x3400, v0
	ds_write2_b32 v34, v48, v64 offset0:104 offset1:136
	v_add_u32_e32 v34, 0x3600, v0
	ds_write2_b32 v34, v49, v65 offset0:108 offset1:140
	v_add_u32_e32 v34, 0x4000, v0
	s_nop 0
	s_nop 11
	ds_write2_b32 v34, v2, v18 offset0:128 offset1:160
	v_add_u32_e32 v2, 0x4400, v0
	ds_write2_b32 v2, v3, v19 offset0:4 offset1:36
	ds_write2_b32 v2, v4, v20 offset0:136 offset1:168
	v_add_u32_e32 v2, 0x4800, v0
	ds_write2_b32 v2, v5, v21 offset0:12 offset1:44
	v_add_u32_e32 v2, 0x5000, v0
	ds_write2_b32 v2, v6, v22 offset0:160 offset1:192
	v_add_u32_e32 v2, 0x5400, v0
	ds_write2_b32 v2, v7, v23 offset0:36 offset1:68
	ds_write2_b32 v2, v8, v24 offset0:168 offset1:200
	v_add_u32_e32 v2, 0x5800, v0
	ds_write2_b32 v2, v9, v25 offset0:44 offset1:76
	v_add_u32_e32 v2, 0x6000, v0
	ds_write2_b32 v2, v10, v26 offset0:192 offset1:224
	v_add_u32_e32 v2, 0x6400, v0
	ds_write2_b32 v2, v11, v27 offset0:68 offset1:100
	ds_write2_b32 v2, v12, v28 offset0:200 offset1:232
	v_add_u32_e32 v2, 0x6800, v0
	ds_write2_b32 v2, v13, v29 offset0:76 offset1:108
	v_add_u32_e32 v2, 0x7200, v0
	ds_write2_b32 v2, v14, v30 offset0:96 offset1:128
	v_add_u32_e32 v2, 0x7400, v0
	ds_write2_b32 v2, v15, v31 offset0:100 offset1:132
	v_add_u32_e32 v2, 0x7600, v0
	v_add_u32_e32 v0, 0x7800, v0
	ds_write2_b32 v0, v17, v33 offset0:108 offset1:140
	v_lshlrev_b32_e32 v0, 3, v66
	v_and_b32_e32 v0, 0x78, v0
	v_or_b32_e32 v12, s0, v0
	v_ashrrev_i32_e32 v13, 31, v12
	v_readlane_b32 s0, v249, 13
	ds_write2_b32 v2, v16, v32 offset0:104 offset1:136
	v_lshlrev_b64 v[2:3], 2, v[12:13]
	v_readlane_b32 s1, v249, 14
	v_lshlrev_b32_e32 v10, 2, v0
	v_lshl_add_u64 v[16:17], s[90:91], 0, v[2:3]
	v_lshl_add_u64 v[14:15], s[0:1], 0, v[2:3]
	s_waitcnt lgkmcnt(0)
	s_barrier
	s_branch .LBB0_912
